# GEMM k-loops: first weight fragment read first + counted lgkmcnt(10..7) so the MFMA ladder starts after 2 LDS reads
# speedup vs baseline: 1.0187x; 1.0102x over previous
.LBB0_30:
	s_mul_i32 s44, s43, 0x6000
	s_add_i32 s45, s44, 0xffffa000
	s_cmp_gt_i32 s43, 0
	s_waitcnt vmcnt(6)
	s_cselect_b32 s45, s45, 0xc000
	s_waitcnt lgkmcnt(0)
	s_barrier
	s_setprio 2
	v_add3_u32 v0, s44, v177, v176
	v_add_u32_e32 v0, s55, v0
	v_add3_u32 v212, s44, v178, v176
	ds_read_b128 v[196:199], v212 offset:8192
	ds_read_b128 v[180:183], v0
	ds_read_b128 v[184:187], v0 offset:1024
	ds_read_b128 v[188:191], v0 offset:2048
	ds_read_b128 v[192:195], v0 offset:3072
	ds_read_b128 v[200:203], v212 offset:9216
	ds_read_b128 v[204:207], v212 offset:10240
	ds_read_b128 v[208:211], v212 offset:11264
	ds_read_b128 v[216:219], v212 offset:12288
	ds_read_b128 v[226:229], v212 offset:13312
	ds_read_b128 v[230:233], v212 offset:14336
	ds_read_b128 v[234:237], v212 offset:15360
	v_lshl_add_u64 v[212:213], v[174:175], 0, s[12:13]
	v_lshl_add_u64 v[212:213], v[162:163], 1, v[212:213]
	s_add_i32 s68, s45, s42
	s_mov_b32 m0, s68
	s_nop 0
	global_load_lds_dwordx4 v[212:213], off
	v_lshl_add_u64 v[212:213], v[174:175], 0, s[12:13]
	v_lshl_add_u64 v[212:213], v[164:165], 1, v[212:213]
	s_add_i32 s68, s45, s40
	s_mov_b32 m0, s68
	s_nop 0
	global_load_lds_dwordx4 v[212:213], off
	s_add_i32 s45, s41, s45
	v_lshl_add_u64 v[212:213], v[172:173], 0, s[12:13]
	s_mov_b32 m0, s45
	s_nop 0
	global_load_lds_dwordx4 v[212:213], off
	v_lshl_add_u64 v[212:213], v[170:171], 0, s[12:13]
	s_add_i32 s68, s45, 0x400
	s_mov_b32 m0, s68
	s_nop 0
	global_load_lds_dwordx4 v[212:213], off
	v_lshl_add_u64 v[212:213], v[168:169], 0, s[12:13]
	s_add_i32 s68, s45, 0x800
	s_mov_b32 m0, s68
	s_nop 0
	global_load_lds_dwordx4 v[212:213], off
	s_addk_i32 s45, 0xc00
	v_lshl_add_u64 v[212:213], v[166:167], 0, s[12:13]
	s_mov_b32 m0, s45
	s_nop 0
	global_load_lds_dwordx4 v[212:213], off
	s_setprio 0
	s_waitcnt lgkmcnt(10)
	v_mfma_f32_16x16x32_bf16 v[34:37], v[196:199], v[180:183], v[34:37]
	s_waitcnt lgkmcnt(9)
	v_mfma_f32_16x16x32_bf16 v[38:41], v[196:199], v[184:187], v[38:41]
	s_waitcnt lgkmcnt(8)
	v_mfma_f32_16x16x32_bf16 v[42:45], v[196:199], v[188:191], v[42:45]
	s_waitcnt lgkmcnt(7)
	v_mfma_f32_16x16x32_bf16 v[46:49], v[196:199], v[192:195], v[46:49]
	s_waitcnt lgkmcnt(6)
	v_mfma_f32_16x16x32_bf16 v[50:53], v[200:203], v[180:183], v[50:53]
	v_mfma_f32_16x16x32_bf16 v[54:57], v[200:203], v[184:187], v[54:57]
	v_mfma_f32_16x16x32_bf16 v[58:61], v[200:203], v[188:191], v[58:61]
	v_mfma_f32_16x16x32_bf16 v[62:65], v[200:203], v[192:195], v[62:65]
	s_waitcnt lgkmcnt(5)
	v_mfma_f32_16x16x32_bf16 v[66:69], v[204:207], v[180:183], v[66:69]
	v_mfma_f32_16x16x32_bf16 v[70:73], v[204:207], v[184:187], v[70:73]
	v_mfma_f32_16x16x32_bf16 v[74:77], v[204:207], v[188:191], v[74:77]
	v_mfma_f32_16x16x32_bf16 v[78:81], v[204:207], v[192:195], v[78:81]
	s_waitcnt lgkmcnt(4)
	v_mfma_f32_16x16x32_bf16 v[82:85], v[208:211], v[180:183], v[82:85]
	v_mfma_f32_16x16x32_bf16 v[86:89], v[208:211], v[184:187], v[86:89]
	v_mfma_f32_16x16x32_bf16 v[90:93], v[208:211], v[188:191], v[90:93]
	v_mfma_f32_16x16x32_bf16 v[94:97], v[208:211], v[192:195], v[94:97]
	s_waitcnt lgkmcnt(3)
	v_mfma_f32_16x16x32_bf16 v[98:101], v[216:219], v[180:183], v[98:101]
	v_mfma_f32_16x16x32_bf16 v[102:105], v[216:219], v[184:187], v[102:105]
	v_mfma_f32_16x16x32_bf16 v[106:109], v[216:219], v[188:191], v[106:109]
	v_mfma_f32_16x16x32_bf16 v[110:113], v[216:219], v[192:195], v[110:113]
	s_waitcnt lgkmcnt(2)
	v_mfma_f32_16x16x32_bf16 v[114:117], v[226:229], v[180:183], v[114:117]
	v_mfma_f32_16x16x32_bf16 v[118:121], v[226:229], v[184:187], v[118:121]
	v_mfma_f32_16x16x32_bf16 v[122:125], v[226:229], v[188:191], v[122:125]
	v_mfma_f32_16x16x32_bf16 v[126:129], v[226:229], v[192:195], v[126:129]
	s_waitcnt lgkmcnt(1)
	v_mfma_f32_16x16x32_bf16 v[130:133], v[230:233], v[180:183], v[130:133]
	v_mfma_f32_16x16x32_bf16 v[134:137], v[230:233], v[184:187], v[134:137]
	v_mfma_f32_16x16x32_bf16 v[138:141], v[230:233], v[188:191], v[138:141]
	v_mfma_f32_16x16x32_bf16 v[142:145], v[230:233], v[192:195], v[142:145]
	s_waitcnt lgkmcnt(0)
	v_mfma_f32_16x16x32_bf16 v[146:149], v[234:237], v[180:183], v[146:149]
	v_mfma_f32_16x16x32_bf16 v[150:153], v[234:237], v[184:187], v[150:153]
	v_mfma_f32_16x16x32_bf16 v[154:157], v[234:237], v[188:191], v[154:157]
	v_mfma_f32_16x16x32_bf16 v[158:161], v[234:237], v[192:195], v[158:161]
	s_add_i32 s44, s43, 1
	s_cmp_lg_u32 s43, 2
	s_cselect_b32 s43, s44, 0
	s_add_u32 s12, s12, 64
	s_addc_u32 s13, s13, 0
	s_cmpk_eq_i32 s12, 0x780
	s_cbranch_scc0 .LBB0_30
	s_waitcnt vmcnt(6)
	v_mov_b32_e32 v162, v23
	v_mov_b32_e32 v163, v24
	v_mov_b32_e32 v23, v25
	v_mov_b32_e32 v164, v7
	v_mov_b32_e32 v165, v8
	v_pk_add_f32 v[22:23], v[162:163], v[22:23]
	v_mov_b32_e32 v7, v9
	v_pk_add_f32 v[6:7], v[164:165], v[6:7]
	v_add_f32_e32 v0, v22, v23
	v_add_f32_e32 v0, v0, v6
	v_add_f32_e32 v0, v0, v7
	v_fmamk_f32 v0, v0, 0x3a800000, v250
	s_mov_b32 s12, 0x800000
	s_waitcnt vmcnt(4)
	v_mov_b32_e32 v166, v19
	v_mov_b32_e32 v167, v20
	v_mov_b32_e32 v168, v3
	v_mul_f32_e32 v3, 0x4b800000, v0
	v_cmp_gt_f32_e32 vcc, s12, v0
	v_mov_b32_e32 v19, v21
	v_mov_b32_e32 v169, v4
	v_cndmask_b32_e32 v0, v0, v3, vcc
	v_pk_add_f32 v[6:7], v[166:167], v[18:19]
	v_mov_b32_e32 v3, v5
	v_pk_add_f32 v[2:3], v[168:169], v[2:3]
	v_add_f32_e32 v4, v6, v7
	v_add_f32_e32 v2, v4, v2
	v_add_f32_e32 v2, v2, v3
	v_fmamk_f32 v2, v2, 0x3a800000, v250
	v_mul_f32_e32 v3, 0x4b800000, v2
	v_cmp_gt_f32_e64 s[40:41], s12, v2
	s_waitcnt vmcnt(2)
	v_mov_b32_e32 v170, v27
	v_mov_b32_e32 v171, v28
	v_cndmask_b32_e64 v2, v2, v3, s[40:41]
	v_mov_b32_e32 v27, v29
	v_mov_b32_e32 v172, v11
	v_mov_b32_e32 v173, v12
	v_rsq_f32_e32 v179, v2
	v_pk_add_f32 v[2:3], v[170:171], v[26:27]
	v_mov_b32_e32 v11, v13
	v_pk_add_f32 v[4:5], v[172:173], v[10:11]
	v_add_f32_e32 v2, v2, v3
	v_add_f32_e32 v2, v2, v4
	v_add_f32_e32 v2, v2, v5
	v_fmamk_f32 v2, v2, 0x3a800000, v250
	v_mul_f32_e32 v3, 0x4b800000, v2
	v_cmp_gt_f32_e64 s[42:43], s12, v2
	s_waitcnt vmcnt(0)
	v_mov_b32_e32 v174, v31
	v_mov_b32_e32 v175, v32
	v_cndmask_b32_e64 v2, v2, v3, s[42:43]
	v_mov_b32_e32 v31, v33
	v_mov_b32_e32 v180, v15
	v_mov_b32_e32 v181, v16
	v_rsq_f32_e32 v182, v2
	v_pk_add_f32 v[2:3], v[174:175], v[30:31]
	v_mov_b32_e32 v15, v17
	v_pk_add_f32 v[4:5], v[180:181], v[14:15]
	v_add_f32_e32 v2, v2, v3
	v_add_f32_e32 v2, v2, v4
	v_add_f32_e32 v2, v2, v5
	v_fmamk_f32 v2, v2, 0x3a800000, v250
	v_mul_f32_e32 v3, 0x4b800000, v2
	v_cmp_gt_f32_e64 s[44:45], s12, v2
	s_waitcnt vmcnt(6)
	v_add_u32_e32 v183, v178, v176
	s_waitcnt lgkmcnt(0)
	s_barrier
	v_cndmask_b32_e64 v2, v2, v3, s[44:45]
	v_rsq_f32_e32 v180, v2
	ds_read_b128 v[2:5], v183 offset:15360
	ds_read_b128 v[6:9], v183 offset:14336
	ds_read_b128 v[10:13], v183 offset:13312
	ds_read_b128 v[14:17], v183 offset:12288
	ds_read_b128 v[18:21], v183 offset:11264
	ds_read_b128 v[22:25], v183 offset:10240
	ds_read_b128 v[26:29], v183 offset:9216
	ds_read_b128 v[30:33], v183 offset:8192
	v_add3_u32 v178, s55, v177, v176
	ds_read_b128 v[162:165], v178 offset:3072
	ds_read_b128 v[166:169], v178 offset:2048
	ds_read_b128 v[170:173], v178 offset:1024
	ds_read_b128 v[174:177], v178
	v_rsq_f32_e32 v0, v0
	v_mul_f32_e32 v184, 0x45800000, v179
	v_mul_f32_e32 v185, 0x45800000, v182
	v_mul_f32_e32 v186, 0x45800000, v180
	v_mul_f32_e32 v181, 0x45800000, v0
	s_waitcnt lgkmcnt(0)
	v_mfma_f32_16x16x32_bf16 v[34:37], v[30:33], v[174:177], v[34:37]
	v_mfma_f32_16x16x32_bf16 v[38:41], v[30:33], v[170:173], v[38:41]
	v_mfma_f32_16x16x32_bf16 v[42:45], v[30:33], v[166:169], v[42:45]
	v_mfma_f32_16x16x32_bf16 v[30:33], v[30:33], v[162:165], v[46:49]
	v_mfma_f32_16x16x32_bf16 v[46:49], v[26:29], v[174:177], v[50:53]
	v_mfma_f32_16x16x32_bf16 v[50:53], v[26:29], v[170:173], v[54:57]
	v_mfma_f32_16x16x32_bf16 v[54:57], v[26:29], v[166:169], v[58:61]
	v_mfma_f32_16x16x32_bf16 v[58:61], v[26:29], v[162:165], v[62:65]
	v_mfma_f32_16x16x32_bf16 v[62:65], v[22:25], v[174:177], v[66:69]
	v_mfma_f32_16x16x32_bf16 v[66:69], v[22:25], v[170:173], v[70:73]
	v_mfma_f32_16x16x32_bf16 v[70:73], v[22:25], v[166:169], v[74:77]
	v_mfma_f32_16x16x32_bf16 v[74:77], v[22:25], v[162:165], v[78:81]
	v_mfma_f32_16x16x32_bf16 v[78:81], v[18:21], v[174:177], v[82:85]
	v_mfma_f32_16x16x32_bf16 v[82:85], v[18:21], v[170:173], v[86:89]
	v_mfma_f32_16x16x32_bf16 v[86:89], v[18:21], v[166:169], v[90:93]
	v_mfma_f32_16x16x32_bf16 v[18:21], v[18:21], v[162:165], v[94:97]
	v_mfma_f32_16x16x32_bf16 v[90:93], v[14:17], v[174:177], v[98:101]
	v_mfma_f32_16x16x32_bf16 v[94:97], v[14:17], v[170:173], v[102:105]
	v_mfma_f32_16x16x32_bf16 v[98:101], v[14:17], v[166:169], v[106:109]
	v_mfma_f32_16x16x32_bf16 v[14:17], v[14:17], v[162:165], v[110:113]
	v_mfma_f32_16x16x32_bf16 v[102:105], v[10:13], v[174:177], v[114:117]
	v_mfma_f32_16x16x32_bf16 v[106:109], v[10:13], v[170:173], v[118:121]
	v_mfma_f32_16x16x32_bf16 v[110:113], v[10:13], v[166:169], v[122:125]
	v_mfma_f32_16x16x32_bf16 v[10:13], v[10:13], v[162:165], v[126:129]
	v_mfma_f32_16x16x32_bf16 v[114:117], v[6:9], v[174:177], v[130:133]
	v_mfma_f32_16x16x32_bf16 v[118:121], v[6:9], v[170:173], v[134:137]
	v_mfma_f32_16x16x32_bf16 v[122:125], v[6:9], v[166:169], v[138:141]
	v_mfma_f32_16x16x32_bf16 v[6:9], v[6:9], v[162:165], v[142:145]
	v_mfma_f32_16x16x32_bf16 v[126:129], v[2:5], v[174:177], v[146:149]
	v_mfma_f32_16x16x32_bf16 v[130:133], v[2:5], v[170:173], v[150:153]
	v_mfma_f32_16x16x32_bf16 v[134:137], v[2:5], v[166:169], v[154:157]
	v_mfma_f32_16x16x32_bf16 v[2:5], v[2:5], v[162:165], v[158:161]
	s_waitcnt vmcnt(0)
	v_cndmask_b32_e32 v26, v0, v181, vcc
	v_cndmask_b32_e64 v24, v179, v184, s[40:41]
	v_cndmask_b32_e64 v22, v182, v185, s[42:43]
	v_cndmask_b32_e64 v0, v180, v186, s[44:45]
	s_waitcnt lgkmcnt(0)
	s_barrier
	ds_read_b128 v[138:141], v178 offset:24576
	ds_read_b128 v[142:145], v178 offset:25600
	ds_read_b128 v[146:149], v178 offset:26624
	ds_read_b128 v[150:153], v178 offset:27648
	ds_read_b128 v[154:157], v183 offset:32768
	ds_read_b128 v[158:161], v183 offset:33792
	ds_read_b128 v[162:165], v183 offset:34816
	ds_read_b128 v[166:169], v183 offset:35840
	ds_read_b128 v[170:173], v183 offset:36864
	ds_read_b128 v[174:177], v183 offset:37888
	ds_read_b128 v[178:181], v183 offset:38912
	ds_read_b128 v[182:185], v183 offset:39936
	s_waitcnt lgkmcnt(7)
	v_mfma_f32_16x16x32_bf16 v[34:37], v[154:157], v[138:141], v[34:37]
	v_mfma_f32_16x16x32_bf16 v[38:41], v[154:157], v[142:145], v[38:41]
	v_mfma_f32_16x16x32_bf16 v[42:45], v[154:157], v[146:149], v[42:45]
	v_mfma_f32_16x16x32_bf16 v[28:31], v[154:157], v[150:153], v[30:33]
	s_waitcnt lgkmcnt(6)
	v_mfma_f32_16x16x32_bf16 v[46:49], v[158:161], v[138:141], v[46:49]
	v_mfma_f32_16x16x32_bf16 v[50:53], v[158:161], v[142:145], v[50:53]
	v_mfma_f32_16x16x32_bf16 v[54:57], v[158:161], v[146:149], v[54:57]
	v_mfma_f32_16x16x32_bf16 v[58:61], v[158:161], v[150:153], v[58:61]
	s_waitcnt lgkmcnt(5)
	v_mfma_f32_16x16x32_bf16 v[62:65], v[162:165], v[138:141], v[62:65]
	v_mfma_f32_16x16x32_bf16 v[66:69], v[162:165], v[142:145], v[66:69]
	v_mfma_f32_16x16x32_bf16 v[70:73], v[162:165], v[146:149], v[70:73]
	v_mfma_f32_16x16x32_bf16 v[74:77], v[162:165], v[150:153], v[74:77]
	s_waitcnt lgkmcnt(4)
	v_mfma_f32_16x16x32_bf16 v[78:81], v[166:169], v[138:141], v[78:81]
	v_mfma_f32_16x16x32_bf16 v[82:85], v[166:169], v[142:145], v[82:85]
	v_mfma_f32_16x16x32_bf16 v[86:89], v[166:169], v[146:149], v[86:89]
	v_mfma_f32_16x16x32_bf16 v[154:157], v[166:169], v[150:153], v[18:21]
	s_waitcnt lgkmcnt(3)
	v_mfma_f32_16x16x32_bf16 v[90:93], v[170:173], v[138:141], v[90:93]
	v_mfma_f32_16x16x32_bf16 v[94:97], v[170:173], v[142:145], v[94:97]
	v_mfma_f32_16x16x32_bf16 v[98:101], v[170:173], v[146:149], v[98:101]
	v_mfma_f32_16x16x32_bf16 v[158:161], v[170:173], v[150:153], v[14:17]
	s_waitcnt lgkmcnt(2)
	v_mfma_f32_16x16x32_bf16 v[102:105], v[174:177], v[138:141], v[102:105]
	v_mfma_f32_16x16x32_bf16 v[106:109], v[174:177], v[142:145], v[106:109]
	v_mfma_f32_16x16x32_bf16 v[110:113], v[174:177], v[146:149], v[110:113]
	v_mfma_f32_16x16x32_bf16 v[162:165], v[174:177], v[150:153], v[10:13]
	s_waitcnt lgkmcnt(1)
	v_mfma_f32_16x16x32_bf16 v[114:117], v[178:181], v[138:141], v[114:117]
	v_mfma_f32_16x16x32_bf16 v[118:121], v[178:181], v[142:145], v[118:121]
	v_mfma_f32_16x16x32_bf16 v[122:125], v[178:181], v[146:149], v[122:125]
	v_mfma_f32_16x16x32_bf16 v[18:21], v[178:181], v[150:153], v[6:9]
	s_waitcnt lgkmcnt(0)
	v_mfma_f32_16x16x32_bf16 v[14:17], v[182:185], v[138:141], v[126:129]
	v_mfma_f32_16x16x32_bf16 v[10:13], v[182:185], v[142:145], v[130:133]
	v_mfma_f32_16x16x32_bf16 v[6:9], v[182:185], v[146:149], v[134:137]
	v_mfma_f32_16x16x32_bf16 v[2:5], v[182:185], v[150:153], v[2:5]
	v_mov_b32_e32 v23, v224
	s_movk_i32 s12, 0x210
	v_lshrrev_b32_e32 v32, 1, v23
	v_and_b32_e32 v27, 0x7fffff80, v23
	v_and_b32_e32 v32, 24, v32
	v_and_b32_e32 v25, 0x4f, v23
	v_lshl_or_b32 v27, v27, 1, v32
	v_pk_mul_f32 v[32:33], v[26:27], v[34:35] op_sel_hi:[0,1]
	v_pk_mul_f32 v[34:35], v[26:27], v[36:37] op_sel_hi:[0,1]
	v_mad_u32_u24 v25, v25, s12, v27
	v_cvt_pk_bf16_f32 v32, v32, v33
	v_cvt_pk_bf16_f32 v33, v34, v35
	v_pk_mul_f32 v[34:35], v[24:25], v[38:39] op_sel_hi:[0,1]
	v_pk_mul_f32 v[36:37], v[24:25], v[40:41] op_sel_hi:[0,1]
	v_cvt_pk_bf16_f32 v34, v34, v35
	v_cvt_pk_bf16_f32 v35, v36, v37
	v_pk_mul_f32 v[36:37], v[22:23], v[42:43] op_sel_hi:[0,1]
	v_pk_mul_f32 v[38:39], v[22:23], v[44:45] op_sel_hi:[0,1]
	v_pk_mul_f32 v[28:29], v[0:1], v[28:29] op_sel_hi:[0,1]
	v_pk_mul_f32 v[30:31], v[0:1], v[30:31] op_sel_hi:[0,1]
	v_cvt_pk_bf16_f32 v36, v36, v37
	v_cvt_pk_bf16_f32 v37, v38, v39
	v_cvt_pk_bf16_f32 v28, v28, v29
	v_cvt_pk_bf16_f32 v29, v30, v31
	v_pk_mul_f32 v[30:31], v[26:27], v[46:47] op_sel_hi:[0,1]
	v_pk_mul_f32 v[38:39], v[26:27], v[48:49] op_sel_hi:[0,1]
	v_cvt_pk_bf16_f32 v30, v30, v31
	v_cvt_pk_bf16_f32 v31, v38, v39
	s_barrier
	ds_write2_b64 v25, v[32:33], v[30:31] offset1:4
	v_pk_mul_f32 v[30:31], v[24:25], v[50:51] op_sel_hi:[0,1]
	v_pk_mul_f32 v[32:33], v[24:25], v[52:53] op_sel_hi:[0,1]
	v_cvt_pk_bf16_f32 v30, v30, v31
	v_cvt_pk_bf16_f32 v31, v32, v33
	v_add_u32_e32 v27, 0x2000, v25
	ds_write2_b64 v27, v[34:35], v[30:31] offset0:32 offset1:36
	v_pk_mul_f32 v[30:31], v[22:23], v[54:55] op_sel_hi:[0,1]
	v_pk_mul_f32 v[32:33], v[22:23], v[56:57] op_sel_hi:[0,1]
	v_cvt_pk_bf16_f32 v30, v30, v31
	v_cvt_pk_bf16_f32 v31, v32, v33
	v_add_u32_e32 v40, 0x4000, v25
	ds_write2_b64 v40, v[36:37], v[30:31] offset0:64 offset1:68
	v_pk_mul_f32 v[30:31], v[0:1], v[58:59] op_sel_hi:[0,1]
	v_pk_mul_f32 v[32:33], v[0:1], v[60:61] op_sel_hi:[0,1]
	v_cvt_pk_bf16_f32 v30, v30, v31
	v_cvt_pk_bf16_f32 v31, v32, v33
	v_add_u32_e32 v41, 0x6000, v25
	ds_write2_b64 v41, v[28:29], v[30:31] offset0:96 offset1:100
	v_pk_mul_f32 v[28:29], v[26:27], v[62:63] op_sel_hi:[0,1]
	v_pk_mul_f32 v[30:31], v[26:27], v[64:65] op_sel_hi:[0,1]
	v_cvt_pk_bf16_f32 v28, v28, v29
	v_cvt_pk_bf16_f32 v29, v30, v31
	v_pk_mul_f32 v[30:31], v[24:25], v[66:67] op_sel_hi:[0,1]
	v_pk_mul_f32 v[32:33], v[24:25], v[68:69] op_sel_hi:[0,1]
	v_cvt_pk_bf16_f32 v30, v30, v31
	v_cvt_pk_bf16_f32 v31, v32, v33
	v_pk_mul_f32 v[32:33], v[22:23], v[70:71] op_sel_hi:[0,1]
	v_pk_mul_f32 v[34:35], v[22:23], v[72:73] op_sel_hi:[0,1]
	v_cvt_pk_bf16_f32 v32, v32, v33
	v_cvt_pk_bf16_f32 v33, v34, v35
	v_pk_mul_f32 v[34:35], v[0:1], v[74:75] op_sel_hi:[0,1]
	v_pk_mul_f32 v[36:37], v[0:1], v[76:77] op_sel_hi:[0,1]
	v_cvt_pk_bf16_f32 v34, v34, v35
	v_cvt_pk_bf16_f32 v35, v36, v37
	v_pk_mul_f32 v[36:37], v[26:27], v[78:79] op_sel_hi:[0,1]
	v_pk_mul_f32 v[38:39], v[26:27], v[80:81] op_sel_hi:[0,1]
	v_cvt_pk_bf16_f32 v36, v36, v37
	v_cvt_pk_bf16_f32 v37, v38, v39
	ds_write2_b64 v25, v[28:29], v[36:37] offset0:8 offset1:12
	v_pk_mul_f32 v[28:29], v[24:25], v[82:83] op_sel_hi:[0,1]
	v_pk_mul_f32 v[36:37], v[24:25], v[84:85] op_sel_hi:[0,1]
	v_cvt_pk_bf16_f32 v28, v28, v29
	v_cvt_pk_bf16_f32 v29, v36, v37
	ds_write2_b64 v27, v[30:31], v[28:29] offset0:40 offset1:44
	v_pk_mul_f32 v[28:29], v[22:23], v[86:87] op_sel_hi:[0,1]
	v_pk_mul_f32 v[30:31], v[22:23], v[88:89] op_sel_hi:[0,1]
	v_cvt_pk_bf16_f32 v28, v28, v29
	v_cvt_pk_bf16_f32 v29, v30, v31
	ds_write2_b64 v40, v[32:33], v[28:29] offset0:72 offset1:76
	v_pk_mul_f32 v[28:29], v[0:1], v[154:155] op_sel_hi:[0,1]
	v_pk_mul_f32 v[30:31], v[0:1], v[156:157] op_sel_hi:[0,1]
	v_cvt_pk_bf16_f32 v28, v28, v29
	v_cvt_pk_bf16_f32 v29, v30, v31
	ds_write2_b64 v41, v[34:35], v[28:29] offset0:104 offset1:108
	v_pk_mul_f32 v[28:29], v[26:27], v[90:91] op_sel_hi:[0,1]
	v_pk_mul_f32 v[30:31], v[26:27], v[92:93] op_sel_hi:[0,1]
	v_cvt_pk_bf16_f32 v28, v28, v29
	v_cvt_pk_bf16_f32 v29, v30, v31
	v_pk_mul_f32 v[30:31], v[24:25], v[94:95] op_sel_hi:[0,1]
	v_pk_mul_f32 v[32:33], v[24:25], v[96:97] op_sel_hi:[0,1]
	v_cvt_pk_bf16_f32 v30, v30, v31
	v_cvt_pk_bf16_f32 v31, v32, v33
	v_pk_mul_f32 v[32:33], v[22:23], v[98:99] op_sel_hi:[0,1]
	v_pk_mul_f32 v[34:35], v[22:23], v[100:101] op_sel_hi:[0,1]
	v_cvt_pk_bf16_f32 v32, v32, v33
	v_cvt_pk_bf16_f32 v33, v34, v35
	v_pk_mul_f32 v[34:35], v[0:1], v[158:159] op_sel_hi:[0,1]
	v_pk_mul_f32 v[36:37], v[0:1], v[160:161] op_sel_hi:[0,1]
	v_cvt_pk_bf16_f32 v34, v34, v35
	v_cvt_pk_bf16_f32 v35, v36, v37
	v_pk_mul_f32 v[36:37], v[26:27], v[102:103] op_sel_hi:[0,1]
	v_pk_mul_f32 v[38:39], v[26:27], v[104:105] op_sel_hi:[0,1]
	v_cvt_pk_bf16_f32 v36, v36, v37
	v_cvt_pk_bf16_f32 v37, v38, v39
	ds_write2_b64 v25, v[28:29], v[36:37] offset0:16 offset1:20
	v_pk_mul_f32 v[28:29], v[24:25], v[106:107] op_sel_hi:[0,1]
	v_pk_mul_f32 v[36:37], v[24:25], v[108:109] op_sel_hi:[0,1]
	v_cvt_pk_bf16_f32 v28, v28, v29
	v_cvt_pk_bf16_f32 v29, v36, v37
	ds_write2_b64 v27, v[30:31], v[28:29] offset0:48 offset1:52
	v_pk_mul_f32 v[28:29], v[22:23], v[110:111] op_sel_hi:[0,1]
	v_pk_mul_f32 v[30:31], v[22:23], v[112:113] op_sel_hi:[0,1]
	v_cvt_pk_bf16_f32 v28, v28, v29
	v_cvt_pk_bf16_f32 v29, v30, v31
	ds_write2_b64 v40, v[32:33], v[28:29] offset0:80 offset1:84
	v_pk_mul_f32 v[28:29], v[0:1], v[162:163] op_sel_hi:[0,1]
	v_pk_mul_f32 v[30:31], v[0:1], v[164:165] op_sel_hi:[0,1]
	v_cvt_pk_bf16_f32 v28, v28, v29
	v_cvt_pk_bf16_f32 v29, v30, v31
	ds_write2_b64 v41, v[34:35], v[28:29] offset0:112 offset1:116
	v_pk_mul_f32 v[28:29], v[26:27], v[114:115] op_sel_hi:[0,1]
	v_pk_mul_f32 v[30:31], v[26:27], v[116:117] op_sel_hi:[0,1]
	v_pk_mul_f32 v[18:19], v[0:1], v[18:19] op_sel_hi:[0,1]
	v_pk_mul_f32 v[20:21], v[0:1], v[20:21] op_sel_hi:[0,1]
	v_pk_mul_f32 v[2:3], v[0:1], v[2:3] op_sel_hi:[0,1]
	v_pk_mul_f32 v[4:5], v[0:1], v[4:5] op_sel_hi:[0,1]
	v_lshlrev_b32_e32 v0, 3, v23
	v_cvt_pk_bf16_f32 v28, v28, v29
	v_cvt_pk_bf16_f32 v29, v30, v31
	v_pk_mul_f32 v[30:31], v[24:25], v[118:119] op_sel_hi:[0,1]
	v_pk_mul_f32 v[32:33], v[24:25], v[120:121] op_sel_hi:[0,1]
	v_cvt_pk_bf16_f32 v18, v18, v19
	v_cvt_pk_bf16_f32 v19, v20, v21
	v_cvt_pk_bf16_f32 v2, v2, v3
	v_cvt_pk_bf16_f32 v3, v4, v5
	v_and_b32_e32 v0, 0xf8, v0
	v_cvt_pk_bf16_f32 v30, v30, v31
	v_cvt_pk_bf16_f32 v31, v32, v33
	v_pk_mul_f32 v[32:33], v[22:23], v[122:123] op_sel_hi:[0,1]
	v_pk_mul_f32 v[34:35], v[22:23], v[124:125] op_sel_hi:[0,1]
	v_pk_mul_f32 v[14:15], v[26:27], v[14:15] op_sel_hi:[0,1]
	v_pk_mul_f32 v[16:17], v[26:27], v[16:17] op_sel_hi:[0,1]
	v_pk_mul_f32 v[10:11], v[24:25], v[10:11] op_sel_hi:[0,1]
	v_pk_mul_f32 v[12:13], v[24:25], v[12:13] op_sel_hi:[0,1]
	v_pk_mul_f32 v[6:7], v[22:23], v[6:7] op_sel_hi:[0,1]
	v_pk_mul_f32 v[8:9], v[22:23], v[8:9] op_sel_hi:[0,1]
	ds_write2_b64 v41, v[18:19], v[2:3] offset0:120 offset1:124
	v_or_b32_e32 v2, s54, v0
	s_movk_i32 s12, 0x400
	v_cvt_pk_bf16_f32 v32, v32, v33
	v_cvt_pk_bf16_f32 v33, v34, v35
	v_cvt_pk_bf16_f32 v14, v14, v15
	v_cvt_pk_bf16_f32 v15, v16, v17
	v_cvt_pk_bf16_f32 v10, v10, v11
	v_cvt_pk_bf16_f32 v11, v12, v13
	v_cvt_pk_bf16_f32 v6, v6, v7
	v_cvt_pk_bf16_f32 v7, v8, v9
	v_cmp_gt_i32_e32 vcc, s12, v2
	ds_write2_b64 v25, v[28:29], v[14:15] offset0:24 offset1:28
	ds_write2_b64 v27, v[30:31], v[10:11] offset0:56 offset1:60
	ds_write2_b64 v40, v[32:33], v[6:7] offset0:88 offset1:92
	s_waitcnt lgkmcnt(0)
	s_barrier
	s_and_saveexec_b64 s[12:13], vcc
	s_cbranch_execz .LBB0_28
	v_ashrrev_i32_e32 v8, 5, v23
	v_lshlrev_b32_e32 v0, 1, v0
	s_movk_i32 s40, 0x210
	v_mad_u64_u32 v[6:7], s[40:41], v8, s40, v[0:1]
	v_add_u32_e32 v8, s57, v8
	ds_read_b128 v[2:5], v6
	v_ashrrev_i32_e32 v9, 31, v8
	s_ashr_i32 s55, s54, 31
	v_lshlrev_b64 v[10:11], 11, v[8:9]
	v_lshl_add_u64 v[10:11], s[4:5], 0, v[10:11]
	s_lshl_b64 s[40:41], s[54:55], 1
	v_lshl_add_u64 v[10:11], v[10:11], 0, s[40:41]
	v_lshl_add_u64 v[10:11], v[10:11], 0, v[0:1]
	s_waitcnt lgkmcnt(0)
	global_store_dwordx4 v[10:11], v[2:5], off
	v_add_u32_e32 v10, 8, v8
	ds_read_b128 v[2:5], v6 offset:4224
	v_ashrrev_i32_e32 v11, 31, v10
	v_lshlrev_b64 v[10:11], 11, v[10:11]
	v_lshl_add_u64 v[10:11], s[4:5], 0, v[10:11]
	v_lshl_add_u64 v[10:11], v[10:11], 0, s[40:41]
	v_lshl_add_u64 v[10:11], v[10:11], 0, v[0:1]
	s_waitcnt lgkmcnt(0)
	global_store_dwordx4 v[10:11], v[2:5], off
	v_add_u32_e32 v10, 16, v8
	ds_read_b128 v[2:5], v6 offset:8448
	v_ashrrev_i32_e32 v11, 31, v10
	v_lshlrev_b64 v[10:11], 11, v[10:11]
	v_lshl_add_u64 v[10:11], s[4:5], 0, v[10:11]
	v_lshl_add_u64 v[10:11], v[10:11], 0, s[40:41]
	v_lshl_add_u64 v[10:11], v[10:11], 0, v[0:1]
	s_waitcnt lgkmcnt(0)
	global_store_dwordx4 v[10:11], v[2:5], off
	v_add_u32_e32 v10, 24, v8
	ds_read_b128 v[2:5], v6 offset:12672
	v_ashrrev_i32_e32 v11, 31, v10
	v_lshlrev_b64 v[10:11], 11, v[10:11]
	v_lshl_add_u64 v[10:11], s[4:5], 0, v[10:11]
	v_lshl_add_u64 v[10:11], v[10:11], 0, s[40:41]
	v_lshl_add_u64 v[10:11], v[10:11], 0, v[0:1]
	s_waitcnt lgkmcnt(0)
	global_store_dwordx4 v[10:11], v[2:5], off
	v_add_u32_e32 v10, 32, v8
	ds_read_b128 v[2:5], v6 offset:16896
	v_ashrrev_i32_e32 v11, 31, v10
	v_lshlrev_b64 v[10:11], 11, v[10:11]
	v_lshl_add_u64 v[10:11], s[4:5], 0, v[10:11]
	v_lshl_add_u64 v[10:11], v[10:11], 0, s[40:41]
	v_lshl_add_u64 v[10:11], v[10:11], 0, v[0:1]
	s_waitcnt lgkmcnt(0)
	global_store_dwordx4 v[10:11], v[2:5], off
	v_add_u32_e32 v10, 40, v8
	ds_read_b128 v[2:5], v6 offset:21120
	v_ashrrev_i32_e32 v11, 31, v10
	v_lshlrev_b64 v[10:11], 11, v[10:11]
	v_lshl_add_u64 v[10:11], s[4:5], 0, v[10:11]
	v_lshl_add_u64 v[10:11], v[10:11], 0, s[40:41]
	v_lshl_add_u64 v[10:11], v[10:11], 0, v[0:1]
	s_waitcnt lgkmcnt(0)
	global_store_dwordx4 v[10:11], v[2:5], off
	v_add_u32_e32 v10, 48, v8
	ds_read_b128 v[2:5], v6 offset:25344
	v_ashrrev_i32_e32 v11, 31, v10
	v_lshlrev_b64 v[10:11], 11, v[10:11]
	v_lshl_add_u64 v[10:11], s[4:5], 0, v[10:11]
	v_lshl_add_u64 v[10:11], v[10:11], 0, s[40:41]
	v_lshl_add_u64 v[10:11], v[10:11], 0, v[0:1]
	s_waitcnt lgkmcnt(0)
	global_store_dwordx4 v[10:11], v[2:5], off
	v_add_u32_e32 v10, 56, v8
	ds_read_b128 v[2:5], v6 offset:29568
	v_ashrrev_i32_e32 v11, 31, v10
	v_lshlrev_b64 v[10:11], 11, v[10:11]
	v_lshl_add_u64 v[10:11], s[4:5], 0, v[10:11]
	v_lshl_add_u64 v[10:11], v[10:11], 0, s[40:41]
	v_lshl_add_u64 v[10:11], v[10:11], 0, v[0:1]
	s_waitcnt lgkmcnt(0)
	global_store_dwordx4 v[10:11], v[2:5], off
	v_add_u32_e32 v10, 64, v8
	ds_read_b128 v[2:5], v6 offset:33792
	v_ashrrev_i32_e32 v11, 31, v10
	v_lshlrev_b64 v[10:11], 11, v[10:11]
	v_lshl_add_u64 v[10:11], s[4:5], 0, v[10:11]
	v_lshl_add_u64 v[10:11], v[10:11], 0, s[40:41]
	v_lshl_add_u64 v[10:11], v[10:11], 0, v[0:1]
	s_waitcnt lgkmcnt(0)
	global_store_dwordx4 v[10:11], v[2:5], off
	v_add_u32_e32 v10, 0x48, v8
	ds_read_b128 v[2:5], v6 offset:38016
	v_ashrrev_i32_e32 v11, 31, v10
	v_lshlrev_b64 v[10:11], 11, v[10:11]
	v_lshl_add_u64 v[10:11], s[4:5], 0, v[10:11]
	v_lshl_add_u64 v[10:11], v[10:11], 0, s[40:41]
	v_lshl_add_u64 v[10:11], v[10:11], 0, v[0:1]
	s_waitcnt lgkmcnt(0)
	global_store_dwordx4 v[10:11], v[2:5], off
	v_add_u32_e32 v10, 0x50, v8
	ds_read_b128 v[2:5], v6 offset:42240
	v_ashrrev_i32_e32 v11, 31, v10
	v_lshlrev_b64 v[10:11], 11, v[10:11]
	v_lshl_add_u64 v[10:11], s[4:5], 0, v[10:11]
	v_lshl_add_u64 v[10:11], v[10:11], 0, s[40:41]
	v_lshl_add_u64 v[10:11], v[10:11], 0, v[0:1]
	s_waitcnt lgkmcnt(0)
	global_store_dwordx4 v[10:11], v[2:5], off
	v_add_u32_e32 v10, 0x58, v8
	ds_read_b128 v[2:5], v6 offset:46464
	v_ashrrev_i32_e32 v11, 31, v10
	v_lshlrev_b64 v[10:11], 11, v[10:11]
	v_lshl_add_u64 v[10:11], s[4:5], 0, v[10:11]
	v_lshl_add_u64 v[10:11], v[10:11], 0, s[40:41]
	v_lshl_add_u64 v[10:11], v[10:11], 0, v[0:1]
	s_waitcnt lgkmcnt(0)
	global_store_dwordx4 v[10:11], v[2:5], off
	v_add_u32_e32 v10, 0x60, v8
	ds_read_b128 v[2:5], v6 offset:50688
	v_ashrrev_i32_e32 v11, 31, v10
	v_lshlrev_b64 v[10:11], 11, v[10:11]
	v_lshl_add_u64 v[10:11], s[4:5], 0, v[10:11]
	v_lshl_add_u64 v[10:11], v[10:11], 0, s[40:41]
	v_lshl_add_u64 v[10:11], v[10:11], 0, v[0:1]
	s_waitcnt lgkmcnt(0)
	global_store_dwordx4 v[10:11], v[2:5], off
	v_add_u32_e32 v10, 0x68, v8
	ds_read_b128 v[2:5], v6 offset:54912
	v_ashrrev_i32_e32 v11, 31, v10
	v_lshlrev_b64 v[10:11], 11, v[10:11]
	v_lshl_add_u64 v[10:11], s[4:5], 0, v[10:11]
	v_lshl_add_u64 v[10:11], v[10:11], 0, s[40:41]
	v_lshl_add_u64 v[10:11], v[10:11], 0, v[0:1]
	s_waitcnt lgkmcnt(0)
	global_store_dwordx4 v[10:11], v[2:5], off
	v_add_u32_e32 v10, 0x70, v8
	ds_read_b128 v[2:5], v6 offset:59136
	v_ashrrev_i32_e32 v11, 31, v10
	v_lshlrev_b64 v[10:11], 11, v[10:11]
	v_lshl_add_u64 v[10:11], s[4:5], 0, v[10:11]
	v_lshl_add_u64 v[10:11], v[10:11], 0, s[40:41]
	v_lshl_add_u64 v[10:11], v[10:11], 0, v[0:1]
	s_waitcnt lgkmcnt(0)
	global_store_dwordx4 v[10:11], v[2:5], off
	ds_read_b128 v[2:5], v6 offset:63360
	v_add_u32_e32 v6, 0x78, v8
	v_ashrrev_i32_e32 v7, 31, v6
	v_lshlrev_b64 v[6:7], 11, v[6:7]
	v_lshl_add_u64 v[6:7], s[4:5], 0, v[6:7]
	v_lshl_add_u64 v[6:7], v[6:7], 0, s[40:41]
	v_lshl_add_u64 v[6:7], v[6:7], 0, v[0:1]
	s_waitcnt lgkmcnt(0)
	global_store_dwordx4 v[6:7], v[2:5], off
	s_branch .LBB0_28

.LBB0_72:
	s_mul_i32 s42, s1, 0x6000
	s_add_i32 s43, s42, 0xffffa000
	s_cmp_gt_i32 s1, 0
	s_waitcnt vmcnt(6)
	s_cselect_b32 s43, s43, 0xc000
	s_waitcnt lgkmcnt(0)
	s_barrier
	s_setprio 2
	v_add3_u32 v0, s42, v177, v176
	v_add_u32_e32 v0, s14, v0
	v_add3_u32 v212, s42, v178, v176
	ds_read_b128 v[196:199], v212 offset:8192
	ds_read_b128 v[180:183], v0
	ds_read_b128 v[184:187], v0 offset:1024
	ds_read_b128 v[188:191], v0 offset:2048
	ds_read_b128 v[192:195], v0 offset:3072
	ds_read_b128 v[200:203], v212 offset:9216
	ds_read_b128 v[204:207], v212 offset:10240
	ds_read_b128 v[208:211], v212 offset:11264
	ds_read_b128 v[216:219], v212 offset:12288
	ds_read_b128 v[226:229], v212 offset:13312
	ds_read_b128 v[230:233], v212 offset:14336
	ds_read_b128 v[234:237], v212 offset:15360
	v_lshl_add_u64 v[212:213], v[174:175], 0, s[12:13]
	v_lshl_add_u64 v[212:213], v[162:163], 1, v[212:213]
	s_add_i32 s44, s43, s41
	s_mov_b32 m0, s44
	s_nop 0
	global_load_lds_dwordx4 v[212:213], off
	v_lshl_add_u64 v[212:213], v[174:175], 0, s[12:13]
	v_lshl_add_u64 v[212:213], v[164:165], 1, v[212:213]
	s_add_i32 s44, s43, s15
	s_mov_b32 m0, s44
	s_nop 0
	global_load_lds_dwordx4 v[212:213], off
	s_add_i32 s43, s40, s43
	v_lshl_add_u64 v[212:213], v[172:173], 0, s[12:13]
	s_mov_b32 m0, s43
	s_nop 0
	global_load_lds_dwordx4 v[212:213], off
	v_lshl_add_u64 v[212:213], v[170:171], 0, s[12:13]
	s_add_i32 s44, s43, 0x400
	s_mov_b32 m0, s44
	s_nop 0
	global_load_lds_dwordx4 v[212:213], off
	v_lshl_add_u64 v[212:213], v[168:169], 0, s[12:13]
	s_add_i32 s44, s43, 0x800
	s_mov_b32 m0, s44
	s_nop 0
	global_load_lds_dwordx4 v[212:213], off
	s_addk_i32 s43, 0xc00
	v_lshl_add_u64 v[212:213], v[166:167], 0, s[12:13]
	s_mov_b32 m0, s43
	s_nop 0
	global_load_lds_dwordx4 v[212:213], off
	s_setprio 0
	s_waitcnt lgkmcnt(10)
	v_mfma_f32_16x16x32_bf16 v[34:37], v[196:199], v[180:183], v[34:37]
	s_waitcnt lgkmcnt(9)
	v_mfma_f32_16x16x32_bf16 v[38:41], v[196:199], v[184:187], v[38:41]
	s_waitcnt lgkmcnt(8)
	v_mfma_f32_16x16x32_bf16 v[42:45], v[196:199], v[188:191], v[42:45]
	s_waitcnt lgkmcnt(7)
	v_mfma_f32_16x16x32_bf16 v[46:49], v[196:199], v[192:195], v[46:49]
	s_waitcnt lgkmcnt(6)
	v_mfma_f32_16x16x32_bf16 v[50:53], v[200:203], v[180:183], v[50:53]
	v_mfma_f32_16x16x32_bf16 v[54:57], v[200:203], v[184:187], v[54:57]
	v_mfma_f32_16x16x32_bf16 v[58:61], v[200:203], v[188:191], v[58:61]
	v_mfma_f32_16x16x32_bf16 v[62:65], v[200:203], v[192:195], v[62:65]
	s_waitcnt lgkmcnt(5)
	v_mfma_f32_16x16x32_bf16 v[66:69], v[204:207], v[180:183], v[66:69]
	v_mfma_f32_16x16x32_bf16 v[70:73], v[204:207], v[184:187], v[70:73]
	v_mfma_f32_16x16x32_bf16 v[74:77], v[204:207], v[188:191], v[74:77]
	v_mfma_f32_16x16x32_bf16 v[78:81], v[204:207], v[192:195], v[78:81]
	s_waitcnt lgkmcnt(4)
	v_mfma_f32_16x16x32_bf16 v[82:85], v[208:211], v[180:183], v[82:85]
	v_mfma_f32_16x16x32_bf16 v[86:89], v[208:211], v[184:187], v[86:89]
	v_mfma_f32_16x16x32_bf16 v[90:93], v[208:211], v[188:191], v[90:93]
	v_mfma_f32_16x16x32_bf16 v[94:97], v[208:211], v[192:195], v[94:97]
	s_waitcnt lgkmcnt(3)
	v_mfma_f32_16x16x32_bf16 v[98:101], v[216:219], v[180:183], v[98:101]
	v_mfma_f32_16x16x32_bf16 v[102:105], v[216:219], v[184:187], v[102:105]
	v_mfma_f32_16x16x32_bf16 v[106:109], v[216:219], v[188:191], v[106:109]
	v_mfma_f32_16x16x32_bf16 v[110:113], v[216:219], v[192:195], v[110:113]
	s_waitcnt lgkmcnt(2)
	v_mfma_f32_16x16x32_bf16 v[114:117], v[226:229], v[180:183], v[114:117]
	v_mfma_f32_16x16x32_bf16 v[118:121], v[226:229], v[184:187], v[118:121]
	v_mfma_f32_16x16x32_bf16 v[122:125], v[226:229], v[188:191], v[122:125]
	v_mfma_f32_16x16x32_bf16 v[126:129], v[226:229], v[192:195], v[126:129]
	s_waitcnt lgkmcnt(1)
	v_mfma_f32_16x16x32_bf16 v[130:133], v[230:233], v[180:183], v[130:133]
	v_mfma_f32_16x16x32_bf16 v[134:137], v[230:233], v[184:187], v[134:137]
	v_mfma_f32_16x16x32_bf16 v[138:141], v[230:233], v[188:191], v[138:141]
	v_mfma_f32_16x16x32_bf16 v[142:145], v[230:233], v[192:195], v[142:145]
	s_waitcnt lgkmcnt(0)
	v_mfma_f32_16x16x32_bf16 v[146:149], v[234:237], v[180:183], v[146:149]
	v_mfma_f32_16x16x32_bf16 v[150:153], v[234:237], v[184:187], v[150:153]
	v_mfma_f32_16x16x32_bf16 v[154:157], v[234:237], v[188:191], v[154:157]
	v_mfma_f32_16x16x32_bf16 v[158:161], v[234:237], v[192:195], v[158:161]
	s_add_i32 s42, s1, 1
	s_cmp_lg_u32 s1, 2
	s_cselect_b32 s1, s42, 0
	s_add_u32 s12, s12, 64
	s_addc_u32 s13, s13, 0
	s_cmpk_eq_i32 s12, 0x780
	s_cbranch_scc0 .LBB0_72
	s_waitcnt vmcnt(6)
	v_mov_b32_e32 v162, v31
	v_mov_b32_e32 v163, v32
	v_mov_b32_e32 v31, v33
	v_mov_b32_e32 v164, v15
	v_mov_b32_e32 v165, v16
	v_pk_add_f32 v[30:31], v[162:163], v[30:31]
	v_mov_b32_e32 v15, v17
	v_pk_add_f32 v[14:15], v[164:165], v[14:15]
	v_add_f32_e32 v0, v30, v31
	v_add_f32_e32 v0, v0, v14
	v_add_f32_e32 v0, v0, v15
	s_waitcnt vmcnt(4)
	v_mov_b32_e32 v166, v27
	v_mov_b32_e32 v167, v28
	v_fmamk_f32 v0, v0, 0x3a800000, v250
	s_mov_b32 s1, 0x800000
	v_mov_b32_e32 v27, v29
	v_mov_b32_e32 v168, v11
	v_mov_b32_e32 v169, v12
	s_waitcnt vmcnt(1)
	v_mov_b32_e32 v180, v3
	v_mul_f32_e32 v3, 0x4b800000, v0
	v_cmp_gt_f32_e32 vcc, s1, v0
	v_pk_add_f32 v[14:15], v[166:167], v[26:27]
	v_mov_b32_e32 v11, v13
	v_cndmask_b32_e32 v0, v0, v3, vcc
	v_pk_add_f32 v[10:11], v[168:169], v[10:11]
	v_add_f32_e32 v3, v14, v15
	v_add_f32_e32 v3, v3, v10
	v_add_f32_e32 v3, v3, v11
	v_fmamk_f32 v3, v3, 0x3a800000, v250
	v_mov_b32_e32 v170, v23
	v_mov_b32_e32 v171, v24
	v_mov_b32_e32 v181, v4
	v_mul_f32_e32 v4, 0x4b800000, v3
	v_cmp_gt_f32_e64 s[40:41], s1, v3
	v_mov_b32_e32 v23, v25
	v_mov_b32_e32 v172, v7
	v_mov_b32_e32 v173, v8
	v_cndmask_b32_e64 v3, v3, v4, s[40:41]
	v_pk_add_f32 v[10:11], v[170:171], v[22:23]
	v_mov_b32_e32 v7, v9
	v_rsq_f32_e32 v179, v3
	v_pk_add_f32 v[6:7], v[172:173], v[6:7]
	v_add_f32_e32 v3, v10, v11
	v_add_f32_e32 v3, v3, v6
	v_add_f32_e32 v3, v3, v7
	v_fmamk_f32 v3, v3, 0x3a800000, v250
	v_mul_f32_e32 v4, 0x4b800000, v3
	v_cmp_gt_f32_e64 s[42:43], s1, v3
	s_waitcnt vmcnt(0)
	v_mov_b32_e32 v174, v19
	v_mov_b32_e32 v175, v20
	v_cndmask_b32_e64 v3, v3, v4, s[42:43]
	v_mov_b32_e32 v19, v21
	v_rsq_f32_e32 v182, v3
	v_pk_add_f32 v[6:7], v[174:175], v[18:19]
	v_mov_b32_e32 v3, v5
	v_pk_add_f32 v[2:3], v[180:181], v[2:3]
	v_add_f32_e32 v4, v6, v7
	v_add_f32_e32 v2, v4, v2
	v_add_f32_e32 v2, v2, v3
	v_fmamk_f32 v2, v2, 0x3a800000, v250
	v_mul_f32_e32 v3, 0x4b800000, v2
	v_cmp_gt_f32_e64 s[44:45], s1, v2
	s_waitcnt vmcnt(6)
	v_add_u32_e32 v183, v178, v176
	s_waitcnt lgkmcnt(0)
	s_barrier
	v_cndmask_b32_e64 v2, v2, v3, s[44:45]
	v_rsq_f32_e32 v180, v2
	ds_read_b128 v[2:5], v183 offset:15360
	ds_read_b128 v[6:9], v183 offset:14336
	ds_read_b128 v[10:13], v183 offset:13312
	ds_read_b128 v[14:17], v183 offset:12288
	ds_read_b128 v[18:21], v183 offset:11264
	ds_read_b128 v[22:25], v183 offset:10240
	ds_read_b128 v[26:29], v183 offset:9216
	ds_read_b128 v[30:33], v183 offset:8192
	v_add3_u32 v178, s14, v177, v176
	ds_read_b128 v[162:165], v178 offset:3072
	ds_read_b128 v[166:169], v178 offset:2048
	ds_read_b128 v[170:173], v178 offset:1024
	ds_read_b128 v[174:177], v178
	v_rsq_f32_e32 v0, v0
	v_mul_f32_e32 v184, 0x45800000, v179
	v_mul_f32_e32 v185, 0x45800000, v182
	v_mul_f32_e32 v186, 0x45800000, v180
	v_mul_f32_e32 v181, 0x45800000, v0
	s_waitcnt lgkmcnt(0)
	v_mfma_f32_16x16x32_bf16 v[34:37], v[30:33], v[174:177], v[34:37]
	v_mfma_f32_16x16x32_bf16 v[38:41], v[30:33], v[170:173], v[38:41]
	v_mfma_f32_16x16x32_bf16 v[42:45], v[30:33], v[166:169], v[42:45]
	v_mfma_f32_16x16x32_bf16 v[46:49], v[30:33], v[162:165], v[46:49]
	v_mfma_f32_16x16x32_bf16 v[50:53], v[26:29], v[174:177], v[50:53]
	v_mfma_f32_16x16x32_bf16 v[54:57], v[26:29], v[170:173], v[54:57]
	v_mfma_f32_16x16x32_bf16 v[58:61], v[26:29], v[166:169], v[58:61]
	v_mfma_f32_16x16x32_bf16 v[62:65], v[26:29], v[162:165], v[62:65]
	v_mfma_f32_16x16x32_bf16 v[66:69], v[22:25], v[174:177], v[66:69]
	v_mfma_f32_16x16x32_bf16 v[70:73], v[22:25], v[170:173], v[70:73]
	v_mfma_f32_16x16x32_bf16 v[74:77], v[22:25], v[166:169], v[74:77]
	v_mfma_f32_16x16x32_bf16 v[22:25], v[22:25], v[162:165], v[78:81]
	v_mfma_f32_16x16x32_bf16 v[78:81], v[18:21], v[174:177], v[82:85]
	v_mfma_f32_16x16x32_bf16 v[82:85], v[18:21], v[170:173], v[86:89]
	v_mfma_f32_16x16x32_bf16 v[86:89], v[18:21], v[166:169], v[90:93]
	v_mfma_f32_16x16x32_bf16 v[18:21], v[18:21], v[162:165], v[94:97]
	v_mfma_f32_16x16x32_bf16 v[90:93], v[14:17], v[174:177], v[98:101]
	v_mfma_f32_16x16x32_bf16 v[94:97], v[14:17], v[170:173], v[102:105]
	v_mfma_f32_16x16x32_bf16 v[98:101], v[14:17], v[166:169], v[106:109]
	v_mfma_f32_16x16x32_bf16 v[14:17], v[14:17], v[162:165], v[110:113]
	v_mfma_f32_16x16x32_bf16 v[102:105], v[10:13], v[174:177], v[114:117]
	v_mfma_f32_16x16x32_bf16 v[106:109], v[10:13], v[170:173], v[118:121]
	v_mfma_f32_16x16x32_bf16 v[110:113], v[10:13], v[166:169], v[122:125]
	v_mfma_f32_16x16x32_bf16 v[10:13], v[10:13], v[162:165], v[126:129]
	v_mfma_f32_16x16x32_bf16 v[114:117], v[6:9], v[174:177], v[130:133]
	v_mfma_f32_16x16x32_bf16 v[118:121], v[6:9], v[170:173], v[134:137]
	v_mfma_f32_16x16x32_bf16 v[122:125], v[6:9], v[166:169], v[138:141]
	v_mfma_f32_16x16x32_bf16 v[6:9], v[6:9], v[162:165], v[142:145]
	v_mfma_f32_16x16x32_bf16 v[126:129], v[2:5], v[174:177], v[146:149]
	v_mfma_f32_16x16x32_bf16 v[130:133], v[2:5], v[170:173], v[150:153]
	v_mfma_f32_16x16x32_bf16 v[134:137], v[2:5], v[166:169], v[154:157]
	v_mfma_f32_16x16x32_bf16 v[2:5], v[2:5], v[162:165], v[158:161]
	s_waitcnt vmcnt(0)
	v_cndmask_b32_e32 v30, v0, v181, vcc
	v_cndmask_b32_e64 v28, v179, v184, s[40:41]
	v_cndmask_b32_e64 v26, v182, v185, s[42:43]
	v_cndmask_b32_e64 v0, v180, v186, s[44:45]
	s_waitcnt lgkmcnt(0)
	s_barrier
	ds_read_b128 v[138:141], v178 offset:24576
	ds_read_b128 v[142:145], v178 offset:25600
	ds_read_b128 v[146:149], v178 offset:26624
	ds_read_b128 v[150:153], v178 offset:27648
	ds_read_b128 v[154:157], v183 offset:32768
	ds_read_b128 v[158:161], v183 offset:33792
	ds_read_b128 v[162:165], v183 offset:34816
	ds_read_b128 v[166:169], v183 offset:35840
	ds_read_b128 v[170:173], v183 offset:36864
	ds_read_b128 v[174:177], v183 offset:37888
	ds_read_b128 v[178:181], v183 offset:38912
	ds_read_b128 v[182:185], v183 offset:39936
	s_waitcnt lgkmcnt(7)
	v_mfma_f32_16x16x32_bf16 v[32:35], v[154:157], v[138:141], v[34:37]
	v_mfma_f32_16x16x32_bf16 v[36:39], v[154:157], v[142:145], v[38:41]
	v_mfma_f32_16x16x32_bf16 v[40:43], v[154:157], v[146:149], v[42:45]
	v_mfma_f32_16x16x32_bf16 v[44:47], v[154:157], v[150:153], v[46:49]
	s_waitcnt lgkmcnt(6)
	v_mfma_f32_16x16x32_bf16 v[48:51], v[158:161], v[138:141], v[50:53]
	v_mfma_f32_16x16x32_bf16 v[52:55], v[158:161], v[142:145], v[54:57]
	v_mfma_f32_16x16x32_bf16 v[56:59], v[158:161], v[146:149], v[58:61]
	v_mfma_f32_16x16x32_bf16 v[60:63], v[158:161], v[150:153], v[62:65]
	s_waitcnt lgkmcnt(5)
	v_mfma_f32_16x16x32_bf16 v[64:67], v[162:165], v[138:141], v[66:69]
	v_mfma_f32_16x16x32_bf16 v[68:71], v[162:165], v[142:145], v[70:73]
	v_mfma_f32_16x16x32_bf16 v[72:75], v[162:165], v[146:149], v[74:77]
	v_mfma_f32_16x16x32_bf16 v[154:157], v[162:165], v[150:153], v[22:25]
	s_waitcnt lgkmcnt(4)
	v_mfma_f32_16x16x32_bf16 v[76:79], v[166:169], v[138:141], v[78:81]
	v_mfma_f32_16x16x32_bf16 v[80:83], v[166:169], v[142:145], v[82:85]
	v_mfma_f32_16x16x32_bf16 v[84:87], v[166:169], v[146:149], v[86:89]
	v_mfma_f32_16x16x32_bf16 v[158:161], v[166:169], v[150:153], v[18:21]
	s_waitcnt lgkmcnt(3)
	v_mfma_f32_16x16x32_bf16 v[88:91], v[170:173], v[138:141], v[90:93]
	v_mfma_f32_16x16x32_bf16 v[92:95], v[170:173], v[142:145], v[94:97]
	v_mfma_f32_16x16x32_bf16 v[96:99], v[170:173], v[146:149], v[98:101]
	v_mfma_f32_16x16x32_bf16 v[162:165], v[170:173], v[150:153], v[14:17]
	s_waitcnt lgkmcnt(2)
	v_mfma_f32_16x16x32_bf16 v[100:103], v[174:177], v[138:141], v[102:105]
	v_mfma_f32_16x16x32_bf16 v[104:107], v[174:177], v[142:145], v[106:109]
	v_mfma_f32_16x16x32_bf16 v[108:111], v[174:177], v[146:149], v[110:113]
	v_mfma_f32_16x16x32_bf16 v[166:169], v[174:177], v[150:153], v[10:13]
	s_waitcnt lgkmcnt(1)
	v_mfma_f32_16x16x32_bf16 v[112:115], v[178:181], v[138:141], v[114:117]
	v_mfma_f32_16x16x32_bf16 v[116:119], v[178:181], v[142:145], v[118:121]
	v_mfma_f32_16x16x32_bf16 v[22:25], v[178:181], v[146:149], v[122:125]
	v_mfma_f32_16x16x32_bf16 v[18:21], v[178:181], v[150:153], v[6:9]
	s_waitcnt lgkmcnt(0)
	v_mfma_f32_16x16x32_bf16 v[14:17], v[182:185], v[138:141], v[126:129]
	v_mfma_f32_16x16x32_bf16 v[10:13], v[182:185], v[142:145], v[130:133]
	v_mfma_f32_16x16x32_bf16 v[6:9], v[182:185], v[146:149], v[134:137]
	v_mfma_f32_16x16x32_bf16 v[2:5], v[182:185], v[150:153], v[2:5]
	v_mov_b32_e32 v27, v224
	s_movk_i32 s1, 0x210
	v_lshrrev_b32_e32 v120, 1, v27
	v_and_b32_e32 v31, 0x7fffff80, v27
	v_and_b32_e32 v120, 24, v120
	v_and_b32_e32 v29, 0x4f, v27
	v_lshl_or_b32 v31, v31, 1, v120
	v_pk_mul_f32 v[32:33], v[30:31], v[32:33] op_sel_hi:[0,1]
	v_pk_mul_f32 v[34:35], v[30:31], v[34:35] op_sel_hi:[0,1]
	v_mad_u32_u24 v29, v29, s1, v31
	v_cvt_pk_bf16_f32 v32, v32, v33
	v_cvt_pk_bf16_f32 v33, v34, v35
	v_pk_mul_f32 v[34:35], v[28:29], v[36:37] op_sel_hi:[0,1]
	v_pk_mul_f32 v[36:37], v[28:29], v[38:39] op_sel_hi:[0,1]
	v_cvt_pk_bf16_f32 v34, v34, v35
	v_cvt_pk_bf16_f32 v35, v36, v37
	v_pk_mul_f32 v[36:37], v[26:27], v[40:41] op_sel_hi:[0,1]
	v_pk_mul_f32 v[38:39], v[26:27], v[42:43] op_sel_hi:[0,1]
	v_cvt_pk_bf16_f32 v36, v36, v37
	v_cvt_pk_bf16_f32 v37, v38, v39
	v_pk_mul_f32 v[38:39], v[0:1], v[44:45] op_sel_hi:[0,1]
	v_pk_mul_f32 v[40:41], v[0:1], v[46:47] op_sel_hi:[0,1]
	v_cvt_pk_bf16_f32 v38, v38, v39
	v_cvt_pk_bf16_f32 v39, v40, v41
	v_pk_mul_f32 v[40:41], v[30:31], v[48:49] op_sel_hi:[0,1]
	v_pk_mul_f32 v[42:43], v[30:31], v[50:51] op_sel_hi:[0,1]
	v_cvt_pk_bf16_f32 v40, v40, v41
	v_cvt_pk_bf16_f32 v41, v42, v43
	s_barrier
	ds_write2_b64 v29, v[32:33], v[40:41] offset1:4
	v_pk_mul_f32 v[32:33], v[28:29], v[52:53] op_sel_hi:[0,1]
	v_pk_mul_f32 v[40:41], v[28:29], v[54:55] op_sel_hi:[0,1]
	v_cvt_pk_bf16_f32 v32, v32, v33
	v_cvt_pk_bf16_f32 v33, v40, v41
	v_add_u32_e32 v31, 0x2000, v29
	ds_write2_b64 v31, v[34:35], v[32:33] offset0:32 offset1:36
	v_pk_mul_f32 v[32:33], v[26:27], v[56:57] op_sel_hi:[0,1]
	v_pk_mul_f32 v[34:35], v[26:27], v[58:59] op_sel_hi:[0,1]
	v_cvt_pk_bf16_f32 v32, v32, v33
	v_cvt_pk_bf16_f32 v33, v34, v35
	v_add_u32_e32 v44, 0x4000, v29
	ds_write2_b64 v44, v[36:37], v[32:33] offset0:64 offset1:68
	v_pk_mul_f32 v[32:33], v[0:1], v[60:61] op_sel_hi:[0,1]
	v_pk_mul_f32 v[34:35], v[0:1], v[62:63] op_sel_hi:[0,1]
	v_cvt_pk_bf16_f32 v32, v32, v33
	v_cvt_pk_bf16_f32 v33, v34, v35
	v_add_u32_e32 v45, 0x6000, v29
	ds_write2_b64 v45, v[38:39], v[32:33] offset0:96 offset1:100
	v_pk_mul_f32 v[32:33], v[30:31], v[64:65] op_sel_hi:[0,1]
	v_pk_mul_f32 v[34:35], v[30:31], v[66:67] op_sel_hi:[0,1]
	v_cvt_pk_bf16_f32 v32, v32, v33
	v_cvt_pk_bf16_f32 v33, v34, v35
	v_pk_mul_f32 v[34:35], v[28:29], v[68:69] op_sel_hi:[0,1]
	v_pk_mul_f32 v[36:37], v[28:29], v[70:71] op_sel_hi:[0,1]
	v_cvt_pk_bf16_f32 v34, v34, v35
	v_cvt_pk_bf16_f32 v35, v36, v37
	v_pk_mul_f32 v[36:37], v[26:27], v[72:73] op_sel_hi:[0,1]
	v_pk_mul_f32 v[38:39], v[26:27], v[74:75] op_sel_hi:[0,1]
	v_cvt_pk_bf16_f32 v36, v36, v37
	v_cvt_pk_bf16_f32 v37, v38, v39
	v_pk_mul_f32 v[38:39], v[0:1], v[154:155] op_sel_hi:[0,1]
	v_pk_mul_f32 v[40:41], v[0:1], v[156:157] op_sel_hi:[0,1]
	v_cvt_pk_bf16_f32 v38, v38, v39
	v_cvt_pk_bf16_f32 v39, v40, v41
	v_pk_mul_f32 v[40:41], v[30:31], v[76:77] op_sel_hi:[0,1]
	v_pk_mul_f32 v[42:43], v[30:31], v[78:79] op_sel_hi:[0,1]
	v_cvt_pk_bf16_f32 v40, v40, v41
	v_cvt_pk_bf16_f32 v41, v42, v43
	ds_write2_b64 v29, v[32:33], v[40:41] offset0:8 offset1:12
	v_pk_mul_f32 v[32:33], v[28:29], v[80:81] op_sel_hi:[0,1]
	v_pk_mul_f32 v[40:41], v[28:29], v[82:83] op_sel_hi:[0,1]
	v_cvt_pk_bf16_f32 v32, v32, v33
	v_cvt_pk_bf16_f32 v33, v40, v41
	ds_write2_b64 v31, v[34:35], v[32:33] offset0:40 offset1:44
	v_pk_mul_f32 v[32:33], v[26:27], v[84:85] op_sel_hi:[0,1]
	v_pk_mul_f32 v[34:35], v[26:27], v[86:87] op_sel_hi:[0,1]
	v_cvt_pk_bf16_f32 v32, v32, v33
	v_cvt_pk_bf16_f32 v33, v34, v35
	ds_write2_b64 v44, v[36:37], v[32:33] offset0:72 offset1:76
	v_pk_mul_f32 v[32:33], v[0:1], v[158:159] op_sel_hi:[0,1]
	v_pk_mul_f32 v[34:35], v[0:1], v[160:161] op_sel_hi:[0,1]
	v_cvt_pk_bf16_f32 v32, v32, v33
	v_cvt_pk_bf16_f32 v33, v34, v35
	ds_write2_b64 v45, v[38:39], v[32:33] offset0:104 offset1:108
	v_pk_mul_f32 v[32:33], v[30:31], v[88:89] op_sel_hi:[0,1]
	v_pk_mul_f32 v[34:35], v[30:31], v[90:91] op_sel_hi:[0,1]
	v_cvt_pk_bf16_f32 v32, v32, v33
	v_cvt_pk_bf16_f32 v33, v34, v35
	v_pk_mul_f32 v[34:35], v[28:29], v[92:93] op_sel_hi:[0,1]
	v_pk_mul_f32 v[36:37], v[28:29], v[94:95] op_sel_hi:[0,1]
	v_cvt_pk_bf16_f32 v34, v34, v35
	v_cvt_pk_bf16_f32 v35, v36, v37
	v_pk_mul_f32 v[36:37], v[26:27], v[96:97] op_sel_hi:[0,1]
	v_pk_mul_f32 v[38:39], v[26:27], v[98:99] op_sel_hi:[0,1]
	v_cvt_pk_bf16_f32 v36, v36, v37
	v_cvt_pk_bf16_f32 v37, v38, v39
	v_pk_mul_f32 v[38:39], v[0:1], v[162:163] op_sel_hi:[0,1]
	v_pk_mul_f32 v[40:41], v[0:1], v[164:165] op_sel_hi:[0,1]
	v_cvt_pk_bf16_f32 v38, v38, v39
	v_cvt_pk_bf16_f32 v39, v40, v41
	v_pk_mul_f32 v[40:41], v[30:31], v[100:101] op_sel_hi:[0,1]
	v_pk_mul_f32 v[42:43], v[30:31], v[102:103] op_sel_hi:[0,1]
	v_cvt_pk_bf16_f32 v40, v40, v41
	v_cvt_pk_bf16_f32 v41, v42, v43
	ds_write2_b64 v29, v[32:33], v[40:41] offset0:16 offset1:20
	v_pk_mul_f32 v[32:33], v[28:29], v[104:105] op_sel_hi:[0,1]
	v_pk_mul_f32 v[40:41], v[28:29], v[106:107] op_sel_hi:[0,1]
	v_cvt_pk_bf16_f32 v32, v32, v33
	v_cvt_pk_bf16_f32 v33, v40, v41
	ds_write2_b64 v31, v[34:35], v[32:33] offset0:48 offset1:52
	v_pk_mul_f32 v[32:33], v[26:27], v[108:109] op_sel_hi:[0,1]
	v_pk_mul_f32 v[34:35], v[26:27], v[110:111] op_sel_hi:[0,1]
	v_cvt_pk_bf16_f32 v32, v32, v33
	v_cvt_pk_bf16_f32 v33, v34, v35
	ds_write2_b64 v44, v[36:37], v[32:33] offset0:80 offset1:84
	v_pk_mul_f32 v[32:33], v[0:1], v[166:167] op_sel_hi:[0,1]
	v_pk_mul_f32 v[34:35], v[0:1], v[168:169] op_sel_hi:[0,1]
	v_cvt_pk_bf16_f32 v32, v32, v33
	v_cvt_pk_bf16_f32 v33, v34, v35
	v_pk_mul_f32 v[18:19], v[0:1], v[18:19] op_sel_hi:[0,1]
	v_pk_mul_f32 v[20:21], v[0:1], v[20:21] op_sel_hi:[0,1]
	v_pk_mul_f32 v[2:3], v[0:1], v[2:3] op_sel_hi:[0,1]
	v_pk_mul_f32 v[4:5], v[0:1], v[4:5] op_sel_hi:[0,1]
	v_lshlrev_b32_e32 v0, 3, v27
	ds_write2_b64 v45, v[38:39], v[32:33] offset0:112 offset1:116
	v_pk_mul_f32 v[32:33], v[30:31], v[112:113] op_sel_hi:[0,1]
	v_pk_mul_f32 v[34:35], v[30:31], v[114:115] op_sel_hi:[0,1]
	v_cvt_pk_bf16_f32 v18, v18, v19
	v_cvt_pk_bf16_f32 v19, v20, v21
	v_cvt_pk_bf16_f32 v2, v2, v3
	v_cvt_pk_bf16_f32 v3, v4, v5
	v_and_b32_e32 v0, 0xf8, v0
	v_cvt_pk_bf16_f32 v32, v32, v33
	v_cvt_pk_bf16_f32 v33, v34, v35
	v_pk_mul_f32 v[34:35], v[28:29], v[116:117] op_sel_hi:[0,1]
	v_pk_mul_f32 v[36:37], v[28:29], v[118:119] op_sel_hi:[0,1]
	v_pk_mul_f32 v[22:23], v[26:27], v[22:23] op_sel_hi:[0,1]
	v_pk_mul_f32 v[24:25], v[26:27], v[24:25] op_sel_hi:[0,1]
	v_pk_mul_f32 v[14:15], v[30:31], v[14:15] op_sel_hi:[0,1]
	v_pk_mul_f32 v[16:17], v[30:31], v[16:17] op_sel_hi:[0,1]
	v_pk_mul_f32 v[10:11], v[28:29], v[10:11] op_sel_hi:[0,1]
	v_pk_mul_f32 v[12:13], v[28:29], v[12:13] op_sel_hi:[0,1]
	v_pk_mul_f32 v[6:7], v[26:27], v[6:7] op_sel_hi:[0,1]
	v_pk_mul_f32 v[8:9], v[26:27], v[8:9] op_sel_hi:[0,1]
	ds_write2_b64 v45, v[18:19], v[2:3] offset0:120 offset1:124
	v_or_b32_e32 v2, s0, v0
	s_movk_i32 s1, 0x400
	v_cvt_pk_bf16_f32 v34, v34, v35
	v_cvt_pk_bf16_f32 v35, v36, v37
	v_cvt_pk_bf16_f32 v22, v22, v23
	v_cvt_pk_bf16_f32 v23, v24, v25
	v_cvt_pk_bf16_f32 v14, v14, v15
	v_cvt_pk_bf16_f32 v15, v16, v17
	v_cvt_pk_bf16_f32 v10, v10, v11
	v_cvt_pk_bf16_f32 v11, v12, v13
	v_cvt_pk_bf16_f32 v6, v6, v7
	v_cvt_pk_bf16_f32 v7, v8, v9
	v_cmp_gt_i32_e64 s[44:45], s1, v2
	ds_write2_b64 v29, v[32:33], v[14:15] offset0:24 offset1:28
	ds_write2_b64 v31, v[34:35], v[10:11] offset0:56 offset1:60
	ds_write2_b64 v44, v[22:23], v[6:7] offset0:88 offset1:92
	s_waitcnt lgkmcnt(0)
	s_barrier
	s_mov_b64 s[12:13], 11
	s_mov_b64 s[40:41], s[46:47]
	s_branch .LBB0_78

.LBB0_76:
	s_mul_i32 s41, s12, 0x6000
	s_add_i32 s42, s41, 0xffffa000
	s_cmp_gt_i32 s12, 0
	s_waitcnt vmcnt(6)
	s_cselect_b32 s42, s42, 0xc000
	s_waitcnt lgkmcnt(0)
	s_barrier
	s_setprio 2
	v_add3_u32 v0, s41, v177, v176
	v_add_u32_e32 v0, s13, v0
	v_add3_u32 v212, s41, v178, v176
	ds_read_b128 v[196:199], v212 offset:8192
	ds_read_b128 v[180:183], v0
	ds_read_b128 v[184:187], v0 offset:1024
	ds_read_b128 v[188:191], v0 offset:2048
	ds_read_b128 v[192:195], v0 offset:3072
	ds_read_b128 v[200:203], v212 offset:9216
	ds_read_b128 v[204:207], v212 offset:10240
	ds_read_b128 v[208:211], v212 offset:11264
	ds_read_b128 v[216:219], v212 offset:12288
	ds_read_b128 v[226:229], v212 offset:13312
	ds_read_b128 v[230:233], v212 offset:14336
	ds_read_b128 v[234:237], v212 offset:15360
	v_lshl_add_u64 v[212:213], v[174:175], 0, s[0:1]
	v_lshl_add_u64 v[212:213], v[162:163], 1, v[212:213]
	s_add_i32 s43, s42, s40
	s_mov_b32 m0, s43
	s_nop 0
	global_load_lds_dwordx4 v[212:213], off
	v_lshl_add_u64 v[212:213], v[174:175], 0, s[0:1]
	v_lshl_add_u64 v[212:213], v[164:165], 1, v[212:213]
	s_add_i32 s43, s42, s14
	s_mov_b32 m0, s43
	s_nop 0
	global_load_lds_dwordx4 v[212:213], off
	s_add_i32 s42, s15, s42
	v_lshl_add_u64 v[212:213], v[172:173], 0, s[0:1]
	s_mov_b32 m0, s42
	s_nop 0
	global_load_lds_dwordx4 v[212:213], off
	v_lshl_add_u64 v[212:213], v[170:171], 0, s[0:1]
	s_add_i32 s43, s42, 0x400
	s_mov_b32 m0, s43
	s_nop 0
	global_load_lds_dwordx4 v[212:213], off
	v_lshl_add_u64 v[212:213], v[168:169], 0, s[0:1]
	s_add_i32 s43, s42, 0x800
	s_mov_b32 m0, s43
	s_nop 0
	global_load_lds_dwordx4 v[212:213], off
	s_addk_i32 s42, 0xc00
	v_lshl_add_u64 v[212:213], v[166:167], 0, s[0:1]
	s_mov_b32 m0, s42
	s_nop 0
	global_load_lds_dwordx4 v[212:213], off
	s_setprio 0
	s_waitcnt lgkmcnt(10)
	v_mfma_f32_16x16x32_bf16 v[34:37], v[196:199], v[180:183], v[34:37]
	s_waitcnt lgkmcnt(9)
	v_mfma_f32_16x16x32_bf16 v[38:41], v[196:199], v[184:187], v[38:41]
	s_waitcnt lgkmcnt(8)
	v_mfma_f32_16x16x32_bf16 v[42:45], v[196:199], v[188:191], v[42:45]
	s_waitcnt lgkmcnt(7)
	v_mfma_f32_16x16x32_bf16 v[46:49], v[196:199], v[192:195], v[46:49]
	s_waitcnt lgkmcnt(6)
	v_mfma_f32_16x16x32_bf16 v[50:53], v[200:203], v[180:183], v[50:53]
	v_mfma_f32_16x16x32_bf16 v[54:57], v[200:203], v[184:187], v[54:57]
	v_mfma_f32_16x16x32_bf16 v[58:61], v[200:203], v[188:191], v[58:61]
	v_mfma_f32_16x16x32_bf16 v[62:65], v[200:203], v[192:195], v[62:65]
	s_waitcnt lgkmcnt(5)
	v_mfma_f32_16x16x32_bf16 v[66:69], v[204:207], v[180:183], v[66:69]
	v_mfma_f32_16x16x32_bf16 v[70:73], v[204:207], v[184:187], v[70:73]
	v_mfma_f32_16x16x32_bf16 v[74:77], v[204:207], v[188:191], v[74:77]
	v_mfma_f32_16x16x32_bf16 v[78:81], v[204:207], v[192:195], v[78:81]
	s_waitcnt lgkmcnt(4)
	v_mfma_f32_16x16x32_bf16 v[82:85], v[208:211], v[180:183], v[82:85]
	v_mfma_f32_16x16x32_bf16 v[86:89], v[208:211], v[184:187], v[86:89]
	v_mfma_f32_16x16x32_bf16 v[90:93], v[208:211], v[188:191], v[90:93]
	v_mfma_f32_16x16x32_bf16 v[94:97], v[208:211], v[192:195], v[94:97]
	s_waitcnt lgkmcnt(3)
	v_mfma_f32_16x16x32_bf16 v[98:101], v[216:219], v[180:183], v[98:101]
	v_mfma_f32_16x16x32_bf16 v[102:105], v[216:219], v[184:187], v[102:105]
	v_mfma_f32_16x16x32_bf16 v[106:109], v[216:219], v[188:191], v[106:109]
	v_mfma_f32_16x16x32_bf16 v[110:113], v[216:219], v[192:195], v[110:113]
	s_waitcnt lgkmcnt(2)
	v_mfma_f32_16x16x32_bf16 v[114:117], v[226:229], v[180:183], v[114:117]
	v_mfma_f32_16x16x32_bf16 v[118:121], v[226:229], v[184:187], v[118:121]
	v_mfma_f32_16x16x32_bf16 v[122:125], v[226:229], v[188:191], v[122:125]
	v_mfma_f32_16x16x32_bf16 v[126:129], v[226:229], v[192:195], v[126:129]
	s_waitcnt lgkmcnt(1)
	v_mfma_f32_16x16x32_bf16 v[130:133], v[230:233], v[180:183], v[130:133]
	v_mfma_f32_16x16x32_bf16 v[134:137], v[230:233], v[184:187], v[134:137]
	v_mfma_f32_16x16x32_bf16 v[138:141], v[230:233], v[188:191], v[138:141]
	v_mfma_f32_16x16x32_bf16 v[142:145], v[230:233], v[192:195], v[142:145]
	s_waitcnt lgkmcnt(0)
	v_mfma_f32_16x16x32_bf16 v[146:149], v[234:237], v[180:183], v[146:149]
	v_mfma_f32_16x16x32_bf16 v[150:153], v[234:237], v[184:187], v[150:153]
	v_mfma_f32_16x16x32_bf16 v[154:157], v[234:237], v[188:191], v[154:157]
	v_mfma_f32_16x16x32_bf16 v[158:161], v[234:237], v[192:195], v[158:161]
	s_add_i32 s41, s12, 1
	s_cmp_lg_u32 s12, 2
	s_cselect_b32 s12, s41, 0
	s_add_u32 s0, s0, 64
	s_addc_u32 s1, s1, 0
	s_cmpk_eq_i32 s0, 0x780
	s_cbranch_scc0 .LBB0_76
	s_waitcnt vmcnt(6)
	v_mov_b32_e32 v162, v23
	v_mov_b32_e32 v163, v24
	v_mov_b32_e32 v23, v25
	v_mov_b32_e32 v164, v7
	v_mov_b32_e32 v165, v8
	v_pk_add_f32 v[22:23], v[162:163], v[22:23]
	v_mov_b32_e32 v7, v9
	v_pk_add_f32 v[6:7], v[164:165], v[6:7]
	v_add_f32_e32 v0, v22, v23
	v_add_f32_e32 v0, v0, v6
	v_add_f32_e32 v0, v0, v7
	v_fmamk_f32 v0, v0, 0x3a800000, v250
	s_mov_b32 s0, 0x800000
	s_waitcnt vmcnt(4)
	v_mov_b32_e32 v166, v19
	v_mov_b32_e32 v167, v20
	v_mov_b32_e32 v168, v3
	v_mul_f32_e32 v3, 0x4b800000, v0
	v_cmp_gt_f32_e32 vcc, s0, v0
	v_mov_b32_e32 v19, v21
	v_mov_b32_e32 v169, v4
	v_cndmask_b32_e32 v0, v0, v3, vcc
	v_pk_add_f32 v[6:7], v[166:167], v[18:19]
	v_mov_b32_e32 v3, v5
	v_pk_add_f32 v[2:3], v[168:169], v[2:3]
	v_add_f32_e32 v4, v6, v7
	v_add_f32_e32 v2, v4, v2
	v_add_f32_e32 v2, v2, v3
	v_fmamk_f32 v2, v2, 0x3a800000, v250
	v_mul_f32_e32 v3, 0x4b800000, v2
	v_cmp_gt_f32_e64 s[40:41], s0, v2
	s_waitcnt vmcnt(2)
	v_mov_b32_e32 v170, v27
	v_mov_b32_e32 v171, v28
	v_cndmask_b32_e64 v2, v2, v3, s[40:41]
	v_mov_b32_e32 v27, v29
	v_mov_b32_e32 v172, v11
	v_mov_b32_e32 v173, v12
	v_rsq_f32_e32 v179, v2
	v_pk_add_f32 v[2:3], v[170:171], v[26:27]
	v_mov_b32_e32 v11, v13
	v_pk_add_f32 v[4:5], v[172:173], v[10:11]
	v_add_f32_e32 v2, v2, v3
	v_add_f32_e32 v2, v2, v4
	v_add_f32_e32 v2, v2, v5
	v_fmamk_f32 v2, v2, 0x3a800000, v250
	v_mul_f32_e32 v3, 0x4b800000, v2
	v_cmp_gt_f32_e64 s[42:43], s0, v2
	s_waitcnt vmcnt(0)
	v_mov_b32_e32 v174, v31
	v_mov_b32_e32 v175, v32
	v_cndmask_b32_e64 v2, v2, v3, s[42:43]
	v_mov_b32_e32 v31, v33
	v_mov_b32_e32 v180, v15
	v_mov_b32_e32 v181, v16
	v_rsq_f32_e32 v182, v2
	v_pk_add_f32 v[2:3], v[174:175], v[30:31]
	v_mov_b32_e32 v15, v17
	v_pk_add_f32 v[4:5], v[180:181], v[14:15]
	v_add_f32_e32 v2, v2, v3
	v_add_f32_e32 v2, v2, v4
	v_add_f32_e32 v2, v2, v5
	v_fmamk_f32 v2, v2, 0x3a800000, v250
	v_mul_f32_e32 v3, 0x4b800000, v2
	v_cmp_gt_f32_e64 s[44:45], s0, v2
	s_waitcnt vmcnt(6)
	v_add_u32_e32 v183, v178, v176
	s_waitcnt lgkmcnt(0)
	s_barrier
	v_cndmask_b32_e64 v2, v2, v3, s[44:45]
	v_rsq_f32_e32 v180, v2
	ds_read_b128 v[2:5], v183 offset:15360
	ds_read_b128 v[6:9], v183 offset:14336
	ds_read_b128 v[10:13], v183 offset:13312
	ds_read_b128 v[14:17], v183 offset:12288
	ds_read_b128 v[18:21], v183 offset:11264
	ds_read_b128 v[22:25], v183 offset:10240
	ds_read_b128 v[26:29], v183 offset:9216
	ds_read_b128 v[30:33], v183 offset:8192
	v_add3_u32 v178, s13, v177, v176
	ds_read_b128 v[162:165], v178 offset:3072
	ds_read_b128 v[166:169], v178 offset:2048
	ds_read_b128 v[170:173], v178 offset:1024
	ds_read_b128 v[174:177], v178
	v_rsq_f32_e32 v0, v0
	v_mul_f32_e32 v184, 0x45800000, v179
	v_mul_f32_e32 v185, 0x45800000, v182
	v_mul_f32_e32 v186, 0x45800000, v180
	v_mul_f32_e32 v181, 0x45800000, v0
	s_waitcnt lgkmcnt(0)
	v_mfma_f32_16x16x32_bf16 v[34:37], v[30:33], v[174:177], v[34:37]
	v_mfma_f32_16x16x32_bf16 v[38:41], v[30:33], v[170:173], v[38:41]
	v_mfma_f32_16x16x32_bf16 v[42:45], v[30:33], v[166:169], v[42:45]
	v_mfma_f32_16x16x32_bf16 v[46:49], v[30:33], v[162:165], v[46:49]
	v_mfma_f32_16x16x32_bf16 v[50:53], v[26:29], v[174:177], v[50:53]
	v_mfma_f32_16x16x32_bf16 v[54:57], v[26:29], v[170:173], v[54:57]
	v_mfma_f32_16x16x32_bf16 v[58:61], v[26:29], v[166:169], v[58:61]
	v_mfma_f32_16x16x32_bf16 v[62:65], v[26:29], v[162:165], v[62:65]
	v_mfma_f32_16x16x32_bf16 v[66:69], v[22:25], v[174:177], v[66:69]
	v_mfma_f32_16x16x32_bf16 v[70:73], v[22:25], v[170:173], v[70:73]
	v_mfma_f32_16x16x32_bf16 v[74:77], v[22:25], v[166:169], v[74:77]
	v_mfma_f32_16x16x32_bf16 v[22:25], v[22:25], v[162:165], v[78:81]
	v_mfma_f32_16x16x32_bf16 v[78:81], v[18:21], v[174:177], v[82:85]
	v_mfma_f32_16x16x32_bf16 v[82:85], v[18:21], v[170:173], v[86:89]
	v_mfma_f32_16x16x32_bf16 v[86:89], v[18:21], v[166:169], v[90:93]
	v_mfma_f32_16x16x32_bf16 v[18:21], v[18:21], v[162:165], v[94:97]
	v_mfma_f32_16x16x32_bf16 v[90:93], v[14:17], v[174:177], v[98:101]
	v_mfma_f32_16x16x32_bf16 v[94:97], v[14:17], v[170:173], v[102:105]
	v_mfma_f32_16x16x32_bf16 v[98:101], v[14:17], v[166:169], v[106:109]
	v_mfma_f32_16x16x32_bf16 v[14:17], v[14:17], v[162:165], v[110:113]
	v_mfma_f32_16x16x32_bf16 v[102:105], v[10:13], v[174:177], v[114:117]
	v_mfma_f32_16x16x32_bf16 v[106:109], v[10:13], v[170:173], v[118:121]
	v_mfma_f32_16x16x32_bf16 v[110:113], v[10:13], v[166:169], v[122:125]
	v_mfma_f32_16x16x32_bf16 v[10:13], v[10:13], v[162:165], v[126:129]
	v_mfma_f32_16x16x32_bf16 v[114:117], v[6:9], v[174:177], v[130:133]
	v_mfma_f32_16x16x32_bf16 v[118:121], v[6:9], v[170:173], v[134:137]
	v_mfma_f32_16x16x32_bf16 v[122:125], v[6:9], v[166:169], v[138:141]
	v_mfma_f32_16x16x32_bf16 v[6:9], v[6:9], v[162:165], v[142:145]
	v_mfma_f32_16x16x32_bf16 v[126:129], v[2:5], v[174:177], v[146:149]
	v_mfma_f32_16x16x32_bf16 v[130:133], v[2:5], v[170:173], v[150:153]
	v_mfma_f32_16x16x32_bf16 v[134:137], v[2:5], v[166:169], v[154:157]
	v_mfma_f32_16x16x32_bf16 v[2:5], v[2:5], v[162:165], v[158:161]
	s_waitcnt vmcnt(0)
	v_cndmask_b32_e32 v30, v0, v181, vcc
	v_cndmask_b32_e64 v28, v179, v184, s[40:41]
	v_cndmask_b32_e64 v26, v182, v185, s[42:43]
	v_cndmask_b32_e64 v0, v180, v186, s[44:45]
	s_waitcnt lgkmcnt(0)
	s_barrier
	ds_read_b128 v[138:141], v178 offset:24576
	ds_read_b128 v[142:145], v178 offset:25600
	ds_read_b128 v[146:149], v178 offset:26624
	ds_read_b128 v[150:153], v178 offset:27648
	ds_read_b128 v[154:157], v183 offset:32768
	ds_read_b128 v[158:161], v183 offset:33792
	ds_read_b128 v[162:165], v183 offset:34816
	ds_read_b128 v[166:169], v183 offset:35840
	ds_read_b128 v[170:173], v183 offset:36864
	ds_read_b128 v[174:177], v183 offset:37888
	ds_read_b128 v[178:181], v183 offset:38912
	ds_read_b128 v[182:185], v183 offset:39936
	s_waitcnt lgkmcnt(7)
	v_mfma_f32_16x16x32_bf16 v[32:35], v[154:157], v[138:141], v[34:37]
	v_mfma_f32_16x16x32_bf16 v[36:39], v[154:157], v[142:145], v[38:41]
	v_mfma_f32_16x16x32_bf16 v[40:43], v[154:157], v[146:149], v[42:45]
	v_mfma_f32_16x16x32_bf16 v[44:47], v[154:157], v[150:153], v[46:49]
	s_waitcnt lgkmcnt(6)
	v_mfma_f32_16x16x32_bf16 v[48:51], v[158:161], v[138:141], v[50:53]
	v_mfma_f32_16x16x32_bf16 v[52:55], v[158:161], v[142:145], v[54:57]
	v_mfma_f32_16x16x32_bf16 v[56:59], v[158:161], v[146:149], v[58:61]
	v_mfma_f32_16x16x32_bf16 v[60:63], v[158:161], v[150:153], v[62:65]
	s_waitcnt lgkmcnt(5)
	v_mfma_f32_16x16x32_bf16 v[64:67], v[162:165], v[138:141], v[66:69]
	v_mfma_f32_16x16x32_bf16 v[68:71], v[162:165], v[142:145], v[70:73]
	v_mfma_f32_16x16x32_bf16 v[72:75], v[162:165], v[146:149], v[74:77]
	v_mfma_f32_16x16x32_bf16 v[154:157], v[162:165], v[150:153], v[22:25]
	s_waitcnt lgkmcnt(4)
	v_mfma_f32_16x16x32_bf16 v[76:79], v[166:169], v[138:141], v[78:81]
	v_mfma_f32_16x16x32_bf16 v[80:83], v[166:169], v[142:145], v[82:85]
	v_mfma_f32_16x16x32_bf16 v[84:87], v[166:169], v[146:149], v[86:89]
	v_mfma_f32_16x16x32_bf16 v[158:161], v[166:169], v[150:153], v[18:21]
	s_waitcnt lgkmcnt(3)
	v_mfma_f32_16x16x32_bf16 v[88:91], v[170:173], v[138:141], v[90:93]
	v_mfma_f32_16x16x32_bf16 v[92:95], v[170:173], v[142:145], v[94:97]
	v_mfma_f32_16x16x32_bf16 v[96:99], v[170:173], v[146:149], v[98:101]
	v_mfma_f32_16x16x32_bf16 v[162:165], v[170:173], v[150:153], v[14:17]
	s_waitcnt lgkmcnt(2)
	v_mfma_f32_16x16x32_bf16 v[100:103], v[174:177], v[138:141], v[102:105]
	v_mfma_f32_16x16x32_bf16 v[104:107], v[174:177], v[142:145], v[106:109]
	v_mfma_f32_16x16x32_bf16 v[108:111], v[174:177], v[146:149], v[110:113]
	v_mfma_f32_16x16x32_bf16 v[166:169], v[174:177], v[150:153], v[10:13]
	s_waitcnt lgkmcnt(1)
	v_mfma_f32_16x16x32_bf16 v[112:115], v[178:181], v[138:141], v[114:117]
	v_mfma_f32_16x16x32_bf16 v[116:119], v[178:181], v[142:145], v[118:121]
	v_mfma_f32_16x16x32_bf16 v[22:25], v[178:181], v[146:149], v[122:125]
	v_mfma_f32_16x16x32_bf16 v[18:21], v[178:181], v[150:153], v[6:9]
	s_waitcnt lgkmcnt(0)
	v_mfma_f32_16x16x32_bf16 v[14:17], v[182:185], v[138:141], v[126:129]
	v_mfma_f32_16x16x32_bf16 v[10:13], v[182:185], v[142:145], v[130:133]
	v_mfma_f32_16x16x32_bf16 v[6:9], v[182:185], v[146:149], v[134:137]
	v_mfma_f32_16x16x32_bf16 v[2:5], v[182:185], v[150:153], v[2:5]
	v_mov_b32_e32 v27, v224
	s_movk_i32 s0, 0x210
	v_lshrrev_b32_e32 v120, 1, v27
	v_and_b32_e32 v31, 0x7fffff80, v27
	v_and_b32_e32 v120, 24, v120
	v_and_b32_e32 v29, 0x4f, v27
	v_lshl_or_b32 v31, v31, 1, v120
	v_pk_mul_f32 v[32:33], v[30:31], v[32:33] op_sel_hi:[0,1]
	v_pk_mul_f32 v[34:35], v[30:31], v[34:35] op_sel_hi:[0,1]
	v_mad_u32_u24 v29, v29, s0, v31
	v_cvt_pk_bf16_f32 v32, v32, v33
	v_cvt_pk_bf16_f32 v33, v34, v35
	v_pk_mul_f32 v[34:35], v[28:29], v[36:37] op_sel_hi:[0,1]
	v_pk_mul_f32 v[36:37], v[28:29], v[38:39] op_sel_hi:[0,1]
	v_cvt_pk_bf16_f32 v34, v34, v35
	v_cvt_pk_bf16_f32 v35, v36, v37
	v_pk_mul_f32 v[36:37], v[26:27], v[40:41] op_sel_hi:[0,1]
	v_pk_mul_f32 v[38:39], v[26:27], v[42:43] op_sel_hi:[0,1]
	v_cvt_pk_bf16_f32 v36, v36, v37
	v_cvt_pk_bf16_f32 v37, v38, v39
	v_pk_mul_f32 v[38:39], v[0:1], v[44:45] op_sel_hi:[0,1]
	v_pk_mul_f32 v[40:41], v[0:1], v[46:47] op_sel_hi:[0,1]
	v_cvt_pk_bf16_f32 v38, v38, v39
	v_cvt_pk_bf16_f32 v39, v40, v41
	v_pk_mul_f32 v[40:41], v[30:31], v[48:49] op_sel_hi:[0,1]
	v_pk_mul_f32 v[42:43], v[30:31], v[50:51] op_sel_hi:[0,1]
	v_cvt_pk_bf16_f32 v40, v40, v41
	v_cvt_pk_bf16_f32 v41, v42, v43
	s_barrier
	ds_write2_b64 v29, v[32:33], v[40:41] offset1:4
	v_pk_mul_f32 v[32:33], v[28:29], v[52:53] op_sel_hi:[0,1]
	v_pk_mul_f32 v[40:41], v[28:29], v[54:55] op_sel_hi:[0,1]
	v_cvt_pk_bf16_f32 v32, v32, v33
	v_cvt_pk_bf16_f32 v33, v40, v41
	v_add_u32_e32 v31, 0x2000, v29
	ds_write2_b64 v31, v[34:35], v[32:33] offset0:32 offset1:36
	v_pk_mul_f32 v[32:33], v[26:27], v[56:57] op_sel_hi:[0,1]
	v_pk_mul_f32 v[34:35], v[26:27], v[58:59] op_sel_hi:[0,1]
	v_cvt_pk_bf16_f32 v32, v32, v33
	v_cvt_pk_bf16_f32 v33, v34, v35
	v_add_u32_e32 v44, 0x4000, v29
	ds_write2_b64 v44, v[36:37], v[32:33] offset0:64 offset1:68
	v_pk_mul_f32 v[32:33], v[0:1], v[60:61] op_sel_hi:[0,1]
	v_pk_mul_f32 v[34:35], v[0:1], v[62:63] op_sel_hi:[0,1]
	v_cvt_pk_bf16_f32 v32, v32, v33
	v_cvt_pk_bf16_f32 v33, v34, v35
	v_add_u32_e32 v45, 0x6000, v29
	ds_write2_b64 v45, v[38:39], v[32:33] offset0:96 offset1:100
	v_pk_mul_f32 v[32:33], v[30:31], v[64:65] op_sel_hi:[0,1]
	v_pk_mul_f32 v[34:35], v[30:31], v[66:67] op_sel_hi:[0,1]
	v_cvt_pk_bf16_f32 v32, v32, v33
	v_cvt_pk_bf16_f32 v33, v34, v35
	v_pk_mul_f32 v[34:35], v[28:29], v[68:69] op_sel_hi:[0,1]
	v_pk_mul_f32 v[36:37], v[28:29], v[70:71] op_sel_hi:[0,1]
	v_cvt_pk_bf16_f32 v34, v34, v35
	v_cvt_pk_bf16_f32 v35, v36, v37
	v_pk_mul_f32 v[36:37], v[26:27], v[72:73] op_sel_hi:[0,1]
	v_pk_mul_f32 v[38:39], v[26:27], v[74:75] op_sel_hi:[0,1]
	v_cvt_pk_bf16_f32 v36, v36, v37
	v_cvt_pk_bf16_f32 v37, v38, v39
	v_pk_mul_f32 v[38:39], v[0:1], v[154:155] op_sel_hi:[0,1]
	v_pk_mul_f32 v[40:41], v[0:1], v[156:157] op_sel_hi:[0,1]
	v_cvt_pk_bf16_f32 v38, v38, v39
	v_cvt_pk_bf16_f32 v39, v40, v41
	v_pk_mul_f32 v[40:41], v[30:31], v[76:77] op_sel_hi:[0,1]
	v_pk_mul_f32 v[42:43], v[30:31], v[78:79] op_sel_hi:[0,1]
	v_cvt_pk_bf16_f32 v40, v40, v41
	v_cvt_pk_bf16_f32 v41, v42, v43
	ds_write2_b64 v29, v[32:33], v[40:41] offset0:8 offset1:12
	v_pk_mul_f32 v[32:33], v[28:29], v[80:81] op_sel_hi:[0,1]
	v_pk_mul_f32 v[40:41], v[28:29], v[82:83] op_sel_hi:[0,1]
	v_cvt_pk_bf16_f32 v32, v32, v33
	v_cvt_pk_bf16_f32 v33, v40, v41
	ds_write2_b64 v31, v[34:35], v[32:33] offset0:40 offset1:44
	v_pk_mul_f32 v[32:33], v[26:27], v[84:85] op_sel_hi:[0,1]
	v_pk_mul_f32 v[34:35], v[26:27], v[86:87] op_sel_hi:[0,1]
	v_cvt_pk_bf16_f32 v32, v32, v33
	v_cvt_pk_bf16_f32 v33, v34, v35
	ds_write2_b64 v44, v[36:37], v[32:33] offset0:72 offset1:76
	v_pk_mul_f32 v[32:33], v[0:1], v[158:159] op_sel_hi:[0,1]
	v_pk_mul_f32 v[34:35], v[0:1], v[160:161] op_sel_hi:[0,1]
	v_cvt_pk_bf16_f32 v32, v32, v33
	v_cvt_pk_bf16_f32 v33, v34, v35
	ds_write2_b64 v45, v[38:39], v[32:33] offset0:104 offset1:108
	v_pk_mul_f32 v[32:33], v[30:31], v[88:89] op_sel_hi:[0,1]
	v_pk_mul_f32 v[34:35], v[30:31], v[90:91] op_sel_hi:[0,1]
	v_cvt_pk_bf16_f32 v32, v32, v33
	v_cvt_pk_bf16_f32 v33, v34, v35
	v_pk_mul_f32 v[34:35], v[28:29], v[92:93] op_sel_hi:[0,1]
	v_pk_mul_f32 v[36:37], v[28:29], v[94:95] op_sel_hi:[0,1]
	v_cvt_pk_bf16_f32 v34, v34, v35
	v_cvt_pk_bf16_f32 v35, v36, v37
	v_pk_mul_f32 v[36:37], v[26:27], v[96:97] op_sel_hi:[0,1]
	v_pk_mul_f32 v[38:39], v[26:27], v[98:99] op_sel_hi:[0,1]
	v_cvt_pk_bf16_f32 v36, v36, v37
	v_cvt_pk_bf16_f32 v37, v38, v39
	v_pk_mul_f32 v[38:39], v[0:1], v[162:163] op_sel_hi:[0,1]
	v_pk_mul_f32 v[40:41], v[0:1], v[164:165] op_sel_hi:[0,1]
	v_cvt_pk_bf16_f32 v38, v38, v39
	v_cvt_pk_bf16_f32 v39, v40, v41
	v_pk_mul_f32 v[40:41], v[30:31], v[100:101] op_sel_hi:[0,1]
	v_pk_mul_f32 v[42:43], v[30:31], v[102:103] op_sel_hi:[0,1]
	v_cvt_pk_bf16_f32 v40, v40, v41
	v_cvt_pk_bf16_f32 v41, v42, v43
	ds_write2_b64 v29, v[32:33], v[40:41] offset0:16 offset1:20
	v_pk_mul_f32 v[32:33], v[28:29], v[104:105] op_sel_hi:[0,1]
	v_pk_mul_f32 v[40:41], v[28:29], v[106:107] op_sel_hi:[0,1]
	v_cvt_pk_bf16_f32 v32, v32, v33
	v_cvt_pk_bf16_f32 v33, v40, v41
	ds_write2_b64 v31, v[34:35], v[32:33] offset0:48 offset1:52
	v_pk_mul_f32 v[32:33], v[26:27], v[108:109] op_sel_hi:[0,1]
	v_pk_mul_f32 v[34:35], v[26:27], v[110:111] op_sel_hi:[0,1]
	v_cvt_pk_bf16_f32 v32, v32, v33
	v_cvt_pk_bf16_f32 v33, v34, v35
	ds_write2_b64 v44, v[36:37], v[32:33] offset0:80 offset1:84
	v_pk_mul_f32 v[32:33], v[0:1], v[166:167] op_sel_hi:[0,1]
	v_pk_mul_f32 v[34:35], v[0:1], v[168:169] op_sel_hi:[0,1]
	v_cvt_pk_bf16_f32 v32, v32, v33
	v_cvt_pk_bf16_f32 v33, v34, v35
	v_pk_mul_f32 v[18:19], v[0:1], v[18:19] op_sel_hi:[0,1]
	v_pk_mul_f32 v[20:21], v[0:1], v[20:21] op_sel_hi:[0,1]
	v_pk_mul_f32 v[2:3], v[0:1], v[2:3] op_sel_hi:[0,1]
	v_pk_mul_f32 v[4:5], v[0:1], v[4:5] op_sel_hi:[0,1]
	v_lshlrev_b32_e32 v0, 3, v27
	ds_write2_b64 v45, v[38:39], v[32:33] offset0:112 offset1:116
	v_pk_mul_f32 v[32:33], v[30:31], v[112:113] op_sel_hi:[0,1]
	v_pk_mul_f32 v[34:35], v[30:31], v[114:115] op_sel_hi:[0,1]
	v_cvt_pk_bf16_f32 v18, v18, v19
	v_cvt_pk_bf16_f32 v19, v20, v21
	v_cvt_pk_bf16_f32 v2, v2, v3
	v_cvt_pk_bf16_f32 v3, v4, v5
	v_and_b32_e32 v0, 0xf8, v0
	v_cvt_pk_bf16_f32 v32, v32, v33
	v_cvt_pk_bf16_f32 v33, v34, v35
	v_pk_mul_f32 v[34:35], v[28:29], v[116:117] op_sel_hi:[0,1]
	v_pk_mul_f32 v[36:37], v[28:29], v[118:119] op_sel_hi:[0,1]
	v_pk_mul_f32 v[22:23], v[26:27], v[22:23] op_sel_hi:[0,1]
	v_pk_mul_f32 v[24:25], v[26:27], v[24:25] op_sel_hi:[0,1]
	v_pk_mul_f32 v[14:15], v[30:31], v[14:15] op_sel_hi:[0,1]
	v_pk_mul_f32 v[16:17], v[30:31], v[16:17] op_sel_hi:[0,1]
	v_pk_mul_f32 v[10:11], v[28:29], v[10:11] op_sel_hi:[0,1]
	v_pk_mul_f32 v[12:13], v[28:29], v[12:13] op_sel_hi:[0,1]
	v_pk_mul_f32 v[6:7], v[26:27], v[6:7] op_sel_hi:[0,1]
	v_pk_mul_f32 v[8:9], v[26:27], v[8:9] op_sel_hi:[0,1]
	ds_write2_b64 v45, v[18:19], v[2:3] offset0:120 offset1:124
	v_or_b32_e32 v2, s82, v0
	s_movk_i32 s0, 0x800
	v_cvt_pk_bf16_f32 v34, v34, v35
	v_cvt_pk_bf16_f32 v35, v36, v37
	v_cvt_pk_bf16_f32 v22, v22, v23
	v_cvt_pk_bf16_f32 v23, v24, v25
	v_cvt_pk_bf16_f32 v14, v14, v15
	v_cvt_pk_bf16_f32 v15, v16, v17
	v_cvt_pk_bf16_f32 v10, v10, v11
	v_cvt_pk_bf16_f32 v11, v12, v13
	v_cvt_pk_bf16_f32 v6, v6, v7
	v_cvt_pk_bf16_f32 v7, v8, v9
	v_cmp_gt_i32_e64 s[44:45], s0, v2
	s_mov_b64 s[12:13], 12
	s_mov_b64 s[40:41], s[54:55]
	s_mov_b32 s0, s82
	ds_write2_b64 v29, v[32:33], v[14:15] offset0:24 offset1:28
	ds_write2_b64 v31, v[34:35], v[10:11] offset0:56 offset1:60
	ds_write2_b64 v44, v[22:23], v[6:7] offset0:88 offset1:92
	s_waitcnt lgkmcnt(0)
	s_barrier

.LBB0_119:
	s_mul_i32 s68, s1, 0x6000
	s_add_i32 s69, s68, 0xffffa000
	s_cmp_gt_i32 s1, 0
	s_waitcnt vmcnt(6)
	s_cselect_b32 s69, s69, 0xc000
	s_waitcnt lgkmcnt(0)
	s_barrier
	s_setprio 2
	v_or_b32_e32 v0, s68, v146
	v_add_u32_e32 v0, v0, v144
	v_add3_u32 v212, s68, v145, v144
	ds_read_b128 v[164:167], v212 offset:8192
	ds_read_b128 v[148:151], v0
	ds_read_b128 v[152:155], v0 offset:1024
	ds_read_b128 v[156:159], v0 offset:2048
	ds_read_b128 v[160:163], v0 offset:3072
	ds_read_b128 v[168:171], v212 offset:9216
	ds_read_b128 v[172:175], v212 offset:10240
	ds_read_b128 v[176:179], v212 offset:11264
	ds_read_b128 v[180:183], v212 offset:12288
	ds_read_b128 v[184:187], v212 offset:13312
	ds_read_b128 v[188:191], v212 offset:14336
	ds_read_b128 v[192:195], v212 offset:15360
	v_lshl_add_u64 v[212:213], v[142:143], 0, s[42:43]
	v_lshl_add_u64 v[212:213], v[130:131], 1, v[212:213]
	s_add_i32 s70, s69, s15
	s_mov_b32 m0, s70
	s_nop 0
	global_load_lds_dwordx4 v[212:213], off
	v_lshl_add_u64 v[212:213], v[142:143], 0, s[42:43]
	v_lshl_add_u64 v[212:213], v[132:133], 1, v[212:213]
	s_add_i32 s70, s69, s13
	s_mov_b32 m0, s70
	s_nop 0
	global_load_lds_dwordx4 v[212:213], off
	s_add_i32 s69, s14, s69
	v_lshl_add_u64 v[212:213], v[140:141], 0, s[42:43]
	s_mov_b32 m0, s69
	s_nop 0
	global_load_lds_dwordx4 v[212:213], off
	v_lshl_add_u64 v[212:213], v[138:139], 0, s[42:43]
	s_add_i32 s70, s69, 0x400
	s_mov_b32 m0, s70
	s_nop 0
	global_load_lds_dwordx4 v[212:213], off
	v_lshl_add_u64 v[212:213], v[136:137], 0, s[42:43]
	s_add_i32 s70, s69, 0x800
	s_mov_b32 m0, s70
	s_nop 0
	global_load_lds_dwordx4 v[212:213], off
	v_lshl_add_u64 v[212:213], v[134:135], 0, s[42:43]
	s_addk_i32 s69, 0xc00
	s_mov_b32 m0, s69
	s_nop 0
	global_load_lds_dwordx4 v[212:213], off
	s_setprio 0
	s_waitcnt lgkmcnt(10)
	v_mfma_f32_16x16x32_bf16 v[126:129], v[164:167], v[148:151], v[126:129]
	s_waitcnt lgkmcnt(9)
	v_mfma_f32_16x16x32_bf16 v[122:125], v[164:167], v[152:155], v[122:125]
	s_waitcnt lgkmcnt(8)
	v_mfma_f32_16x16x32_bf16 v[118:121], v[164:167], v[156:159], v[118:121]
	s_waitcnt lgkmcnt(7)
	v_mfma_f32_16x16x32_bf16 v[114:117], v[164:167], v[160:163], v[114:117]
	s_waitcnt lgkmcnt(6)
	v_mfma_f32_16x16x32_bf16 v[110:113], v[168:171], v[148:151], v[110:113]
	v_mfma_f32_16x16x32_bf16 v[106:109], v[168:171], v[152:155], v[106:109]
	v_mfma_f32_16x16x32_bf16 v[102:105], v[168:171], v[156:159], v[102:105]
	v_mfma_f32_16x16x32_bf16 v[98:101], v[168:171], v[160:163], v[98:101]
	s_waitcnt lgkmcnt(5)
	v_mfma_f32_16x16x32_bf16 v[94:97], v[172:175], v[148:151], v[94:97]
	v_mfma_f32_16x16x32_bf16 v[90:93], v[172:175], v[152:155], v[90:93]
	v_mfma_f32_16x16x32_bf16 v[86:89], v[172:175], v[156:159], v[86:89]
	v_mfma_f32_16x16x32_bf16 v[82:85], v[172:175], v[160:163], v[82:85]
	s_waitcnt lgkmcnt(4)
	v_mfma_f32_16x16x32_bf16 v[78:81], v[176:179], v[148:151], v[78:81]
	v_mfma_f32_16x16x32_bf16 v[74:77], v[176:179], v[152:155], v[74:77]
	v_mfma_f32_16x16x32_bf16 v[70:73], v[176:179], v[156:159], v[70:73]
	v_mfma_f32_16x16x32_bf16 v[66:69], v[176:179], v[160:163], v[66:69]
	s_waitcnt lgkmcnt(3)
	v_mfma_f32_16x16x32_bf16 v[62:65], v[180:183], v[148:151], v[62:65]
	v_mfma_f32_16x16x32_bf16 v[58:61], v[180:183], v[152:155], v[58:61]
	v_mfma_f32_16x16x32_bf16 v[54:57], v[180:183], v[156:159], v[54:57]
	v_mfma_f32_16x16x32_bf16 v[50:53], v[180:183], v[160:163], v[50:53]
	s_waitcnt lgkmcnt(2)
	v_mfma_f32_16x16x32_bf16 v[46:49], v[184:187], v[148:151], v[46:49]
	v_mfma_f32_16x16x32_bf16 v[42:45], v[184:187], v[152:155], v[42:45]
	v_mfma_f32_16x16x32_bf16 v[38:41], v[184:187], v[156:159], v[38:41]
	v_mfma_f32_16x16x32_bf16 v[34:37], v[184:187], v[160:163], v[34:37]
	s_waitcnt lgkmcnt(1)
	v_mfma_f32_16x16x32_bf16 v[30:33], v[188:191], v[148:151], v[30:33]
	v_mfma_f32_16x16x32_bf16 v[26:29], v[188:191], v[152:155], v[26:29]
	v_mfma_f32_16x16x32_bf16 v[22:25], v[188:191], v[156:159], v[22:25]
	v_mfma_f32_16x16x32_bf16 v[18:21], v[188:191], v[160:163], v[18:21]
	s_waitcnt lgkmcnt(0)
	v_mfma_f32_16x16x32_bf16 v[14:17], v[192:195], v[148:151], v[14:17]
	v_mfma_f32_16x16x32_bf16 v[10:13], v[192:195], v[152:155], v[10:13]
	v_mfma_f32_16x16x32_bf16 v[6:9], v[192:195], v[156:159], v[6:9]
	v_mfma_f32_16x16x32_bf16 v[2:5], v[192:195], v[160:163], v[2:5]
	s_add_i32 s68, s1, 1
	s_cmp_lg_u32 s1, 2
	s_cselect_b32 s1, s68, 0
	s_add_u32 s42, s42, 64
	s_addc_u32 s43, s43, 0
	s_cmpk_eq_i32 s42, 0x1500
	s_cbranch_scc0 .LBB0_119
	s_waitcnt vmcnt(6)
	v_add_u32_e32 v0, v146, v144
	v_add_u32_e32 v221, v145, v144
	s_waitcnt lgkmcnt(0)
	s_barrier
	ds_read_b128 v[130:133], v0
	ds_read_b128 v[134:137], v0 offset:1024
	ds_read_b128 v[138:141], v0 offset:2048
	ds_read_b128 v[146:149], v0 offset:3072
	ds_read_b128 v[142:145], v221 offset:8192
	ds_read_b128 v[150:153], v221 offset:9216
	ds_read_b128 v[154:157], v221 offset:10240
	ds_read_b128 v[158:161], v221 offset:11264
	ds_read_b128 v[162:165], v221 offset:12288
	ds_read_b128 v[166:169], v221 offset:13312
	ds_read_b128 v[170:173], v221 offset:14336
	ds_read_b128 v[174:177], v221 offset:15360
	s_waitcnt lgkmcnt(7)
	v_mfma_f32_16x16x32_bf16 v[126:129], v[142:145], v[130:133], v[126:129]
	v_mfma_f32_16x16x32_bf16 v[122:125], v[142:145], v[134:137], v[122:125]
	v_mfma_f32_16x16x32_bf16 v[118:121], v[142:145], v[138:141], v[118:121]
	v_mfma_f32_16x16x32_bf16 v[114:117], v[142:145], v[146:149], v[114:117]
	s_waitcnt lgkmcnt(6)
	v_mfma_f32_16x16x32_bf16 v[110:113], v[150:153], v[130:133], v[110:113]
	v_mfma_f32_16x16x32_bf16 v[106:109], v[150:153], v[134:137], v[106:109]
	v_mfma_f32_16x16x32_bf16 v[102:105], v[150:153], v[138:141], v[102:105]
	v_mfma_f32_16x16x32_bf16 v[98:101], v[150:153], v[146:149], v[98:101]
	s_waitcnt lgkmcnt(5)
	v_mfma_f32_16x16x32_bf16 v[94:97], v[154:157], v[130:133], v[94:97]
	v_mfma_f32_16x16x32_bf16 v[90:93], v[154:157], v[134:137], v[90:93]
	v_mfma_f32_16x16x32_bf16 v[86:89], v[154:157], v[138:141], v[86:89]
	v_mfma_f32_16x16x32_bf16 v[82:85], v[154:157], v[146:149], v[82:85]
	s_waitcnt lgkmcnt(4)
	v_mfma_f32_16x16x32_bf16 v[78:81], v[158:161], v[130:133], v[78:81]
	v_mfma_f32_16x16x32_bf16 v[74:77], v[158:161], v[134:137], v[74:77]
	v_mfma_f32_16x16x32_bf16 v[70:73], v[158:161], v[138:141], v[70:73]
	v_mfma_f32_16x16x32_bf16 v[66:69], v[158:161], v[146:149], v[66:69]
	s_waitcnt lgkmcnt(3)
	v_mfma_f32_16x16x32_bf16 v[142:145], v[162:165], v[130:133], v[62:65]
	v_mfma_f32_16x16x32_bf16 v[150:153], v[162:165], v[134:137], v[58:61]
	v_mfma_f32_16x16x32_bf16 v[154:157], v[162:165], v[138:141], v[54:57]
	v_mfma_f32_16x16x32_bf16 v[158:161], v[162:165], v[146:149], v[50:53]
	s_waitcnt lgkmcnt(2)
	v_mfma_f32_16x16x32_bf16 v[162:165], v[166:169], v[130:133], v[46:49]
	v_mfma_f32_16x16x32_bf16 v[178:181], v[166:169], v[134:137], v[42:45]
	v_mfma_f32_16x16x32_bf16 v[182:185], v[166:169], v[138:141], v[38:41]
	v_mfma_f32_16x16x32_bf16 v[166:169], v[166:169], v[146:149], v[34:37]
	s_waitcnt lgkmcnt(1)
	v_mfma_f32_16x16x32_bf16 v[186:189], v[170:173], v[130:133], v[30:33]
	v_mfma_f32_16x16x32_bf16 v[190:193], v[170:173], v[134:137], v[26:29]
	v_mfma_f32_16x16x32_bf16 v[194:197], v[170:173], v[138:141], v[22:25]
	v_mfma_f32_16x16x32_bf16 v[170:173], v[170:173], v[146:149], v[18:21]
	s_waitcnt lgkmcnt(0)
	v_mfma_f32_16x16x32_bf16 v[130:133], v[174:177], v[130:133], v[14:17]
	v_mfma_f32_16x16x32_bf16 v[134:137], v[174:177], v[134:137], v[10:13]
	v_mfma_f32_16x16x32_bf16 v[138:141], v[174:177], v[138:141], v[6:9]
	v_mfma_f32_16x16x32_bf16 v[146:149], v[174:177], v[146:149], v[2:5]
	s_waitcnt vmcnt(0)
	s_waitcnt lgkmcnt(0)
	s_barrier
	ds_read_b128 v[174:177], v0 offset:24576
	ds_read_b128 v[198:201], v0 offset:25600
	ds_read_b128 v[202:205], v0 offset:26624
	ds_read_b128 v[206:209], v0 offset:27648
	ds_read_b128 v[14:17], v221 offset:32768
	ds_read_b128 v[30:33], v221 offset:33792
	ds_read_b128 v[46:49], v221 offset:34816
	ds_read_b128 v[62:65], v221 offset:35840
	ds_read_b128 v[210:213], v221 offset:36864
	ds_read_b128 v[216:219], v221 offset:37888
	ds_read_b128 v[226:229], v221 offset:38912
	ds_read_b128 v[230:233], v221 offset:39936
	s_waitcnt lgkmcnt(7)
	v_mfma_f32_16x16x32_bf16 v[2:5], v[14:17], v[174:177], v[126:129]
	v_mfma_f32_16x16x32_bf16 v[6:9], v[14:17], v[198:201], v[122:125]
	v_mfma_f32_16x16x32_bf16 v[10:13], v[14:17], v[202:205], v[118:121]
	v_mfma_f32_16x16x32_bf16 v[14:17], v[14:17], v[206:209], v[114:117]
	s_waitcnt lgkmcnt(6)
	v_mfma_f32_16x16x32_bf16 v[18:21], v[30:33], v[174:177], v[110:113]
	v_mfma_f32_16x16x32_bf16 v[22:25], v[30:33], v[198:201], v[106:109]
	v_mfma_f32_16x16x32_bf16 v[26:29], v[30:33], v[202:205], v[102:105]
	v_mfma_f32_16x16x32_bf16 v[30:33], v[30:33], v[206:209], v[98:101]
	s_waitcnt lgkmcnt(5)
	v_mfma_f32_16x16x32_bf16 v[34:37], v[46:49], v[174:177], v[94:97]
	v_mfma_f32_16x16x32_bf16 v[38:41], v[46:49], v[198:201], v[90:93]
	v_mfma_f32_16x16x32_bf16 v[42:45], v[46:49], v[202:205], v[86:89]
	v_mfma_f32_16x16x32_bf16 v[46:49], v[46:49], v[206:209], v[82:85]
	s_waitcnt lgkmcnt(4)
	v_mfma_f32_16x16x32_bf16 v[50:53], v[62:65], v[174:177], v[78:81]
	v_mfma_f32_16x16x32_bf16 v[54:57], v[62:65], v[198:201], v[74:77]
	v_mfma_f32_16x16x32_bf16 v[58:61], v[62:65], v[202:205], v[70:73]
	v_mfma_f32_16x16x32_bf16 v[62:65], v[62:65], v[206:209], v[66:69]
	s_waitcnt lgkmcnt(3)
	v_mfma_f32_16x16x32_bf16 v[66:69], v[210:213], v[174:177], v[142:145]
	v_mfma_f32_16x16x32_bf16 v[70:73], v[210:213], v[198:201], v[150:153]
	v_mfma_f32_16x16x32_bf16 v[74:77], v[210:213], v[202:205], v[154:157]
	v_mfma_f32_16x16x32_bf16 v[78:81], v[210:213], v[206:209], v[158:161]
	s_waitcnt lgkmcnt(2)
	v_mfma_f32_16x16x32_bf16 v[82:85], v[216:219], v[174:177], v[162:165]
	v_mfma_f32_16x16x32_bf16 v[86:89], v[216:219], v[198:201], v[178:181]
	v_mfma_f32_16x16x32_bf16 v[90:93], v[216:219], v[202:205], v[182:185]
	v_mfma_f32_16x16x32_bf16 v[94:97], v[216:219], v[206:209], v[166:169]
	s_waitcnt lgkmcnt(1)
	v_mfma_f32_16x16x32_bf16 v[98:101], v[226:229], v[174:177], v[186:189]
	v_mfma_f32_16x16x32_bf16 v[102:105], v[226:229], v[198:201], v[190:193]
	v_mfma_f32_16x16x32_bf16 v[106:109], v[226:229], v[202:205], v[194:197]
	v_mfma_f32_16x16x32_bf16 v[110:113], v[226:229], v[206:209], v[170:173]
	s_waitcnt lgkmcnt(0)
	v_mfma_f32_16x16x32_bf16 v[114:117], v[230:233], v[174:177], v[130:133]
	v_mfma_f32_16x16x32_bf16 v[118:121], v[230:233], v[198:201], v[134:137]
	v_mfma_f32_16x16x32_bf16 v[122:125], v[230:233], v[202:205], v[138:141]
	v_mfma_f32_16x16x32_bf16 v[126:129], v[230:233], v[206:209], v[146:149]
	v_mov_b32_e32 v130, v224
	s_ashr_i32 s13, s12, 31
	v_and_b32_e32 v131, 31, v130
	v_ashrrev_i32_e32 v197, 7, v130
	v_ashrrev_i32_e32 v132, 5, v130
	v_lshlrev_b32_e32 v0, 2, v131
	s_lshl_b64 s[68:69], s[12:13], 11
	v_lshlrev_b32_e32 v164, 4, v131
	v_cmp_eq_u32_e64 s[42:43], 0, v131
	v_and_b32_e32 v131, 0x4f, v130
	v_and_b32_e32 v130, 48, v130
	s_movk_i32 s13, 0x210
	v_cmp_lt_i32_e32 vcc, v247, v214
	v_mad_u32_u24 v202, v131, s13, v130
	s_ashr_i32 s1, s0, 31
	v_cndmask_b32_e32 v130, v225, v247, vcc
	v_cmp_lt_i32_e32 vcc, v248, v214
	v_lshlrev_b32_e32 v203, 2, v130
	s_lshl_b32 s70, s87, 1
	v_cndmask_b32_e32 v130, v225, v248, vcc
	v_cmp_lt_i32_e32 vcc, v249, v214
	v_lshlrev_b32_e32 v204, 2, v130
	v_lshl_or_b32 v0, v132, 10, v0
	v_cndmask_b32_e32 v130, v225, v249, vcc
	v_cmp_lt_i32_e32 vcc, v223, v214
	v_lshlrev_b32_e32 v205, 2, v130
	v_mul_lo_u32 v165, v132, s13
	v_cndmask_b32_e32 v130, v225, v223, vcc
	v_cmp_lt_i32_e32 vcc, v252, v214
	v_lshlrev_b32_e32 v206, 2, v130
	s_mov_b32 s14, 0
	v_cndmask_b32_e32 v130, v225, v252, vcc
	v_lshlrev_b32_e32 v207, 2, v130
	v_add_u32_e32 v130, s12, v132
	v_ashrrev_i32_e32 v131, 31, v130
	s_add_u32 s12, s74, s68
	v_lshlrev_b64 v[132:133], 5, v[130:131]
	v_add_u32_e32 v134, 8, v130
	v_add_u32_e32 v136, 16, v130
	v_add_u32_e32 v138, 24, v130
	v_add_u32_e32 v140, 32, v130
	v_add_u32_e32 v142, 40, v130
	v_add_u32_e32 v144, 48, v130
	v_add_u32_e32 v146, 56, v130
	v_add_u32_e32 v148, 64, v130
	v_add_u32_e32 v150, 0x48, v130
	v_add_u32_e32 v152, 0x50, v130
	v_add_u32_e32 v154, 0x58, v130
	v_add_u32_e32 v156, 0x60, v130
	v_add_u32_e32 v158, 0x68, v130
	v_add_u32_e32 v160, 0x70, v130
	v_add_u32_e32 v130, 0x78, v130
	s_addc_u32 s13, s75, s69
	s_lshl_b64 s[0:1], s[0:1], 1
	v_ashrrev_i32_e32 v135, 31, v134
	v_ashrrev_i32_e32 v137, 31, v136
	v_ashrrev_i32_e32 v139, 31, v138
	v_ashrrev_i32_e32 v141, 31, v140
	v_ashrrev_i32_e32 v143, 31, v142
	v_ashrrev_i32_e32 v145, 31, v144
	v_ashrrev_i32_e32 v147, 31, v146
	v_ashrrev_i32_e32 v149, 31, v148
	v_ashrrev_i32_e32 v151, 31, v150
	v_ashrrev_i32_e32 v153, 31, v152
	v_ashrrev_i32_e32 v155, 31, v154
	v_ashrrev_i32_e32 v157, 31, v156
	v_ashrrev_i32_e32 v159, 31, v158
	v_ashrrev_i32_e32 v161, 31, v160
	v_ashrrev_i32_e32 v131, 31, v130
	s_add_u32 s0, s12, s0
	v_lshlrev_b64 v[134:135], 5, v[134:135]
	v_lshlrev_b64 v[136:137], 5, v[136:137]
	v_lshlrev_b64 v[138:139], 5, v[138:139]
	v_lshlrev_b64 v[140:141], 5, v[140:141]
	v_lshlrev_b64 v[142:143], 5, v[142:143]
	v_lshlrev_b64 v[144:145], 5, v[144:145]
	v_lshlrev_b64 v[146:147], 5, v[146:147]
	v_lshlrev_b64 v[148:149], 5, v[148:149]
	v_lshlrev_b64 v[150:151], 5, v[150:151]
	v_lshlrev_b64 v[152:153], 5, v[152:153]
	v_lshlrev_b64 v[154:155], 5, v[154:155]
	v_lshlrev_b64 v[156:157], 5, v[156:157]
	v_lshlrev_b64 v[158:159], 5, v[158:159]
	v_lshlrev_b64 v[160:161], 5, v[160:161]
	v_lshlrev_b64 v[162:163], 5, v[130:131]
	s_addc_u32 s1, s13, s1
	v_lshl_add_u64 v[130:131], v[0:1], 1, s[0:1]
	v_lshl_add_u64 v[132:133], s[44:45], 0, v[132:133]
	v_lshl_add_u64 v[134:135], s[44:45], 0, v[134:135]
	v_lshl_add_u64 v[136:137], s[44:45], 0, v[136:137]
	v_lshl_add_u64 v[138:139], s[44:45], 0, v[138:139]
	v_lshl_add_u64 v[140:141], s[44:45], 0, v[140:141]
	v_lshl_add_u64 v[142:143], s[44:45], 0, v[142:143]
	v_lshl_add_u64 v[144:145], s[44:45], 0, v[144:145]
	v_lshl_add_u64 v[146:147], s[44:45], 0, v[146:147]
	v_lshl_add_u64 v[148:149], s[44:45], 0, v[148:149]
	v_lshl_add_u64 v[150:151], s[44:45], 0, v[150:151]
	v_lshl_add_u64 v[152:153], s[44:45], 0, v[152:153]
	v_lshl_add_u64 v[154:155], s[44:45], 0, v[154:155]
	v_lshl_add_u64 v[156:157], s[44:45], 0, v[156:157]
	v_lshl_add_u64 v[158:159], s[44:45], 0, v[158:159]
	v_lshl_add_u64 v[160:161], s[44:45], 0, v[160:161]
	v_lshl_add_u64 v[162:163], s[44:45], 0, v[162:163]
	s_mov_b64 s[0:1], -1
	v_add_u32_e32 v0, v164, v165
	s_branch .LBB0_122

.LBB0_167:
	s_mul_i32 s4, s43, 0x6000
	s_add_i32 s5, s4, 0xffffa000
	s_cmp_gt_i32 s43, 0
	s_waitcnt vmcnt(6)
	s_cselect_b32 s5, s5, 0xc000
	s_waitcnt lgkmcnt(0)
	s_barrier
	s_setprio 2
	v_add3_u32 v0, s4, v177, v176
	v_add_u32_e32 v0, s47, v0
	v_add3_u32 v212, s4, v178, v176
	ds_read_b128 v[196:199], v212 offset:8192
	ds_read_b128 v[180:183], v0
	ds_read_b128 v[184:187], v0 offset:1024
	ds_read_b128 v[188:191], v0 offset:2048
	ds_read_b128 v[192:195], v0 offset:3072
	ds_read_b128 v[200:203], v212 offset:9216
	ds_read_b128 v[204:207], v212 offset:10240
	ds_read_b128 v[208:211], v212 offset:11264
	ds_read_b128 v[216:219], v212 offset:12288
	ds_read_b128 v[226:229], v212 offset:13312
	ds_read_b128 v[230:233], v212 offset:14336
	ds_read_b128 v[234:237], v212 offset:15360
	v_lshl_add_u64 v[212:213], v[174:175], 0, s[12:13]
	v_lshl_add_u64 v[212:213], v[162:163], 1, v[212:213]
	s_add_i32 s44, s5, s42
	s_mov_b32 m0, s44
	s_nop 0
	global_load_lds_dwordx4 v[212:213], off
	v_lshl_add_u64 v[212:213], v[174:175], 0, s[12:13]
	v_lshl_add_u64 v[212:213], v[164:165], 1, v[212:213]
	s_add_i32 s44, s5, s40
	s_mov_b32 m0, s44
	s_nop 0
	global_load_lds_dwordx4 v[212:213], off
	s_add_i32 s5, s41, s5
	v_lshl_add_u64 v[212:213], v[172:173], 0, s[12:13]
	s_mov_b32 m0, s5
	s_nop 0
	global_load_lds_dwordx4 v[212:213], off
	v_lshl_add_u64 v[212:213], v[170:171], 0, s[12:13]
	s_add_i32 s44, s5, 0x400
	s_mov_b32 m0, s44
	s_nop 0
	global_load_lds_dwordx4 v[212:213], off
	v_lshl_add_u64 v[212:213], v[168:169], 0, s[12:13]
	s_add_i32 s44, s5, 0x800
	s_mov_b32 m0, s44
	s_nop 0
	global_load_lds_dwordx4 v[212:213], off
	s_addk_i32 s5, 0xc00
	v_lshl_add_u64 v[212:213], v[166:167], 0, s[12:13]
	s_mov_b32 m0, s5
	s_nop 0
	global_load_lds_dwordx4 v[212:213], off
	s_setprio 0
	s_waitcnt lgkmcnt(10)
	v_mfma_f32_16x16x32_bf16 v[34:37], v[196:199], v[180:183], v[34:37]
	s_waitcnt lgkmcnt(9)
	v_mfma_f32_16x16x32_bf16 v[38:41], v[196:199], v[184:187], v[38:41]
	s_waitcnt lgkmcnt(8)
	v_mfma_f32_16x16x32_bf16 v[42:45], v[196:199], v[188:191], v[42:45]
	s_waitcnt lgkmcnt(7)
	v_mfma_f32_16x16x32_bf16 v[46:49], v[196:199], v[192:195], v[46:49]
	s_waitcnt lgkmcnt(6)
	v_mfma_f32_16x16x32_bf16 v[50:53], v[200:203], v[180:183], v[50:53]
	v_mfma_f32_16x16x32_bf16 v[54:57], v[200:203], v[184:187], v[54:57]
	v_mfma_f32_16x16x32_bf16 v[58:61], v[200:203], v[188:191], v[58:61]
	v_mfma_f32_16x16x32_bf16 v[62:65], v[200:203], v[192:195], v[62:65]
	s_waitcnt lgkmcnt(5)
	v_mfma_f32_16x16x32_bf16 v[66:69], v[204:207], v[180:183], v[66:69]
	v_mfma_f32_16x16x32_bf16 v[70:73], v[204:207], v[184:187], v[70:73]
	v_mfma_f32_16x16x32_bf16 v[74:77], v[204:207], v[188:191], v[74:77]
	v_mfma_f32_16x16x32_bf16 v[78:81], v[204:207], v[192:195], v[78:81]
	s_waitcnt lgkmcnt(4)
	v_mfma_f32_16x16x32_bf16 v[82:85], v[208:211], v[180:183], v[82:85]
	v_mfma_f32_16x16x32_bf16 v[86:89], v[208:211], v[184:187], v[86:89]
	v_mfma_f32_16x16x32_bf16 v[90:93], v[208:211], v[188:191], v[90:93]
	v_mfma_f32_16x16x32_bf16 v[94:97], v[208:211], v[192:195], v[94:97]
	s_waitcnt lgkmcnt(3)
	v_mfma_f32_16x16x32_bf16 v[98:101], v[216:219], v[180:183], v[98:101]
	v_mfma_f32_16x16x32_bf16 v[102:105], v[216:219], v[184:187], v[102:105]
	v_mfma_f32_16x16x32_bf16 v[106:109], v[216:219], v[188:191], v[106:109]
	v_mfma_f32_16x16x32_bf16 v[110:113], v[216:219], v[192:195], v[110:113]
	s_waitcnt lgkmcnt(2)
	v_mfma_f32_16x16x32_bf16 v[114:117], v[226:229], v[180:183], v[114:117]
	v_mfma_f32_16x16x32_bf16 v[118:121], v[226:229], v[184:187], v[118:121]
	v_mfma_f32_16x16x32_bf16 v[122:125], v[226:229], v[188:191], v[122:125]
	v_mfma_f32_16x16x32_bf16 v[126:129], v[226:229], v[192:195], v[126:129]
	s_waitcnt lgkmcnt(1)
	v_mfma_f32_16x16x32_bf16 v[130:133], v[230:233], v[180:183], v[130:133]
	v_mfma_f32_16x16x32_bf16 v[134:137], v[230:233], v[184:187], v[134:137]
	v_mfma_f32_16x16x32_bf16 v[138:141], v[230:233], v[188:191], v[138:141]
	v_mfma_f32_16x16x32_bf16 v[142:145], v[230:233], v[192:195], v[142:145]
	s_waitcnt lgkmcnt(0)
	v_mfma_f32_16x16x32_bf16 v[146:149], v[234:237], v[180:183], v[146:149]
	v_mfma_f32_16x16x32_bf16 v[150:153], v[234:237], v[184:187], v[150:153]
	v_mfma_f32_16x16x32_bf16 v[154:157], v[234:237], v[188:191], v[154:157]
	v_mfma_f32_16x16x32_bf16 v[158:161], v[234:237], v[192:195], v[158:161]
	s_add_i32 s4, s43, 1
	s_cmp_lg_u32 s43, 2
	s_cselect_b32 s43, s4, 0
	s_add_u32 s12, s12, 64
	s_addc_u32 s13, s13, 0
	s_cmpk_eq_i32 s12, 0x780
	s_cbranch_scc0 .LBB0_167
	s_waitcnt vmcnt(6)
	v_mov_b32_e32 v162, v23
	v_mov_b32_e32 v163, v24
	v_mov_b32_e32 v23, v25
	v_mov_b32_e32 v164, v7
	v_mov_b32_e32 v165, v8
	v_pk_add_f32 v[22:23], v[162:163], v[22:23]
	v_mov_b32_e32 v7, v9
	v_pk_add_f32 v[6:7], v[164:165], v[6:7]
	v_add_f32_e32 v0, v22, v23
	v_add_f32_e32 v0, v0, v6
	v_add_f32_e32 v0, v0, v7
	v_fmamk_f32 v0, v0, 0x3a800000, v250
	s_mov_b32 s4, 0x800000
	s_waitcnt vmcnt(4)
	v_mov_b32_e32 v166, v19
	v_mov_b32_e32 v167, v20
	v_mov_b32_e32 v168, v3
	v_mul_f32_e32 v3, 0x4b800000, v0
	v_cmp_gt_f32_e32 vcc, s4, v0
	v_mov_b32_e32 v19, v21
	v_mov_b32_e32 v169, v4
	v_cndmask_b32_e32 v0, v0, v3, vcc
	v_pk_add_f32 v[6:7], v[166:167], v[18:19]
	v_mov_b32_e32 v3, v5
	v_pk_add_f32 v[2:3], v[168:169], v[2:3]
	v_add_f32_e32 v4, v6, v7
	v_add_f32_e32 v2, v4, v2
	v_add_f32_e32 v2, v2, v3
	v_fmamk_f32 v2, v2, 0x3a800000, v250
	v_mul_f32_e32 v3, 0x4b800000, v2
	v_cmp_gt_f32_e64 s[40:41], s4, v2
	s_waitcnt vmcnt(2)
	v_mov_b32_e32 v170, v27
	v_mov_b32_e32 v171, v28
	v_cndmask_b32_e64 v2, v2, v3, s[40:41]
	v_mov_b32_e32 v27, v29
	v_mov_b32_e32 v172, v11
	v_mov_b32_e32 v173, v12
	v_rsq_f32_e32 v182, v2
	v_pk_add_f32 v[2:3], v[170:171], v[26:27]
	v_mov_b32_e32 v11, v13
	v_pk_add_f32 v[4:5], v[172:173], v[10:11]
	v_add_f32_e32 v2, v2, v3
	v_add_f32_e32 v2, v2, v4
	v_add_f32_e32 v2, v2, v5
	v_fmamk_f32 v2, v2, 0x3a800000, v250
	v_mul_f32_e32 v3, 0x4b800000, v2
	v_cmp_gt_f32_e64 s[42:43], s4, v2
	s_waitcnt vmcnt(0)
	v_mov_b32_e32 v174, v31
	v_mov_b32_e32 v175, v32
	v_cndmask_b32_e64 v2, v2, v3, s[42:43]
	v_mov_b32_e32 v31, v33
	v_mov_b32_e32 v180, v15
	v_mov_b32_e32 v181, v16
	v_rsq_f32_e32 v183, v2
	v_pk_add_f32 v[2:3], v[174:175], v[30:31]
	v_mov_b32_e32 v15, v17
	v_pk_add_f32 v[4:5], v[180:181], v[14:15]
	v_add_f32_e32 v2, v2, v3
	v_add_f32_e32 v2, v2, v4
	v_add_f32_e32 v2, v2, v5
	v_fmamk_f32 v2, v2, 0x3a800000, v250
	v_mul_f32_e32 v3, 0x4b800000, v2
	v_cmp_gt_f32_e64 s[44:45], s4, v2
	s_waitcnt vmcnt(6)
	v_add_u32_e32 v185, v178, v176
	s_waitcnt lgkmcnt(0)
	s_barrier
	v_cndmask_b32_e64 v2, v2, v3, s[44:45]
	v_rsq_f32_e32 v184, v2
	ds_read_b128 v[2:5], v185 offset:15360
	ds_read_b128 v[6:9], v185 offset:14336
	ds_read_b128 v[10:13], v185 offset:13312
	ds_read_b128 v[14:17], v185 offset:12288
	ds_read_b128 v[18:21], v185 offset:11264
	ds_read_b128 v[22:25], v185 offset:10240
	ds_read_b128 v[26:29], v185 offset:9216
	ds_read_b128 v[30:33], v185 offset:8192
	v_add3_u32 v186, s47, v177, v176
	ds_read_b128 v[162:165], v186 offset:3072
	ds_read_b128 v[166:169], v186 offset:2048
	ds_read_b128 v[170:173], v186 offset:1024
	ds_read_b128 v[174:177], v186
	v_rsq_f32_e32 v0, v0
	v_mul_f32_e32 v188, 0x45800000, v182
	v_mul_f32_e32 v189, 0x45800000, v183
	v_mul_f32_e32 v190, 0x45800000, v184
	v_mul_f32_e32 v187, 0x45800000, v0
	s_waitcnt lgkmcnt(0)
	v_mfma_f32_16x16x32_bf16 v[34:37], v[30:33], v[174:177], v[34:37]
	v_mfma_f32_16x16x32_bf16 v[38:41], v[30:33], v[170:173], v[38:41]
	v_mfma_f32_16x16x32_bf16 v[178:181], v[30:33], v[166:169], v[42:45]
	v_mfma_f32_16x16x32_bf16 v[30:33], v[30:33], v[162:165], v[46:49]
	v_mfma_f32_16x16x32_bf16 v[48:51], v[26:29], v[174:177], v[50:53]
	v_mfma_f32_16x16x32_bf16 v[52:55], v[26:29], v[170:173], v[54:57]
	v_mfma_f32_16x16x32_bf16 v[56:59], v[26:29], v[166:169], v[58:61]
	v_mfma_f32_16x16x32_bf16 v[26:29], v[26:29], v[162:165], v[62:65]
	v_mfma_f32_16x16x32_bf16 v[60:63], v[22:25], v[174:177], v[66:69]
	v_mfma_f32_16x16x32_bf16 v[64:67], v[22:25], v[170:173], v[70:73]
	v_mfma_f32_16x16x32_bf16 v[68:71], v[22:25], v[166:169], v[74:77]
	v_mfma_f32_16x16x32_bf16 v[22:25], v[22:25], v[162:165], v[78:81]
	v_mfma_f32_16x16x32_bf16 v[72:75], v[18:21], v[174:177], v[82:85]
	v_mfma_f32_16x16x32_bf16 v[76:79], v[18:21], v[170:173], v[86:89]
	v_mfma_f32_16x16x32_bf16 v[80:83], v[18:21], v[166:169], v[90:93]
	v_mfma_f32_16x16x32_bf16 v[18:21], v[18:21], v[162:165], v[94:97]
	v_mfma_f32_16x16x32_bf16 v[84:87], v[14:17], v[174:177], v[98:101]
	v_mfma_f32_16x16x32_bf16 v[88:91], v[14:17], v[170:173], v[102:105]
	v_mfma_f32_16x16x32_bf16 v[92:95], v[14:17], v[166:169], v[106:109]
	v_mfma_f32_16x16x32_bf16 v[14:17], v[14:17], v[162:165], v[110:113]
	v_mfma_f32_16x16x32_bf16 v[96:99], v[10:13], v[174:177], v[114:117]
	v_mfma_f32_16x16x32_bf16 v[100:103], v[10:13], v[170:173], v[118:121]
	v_mfma_f32_16x16x32_bf16 v[104:107], v[10:13], v[166:169], v[122:125]
	v_mfma_f32_16x16x32_bf16 v[10:13], v[10:13], v[162:165], v[126:129]
	v_mfma_f32_16x16x32_bf16 v[108:111], v[6:9], v[174:177], v[130:133]
	v_mfma_f32_16x16x32_bf16 v[112:115], v[6:9], v[170:173], v[134:137]
	v_mfma_f32_16x16x32_bf16 v[116:119], v[6:9], v[166:169], v[138:141]
	v_mfma_f32_16x16x32_bf16 v[120:123], v[2:5], v[174:177], v[146:149]
	v_mfma_f32_16x16x32_bf16 v[124:127], v[2:5], v[170:173], v[150:153]
	v_mfma_f32_16x16x32_bf16 v[128:131], v[2:5], v[166:169], v[154:157]
	v_mfma_f32_16x16x32_bf16 v[6:9], v[6:9], v[162:165], v[142:145]
	v_mfma_f32_16x16x32_bf16 v[2:5], v[2:5], v[162:165], v[158:161]
	s_waitcnt vmcnt(0)
	v_cndmask_b32_e32 v46, v0, v187, vcc
	v_cndmask_b32_e64 v44, v182, v188, s[40:41]
	v_cndmask_b32_e64 v42, v183, v189, s[42:43]
	v_cndmask_b32_e64 v0, v184, v190, s[44:45]
	s_waitcnt lgkmcnt(0)
	s_barrier
	ds_read_b128 v[132:135], v186 offset:24576
	ds_read_b128 v[136:139], v186 offset:25600
	ds_read_b128 v[140:143], v186 offset:26624
	ds_read_b128 v[144:147], v186 offset:27648
	ds_read_b128 v[148:151], v185 offset:32768
	ds_read_b128 v[152:155], v185 offset:33792
	ds_read_b128 v[156:159], v185 offset:34816
	ds_read_b128 v[160:163], v185 offset:35840
	ds_read_b128 v[164:167], v185 offset:36864
	ds_read_b128 v[168:171], v185 offset:37888
	ds_read_b128 v[172:175], v185 offset:38912
	ds_read_b128 v[182:185], v185 offset:39936
	s_waitcnt lgkmcnt(4)
	v_mfma_f32_16x16x32_bf16 v[242:245], v[160:163], v[140:143], v[80:83]
	v_mfma_f32_16x16x32_bf16 v[246:249], v[160:163], v[144:147], v[18:21]
	s_waitcnt lgkmcnt(3)
	v_mfma_f32_16x16x32_bf16 v[210:213], v[164:167], v[132:135], v[84:87]
	v_mfma_f32_16x16x32_bf16 v[194:197], v[164:167], v[136:139], v[88:91]
	v_mfma_f32_16x16x32_bf16 v[206:209], v[164:167], v[140:143], v[92:95]
	v_mfma_f32_16x16x32_bf16 v[164:167], v[164:167], v[144:147], v[14:17]
	v_mfma_f32_16x16x32_bf16 v[186:189], v[148:151], v[132:135], v[34:37]
	v_mfma_f32_16x16x32_bf16 v[190:193], v[148:151], v[136:139], v[38:41]
	v_mfma_f32_16x16x32_bf16 v[176:179], v[148:151], v[140:143], v[178:181]
	v_mfma_f32_16x16x32_bf16 v[198:201], v[148:151], v[144:147], v[30:33]
	v_mfma_f32_16x16x32_bf16 v[48:51], v[152:155], v[132:135], v[48:51]
	v_mfma_f32_16x16x32_bf16 v[52:55], v[152:155], v[136:139], v[52:55]
	v_mfma_f32_16x16x32_bf16 v[56:59], v[152:155], v[140:143], v[56:59]
	v_mfma_f32_16x16x32_bf16 v[202:205], v[152:155], v[144:147], v[26:29]
	v_mfma_f32_16x16x32_bf16 v[60:63], v[156:159], v[132:135], v[60:63]
	v_mfma_f32_16x16x32_bf16 v[216:219], v[156:159], v[136:139], v[64:67]
	v_mfma_f32_16x16x32_bf16 v[226:229], v[156:159], v[140:143], v[68:71]
	v_mfma_f32_16x16x32_bf16 v[230:233], v[156:159], v[144:147], v[22:25]
	v_mfma_f32_16x16x32_bf16 v[234:237], v[160:163], v[132:135], v[72:75]
	v_mfma_f32_16x16x32_bf16 v[238:241], v[160:163], v[136:139], v[76:79]
	s_waitcnt lgkmcnt(2)
	v_mfma_f32_16x16x32_bf16 v[150:153], v[168:171], v[132:135], v[96:99]
	v_mfma_f32_16x16x32_bf16 v[160:163], v[168:171], v[136:139], v[100:103]
	v_mfma_f32_16x16x32_bf16 v[38:41], v[168:171], v[140:143], v[104:107]
	v_mfma_f32_16x16x32_bf16 v[34:37], v[168:171], v[144:147], v[10:13]
	s_waitcnt lgkmcnt(1)
	v_mfma_f32_16x16x32_bf16 v[30:33], v[172:175], v[132:135], v[108:111]
	v_mfma_f32_16x16x32_bf16 v[26:29], v[172:175], v[136:139], v[112:115]
	v_mfma_f32_16x16x32_bf16 v[22:25], v[172:175], v[140:143], v[116:119]
	v_mfma_f32_16x16x32_bf16 v[18:21], v[172:175], v[144:147], v[6:9]
	s_waitcnt lgkmcnt(0)
	v_mfma_f32_16x16x32_bf16 v[14:17], v[182:185], v[132:135], v[120:123]
	v_mfma_f32_16x16x32_bf16 v[10:13], v[182:185], v[136:139], v[124:127]
	v_mfma_f32_16x16x32_bf16 v[6:9], v[182:185], v[140:143], v[128:131]
	v_mfma_f32_16x16x32_bf16 v[2:5], v[182:185], v[144:147], v[2:5]
	v_mov_b32_e32 v43, v224
	s_lshl_b32 s4, s46, 3
	v_lshrrev_b32_e32 v65, 1, v43
	v_lshlrev_b32_e32 v45, 3, v43
	v_and_b32_e32 v140, 24, v65
	v_ashrrev_i32_e32 v65, 4, v43
	v_and_b32_e32 v47, 56, v45
	v_add_u32_e32 v66, 0x7c, v65
	v_cmp_gt_i32_e32 vcc, 2, v65
	v_ashrrev_i32_e32 v142, 7, v43
	v_and_b32_e32 v64, 0x4f, v43
	v_cmp_gt_i32_e64 s[40:41], 64, v43
	v_cndmask_b32_e32 v66, v66, v65, vcc
	v_and_b32_e32 v67, 0x78, v45
	v_bfe_u32 v45, v45, 6, 1
	v_lshl_add_u32 v65, v65, 1, s4
	v_ashrrev_i32_e32 v43, 3, v43
	s_movk_i32 s4, 0xffe1
	v_pk_mul_f32 v[48:49], v[46:47], v[48:49] op_sel_hi:[0,1]
	v_or_b32_e32 v45, v65, v45
	v_cmp_lt_i32_e64 s[44:45], s4, v43
	s_movk_i32 s4, 0xffc1
	v_cvt_pk_bf16_f32 v74, v48, v49
	v_pk_mul_f32 v[48:49], v[46:47], v[50:51] op_sel_hi:[0,1]
	s_movk_i32 s5, 0x110
	v_add_u32_e32 v132, s15, v43
	v_cmp_lt_i32_e64 s[46:47], s4, v43
	s_movk_i32 s4, 0xffa1
	v_cvt_pk_bf16_f32 v75, v48, v49
	v_pk_mul_f32 v[48:49], v[44:45], v[52:53] op_sel_hi:[0,1]
	v_mul_u32_u24_e32 v141, 0x110, v64
	v_cmp_lt_i32_e64 s[42:43], 1, v43
	v_mul_lo_u32 v64, v43, s5
	v_cmp_lt_i32_e64 s[48:49], s4, v43
	v_add_u32_e32 v43, 0x60, v132
	v_cvt_pk_bf16_f32 v76, v48, v49
	v_pk_mul_f32 v[48:49], v[44:45], v[54:55] op_sel_hi:[0,1]
	v_cvt_pk_bf16_f32 v77, v48, v49
	v_pk_mul_f32 v[48:49], v[42:43], v[56:57] op_sel_hi:[0,1]
	v_cvt_pk_bf16_f32 v78, v48, v49
	v_pk_mul_f32 v[48:49], v[42:43], v[58:59] op_sel_hi:[0,1]
	v_cvt_pk_bf16_f32 v79, v48, v49
	v_pk_mul_f32 v[48:49], v[0:1], v[202:203] op_sel_hi:[0,1]
	v_cvt_pk_bf16_f32 v80, v48, v49
	v_pk_mul_f32 v[48:49], v[0:1], v[204:205] op_sel_hi:[0,1]
	v_cvt_pk_bf16_f32 v81, v48, v49
	v_pk_mul_f32 v[48:49], v[46:47], v[60:61] op_sel_hi:[0,1]
	v_cvt_pk_bf16_f32 v82, v48, v49
	v_pk_mul_f32 v[48:49], v[46:47], v[62:63] op_sel_hi:[0,1]
	v_cvt_pk_bf16_f32 v83, v48, v49
	v_pk_mul_f32 v[48:49], v[44:45], v[216:217] op_sel_hi:[0,1]
	v_cvt_pk_bf16_f32 v84, v48, v49
	v_pk_mul_f32 v[48:49], v[44:45], v[218:219] op_sel_hi:[0,1]
	v_cvt_pk_bf16_f32 v85, v48, v49
	v_pk_mul_f32 v[48:49], v[42:43], v[226:227] op_sel_hi:[0,1]
	v_cvt_pk_bf16_f32 v86, v48, v49
	v_pk_mul_f32 v[48:49], v[42:43], v[228:229] op_sel_hi:[0,1]
	v_cvt_pk_bf16_f32 v87, v48, v49
	v_pk_mul_f32 v[48:49], v[0:1], v[230:231] op_sel_hi:[0,1]
	v_cvt_pk_bf16_f32 v88, v48, v49
	v_pk_mul_f32 v[48:49], v[0:1], v[232:233] op_sel_hi:[0,1]
	v_cvt_pk_bf16_f32 v89, v48, v49
	v_pk_mul_f32 v[48:49], v[46:47], v[234:235] op_sel_hi:[0,1]
	v_cvt_pk_bf16_f32 v90, v48, v49
	v_pk_mul_f32 v[48:49], v[46:47], v[236:237] op_sel_hi:[0,1]
	v_cvt_pk_bf16_f32 v91, v48, v49
	v_pk_mul_f32 v[48:49], v[44:45], v[238:239] op_sel_hi:[0,1]
	v_cvt_pk_bf16_f32 v92, v48, v49
	v_pk_mul_f32 v[48:49], v[44:45], v[240:241] op_sel_hi:[0,1]
	v_cvt_pk_bf16_f32 v93, v48, v49
	v_pk_mul_f32 v[48:49], v[42:43], v[242:243] op_sel_hi:[0,1]
	v_cvt_pk_bf16_f32 v94, v48, v49
	v_pk_mul_f32 v[48:49], v[42:43], v[244:245] op_sel_hi:[0,1]
	v_cvt_pk_bf16_f32 v95, v48, v49
	v_pk_mul_f32 v[48:49], v[0:1], v[246:247] op_sel_hi:[0,1]
	v_cvt_pk_bf16_f32 v96, v48, v49
	v_pk_mul_f32 v[48:49], v[0:1], v[248:249] op_sel_hi:[0,1]
	v_cvt_pk_bf16_f32 v97, v48, v49
	v_pk_mul_f32 v[48:49], v[46:47], v[210:211] op_sel_hi:[0,1]
	v_cvt_pk_bf16_f32 v98, v48, v49
	v_pk_mul_f32 v[48:49], v[46:47], v[212:213] op_sel_hi:[0,1]
	v_cvt_pk_bf16_f32 v99, v48, v49
	v_pk_mul_f32 v[48:49], v[44:45], v[194:195] op_sel_hi:[0,1]
	v_cvt_pk_bf16_f32 v100, v48, v49
	v_pk_mul_f32 v[48:49], v[44:45], v[196:197] op_sel_hi:[0,1]
	v_mul_lo_u32 v66, v66, s5
	v_lshl_add_u32 v144, v47, 1, v64
	v_pk_mul_f32 v[64:65], v[46:47], v[186:187] op_sel_hi:[0,1]
	v_cvt_pk_bf16_f32 v101, v48, v49
	v_pk_mul_f32 v[48:49], v[42:43], v[206:207] op_sel_hi:[0,1]
	v_lshl_add_u32 v143, v67, 1, v66
	v_cvt_pk_bf16_f32 v66, v64, v65
	v_pk_mul_f32 v[64:65], v[46:47], v[188:189] op_sel_hi:[0,1]
	v_cvt_pk_bf16_f32 v102, v48, v49
	v_pk_mul_f32 v[48:49], v[42:43], v[208:209] op_sel_hi:[0,1]
	v_cvt_pk_bf16_f32 v67, v64, v65
	v_pk_mul_f32 v[64:65], v[44:45], v[190:191] op_sel_hi:[0,1]
	v_cvt_pk_bf16_f32 v103, v48, v49
	v_pk_mul_f32 v[48:49], v[0:1], v[164:165] op_sel_hi:[0,1]
	v_cvt_pk_bf16_f32 v68, v64, v65
	v_pk_mul_f32 v[64:65], v[44:45], v[192:193] op_sel_hi:[0,1]
	v_cvt_pk_bf16_f32 v104, v48, v49
	v_pk_mul_f32 v[48:49], v[0:1], v[166:167] op_sel_hi:[0,1]
	v_pk_mul_f32 v[2:3], v[0:1], v[2:3] op_sel_hi:[0,1]
	v_cvt_pk_bf16_f32 v69, v64, v65
	v_pk_mul_f32 v[64:65], v[42:43], v[176:177] op_sel_hi:[0,1]
	v_cvt_pk_bf16_f32 v105, v48, v49
	v_pk_mul_f32 v[48:49], v[46:47], v[150:151] op_sel_hi:[0,1]
	v_cvt_pk_bf16_f32 v128, v2, v3
	v_pk_mul_f32 v[2:3], v[0:1], v[4:5] op_sel_hi:[0,1]
	v_cvt_pk_bf16_f32 v70, v64, v65
	v_pk_mul_f32 v[64:65], v[42:43], v[178:179] op_sel_hi:[0,1]
	v_cvt_pk_bf16_f32 v106, v48, v49
	v_pk_mul_f32 v[48:49], v[46:47], v[152:153] op_sel_hi:[0,1]
	v_cvt_pk_bf16_f32 v129, v2, v3
	v_mov_b64_e32 v[2:3], s[54:55]
	v_add_u32_e32 v134, 32, v132
	v_add_u32_e32 v136, 64, v132
	v_cvt_pk_bf16_f32 v71, v64, v65
	v_pk_mul_f32 v[64:65], v[0:1], v[198:199] op_sel_hi:[0,1]
	v_cvt_pk_bf16_f32 v107, v48, v49
	v_pk_mul_f32 v[48:49], v[44:45], v[160:161] op_sel_hi:[0,1]
	v_pk_mul_f32 v[38:39], v[42:43], v[38:39] op_sel_hi:[0,1]
	v_pk_mul_f32 v[34:35], v[0:1], v[34:35] op_sel_hi:[0,1]
	v_pk_mul_f32 v[30:31], v[46:47], v[30:31] op_sel_hi:[0,1]
	v_pk_mul_f32 v[26:27], v[44:45], v[26:27] op_sel_hi:[0,1]
	v_pk_mul_f32 v[22:23], v[42:43], v[22:23] op_sel_hi:[0,1]
	v_pk_mul_f32 v[18:19], v[0:1], v[18:19] op_sel_hi:[0,1]
	v_pk_mul_f32 v[14:15], v[46:47], v[14:15] op_sel_hi:[0,1]
	v_pk_mul_f32 v[10:11], v[44:45], v[10:11] op_sel_hi:[0,1]
	v_pk_mul_f32 v[6:7], v[42:43], v[6:7] op_sel_hi:[0,1]
	v_mad_i64_i32 v[130:131], s[4:5], v45, s19, v[2:3]
	v_mov_b64_e32 v[2:3], s[52:53]
	v_cvt_pk_bf16_f32 v72, v64, v65
	v_pk_mul_f32 v[64:65], v[0:1], v[200:201] op_sel_hi:[0,1]
	v_cvt_pk_bf16_f32 v108, v48, v49
	v_pk_mul_f32 v[48:49], v[44:45], v[162:163] op_sel_hi:[0,1]
	v_cvt_pk_bf16_f32 v110, v38, v39
	v_pk_mul_f32 v[38:39], v[42:43], v[40:41] op_sel_hi:[0,1]
	v_cvt_pk_bf16_f32 v112, v34, v35
	v_pk_mul_f32 v[34:35], v[0:1], v[36:37] op_sel_hi:[0,1]
	v_cvt_pk_bf16_f32 v114, v30, v31
	v_pk_mul_f32 v[30:31], v[46:47], v[32:33] op_sel_hi:[0,1]
	v_cvt_pk_bf16_f32 v116, v26, v27
	v_pk_mul_f32 v[26:27], v[44:45], v[28:29] op_sel_hi:[0,1]
	v_cvt_pk_bf16_f32 v118, v22, v23
	v_pk_mul_f32 v[22:23], v[42:43], v[24:25] op_sel_hi:[0,1]
	v_cvt_pk_bf16_f32 v120, v18, v19
	v_pk_mul_f32 v[18:19], v[0:1], v[20:21] op_sel_hi:[0,1]
	v_cvt_pk_bf16_f32 v122, v14, v15
	v_pk_mul_f32 v[14:15], v[46:47], v[16:17] op_sel_hi:[0,1]
	v_cvt_pk_bf16_f32 v124, v10, v11
	v_pk_mul_f32 v[10:11], v[44:45], v[12:13] op_sel_hi:[0,1]
	v_cvt_pk_bf16_f32 v126, v6, v7
	v_pk_mul_f32 v[6:7], v[42:43], v[8:9] op_sel_hi:[0,1]
	v_mad_i64_i32 v[132:133], s[4:5], v132, s19, v[2:3]
	v_mad_i64_i32 v[134:135], s[4:5], v134, s19, v[2:3]
	v_mad_i64_i32 v[136:137], s[4:5], v136, s19, v[2:3]
	v_mad_i64_i32 v[138:139], s[4:5], v43, s19, v[2:3]
	v_add_u32_e32 v145, 0xfffffef0, v144
	v_add_u32_e32 v146, 0xffffff70, v144
	v_add_u32_e32 v147, 0xfffffde0, v144
	v_add_u32_e32 v148, 0xfffffe60, v144
	v_add_u32_e32 v149, 0x2200, v144
	v_add_u32_e32 v168, 0x20f0, v144
	v_add_u32_e32 v169, 0x2170, v144
	v_add_u32_e32 v170, 0x1fe0, v144
	v_add_u32_e32 v171, 0x2060, v144
	v_add_u32_e32 v154, 0x4400, v144
	v_add_u32_e32 v155, 0x42f0, v144
	v_add_u32_e32 v156, 0x4370, v144
	v_add_u32_e32 v157, 0x41e0, v144
	v_add_u32_e32 v158, 0x4260, v144
	v_add_u32_e32 v159, 0x6600, v144
	v_add_u32_e32 v172, 0x64f0, v144
	v_add_u32_e32 v173, 0x6570, v144
	v_add_u32_e32 v174, 0x63e0, v144
	v_add_u32_e32 v175, 0x6460, v144
	v_cvt_pk_bf16_f32 v73, v64, v65
	v_cvt_pk_bf16_f32 v109, v48, v49
	v_cvt_pk_bf16_f32 v111, v38, v39
	v_cvt_pk_bf16_f32 v113, v34, v35
	v_cvt_pk_bf16_f32 v115, v30, v31
	v_cvt_pk_bf16_f32 v117, v26, v27
	v_cvt_pk_bf16_f32 v119, v22, v23
	v_cvt_pk_bf16_f32 v121, v18, v19
	v_cvt_pk_bf16_f32 v123, v14, v15
	v_cvt_pk_bf16_f32 v125, v10, v11
	v_cvt_pk_bf16_f32 v127, v6, v7
	v_lshl_or_b32 v0, s14, 7, v47
	s_mov_b32 s4, 0
	s_mov_b64 s[12:13], -1
	v_add_u32_e32 v164, v140, v141
	v_xor_b32_e32 v246, 32, v225
	v_xor_b32_e32 v247, 16, v225
	v_xor_b32_e32 v248, 8, v225
	v_xor_b32_e32 v249, 4, v225
	v_mov_b32_e32 v243, v221
	s_branch .LBB0_171

.LBB0_194:
	s_mul_i32 s48, s13, 0x6000
	s_add_i32 s49, s48, 0xffffa000
	s_cmp_gt_i32 s13, 0
	s_waitcnt vmcnt(6)
	s_cselect_b32 s49, s49, 0xc000
	s_waitcnt lgkmcnt(0)
	s_barrier
	s_setprio 2
	v_or_b32_e32 v0, s48, v146
	v_add_u32_e32 v0, v0, v144
	v_add3_u32 v212, s48, v145, v144
	ds_read_b128 v[164:167], v212 offset:8192
	ds_read_b128 v[148:151], v0
	ds_read_b128 v[152:155], v0 offset:1024
	ds_read_b128 v[156:159], v0 offset:2048
	ds_read_b128 v[160:163], v0 offset:3072
	ds_read_b128 v[168:171], v212 offset:9216
	ds_read_b128 v[172:175], v212 offset:10240
	ds_read_b128 v[176:179], v212 offset:11264
	ds_read_b128 v[180:183], v212 offset:12288
	ds_read_b128 v[184:187], v212 offset:13312
	ds_read_b128 v[188:191], v212 offset:14336
	ds_read_b128 v[198:201], v212 offset:15360
	v_lshl_add_u64 v[212:213], v[142:143], 0, s[40:41]
	v_lshl_add_u64 v[212:213], v[130:131], 1, v[212:213]
	s_add_i32 s69, s49, s47
	s_mov_b32 m0, s69
	s_nop 0
	global_load_lds_dwordx4 v[212:213], off
	v_lshl_add_u64 v[212:213], v[142:143], 0, s[40:41]
	v_lshl_add_u64 v[212:213], v[132:133], 1, v[212:213]
	s_add_i32 s69, s49, s14
	s_mov_b32 m0, s69
	s_nop 0
	global_load_lds_dwordx4 v[212:213], off
	s_add_i32 s49, s15, s49
	v_lshl_add_u64 v[212:213], v[140:141], 0, s[40:41]
	s_mov_b32 m0, s49
	s_nop 0
	global_load_lds_dwordx4 v[212:213], off
	v_lshl_add_u64 v[212:213], v[138:139], 0, s[40:41]
	s_add_i32 s69, s49, 0x400
	s_mov_b32 m0, s69
	s_nop 0
	global_load_lds_dwordx4 v[212:213], off
	v_lshl_add_u64 v[212:213], v[136:137], 0, s[40:41]
	s_add_i32 s69, s49, 0x800
	s_mov_b32 m0, s69
	s_nop 0
	global_load_lds_dwordx4 v[212:213], off
	v_lshl_add_u64 v[212:213], v[134:135], 0, s[40:41]
	s_addk_i32 s49, 0xc00
	s_mov_b32 m0, s49
	s_nop 0
	global_load_lds_dwordx4 v[212:213], off
	s_setprio 0
	s_waitcnt lgkmcnt(10)
	v_mfma_f32_16x16x32_bf16 v[126:129], v[164:167], v[148:151], v[126:129]
	s_waitcnt lgkmcnt(9)
	v_mfma_f32_16x16x32_bf16 v[122:125], v[164:167], v[152:155], v[122:125]
	s_waitcnt lgkmcnt(8)
	v_mfma_f32_16x16x32_bf16 v[118:121], v[164:167], v[156:159], v[118:121]
	s_waitcnt lgkmcnt(7)
	v_mfma_f32_16x16x32_bf16 v[114:117], v[164:167], v[160:163], v[114:117]
	s_waitcnt lgkmcnt(6)
	v_mfma_f32_16x16x32_bf16 v[110:113], v[168:171], v[148:151], v[110:113]
	v_mfma_f32_16x16x32_bf16 v[106:109], v[168:171], v[152:155], v[106:109]
	v_mfma_f32_16x16x32_bf16 v[102:105], v[168:171], v[156:159], v[102:105]
	v_mfma_f32_16x16x32_bf16 v[98:101], v[168:171], v[160:163], v[98:101]
	s_waitcnt lgkmcnt(5)
	v_mfma_f32_16x16x32_bf16 v[94:97], v[172:175], v[148:151], v[94:97]
	v_mfma_f32_16x16x32_bf16 v[90:93], v[172:175], v[152:155], v[90:93]
	v_mfma_f32_16x16x32_bf16 v[86:89], v[172:175], v[156:159], v[86:89]
	v_mfma_f32_16x16x32_bf16 v[82:85], v[172:175], v[160:163], v[82:85]
	s_waitcnt lgkmcnt(4)
	v_mfma_f32_16x16x32_bf16 v[78:81], v[176:179], v[148:151], v[78:81]
	v_mfma_f32_16x16x32_bf16 v[74:77], v[176:179], v[152:155], v[74:77]
	v_mfma_f32_16x16x32_bf16 v[70:73], v[176:179], v[156:159], v[70:73]
	v_mfma_f32_16x16x32_bf16 v[66:69], v[176:179], v[160:163], v[66:69]
	s_waitcnt lgkmcnt(3)
	v_mfma_f32_16x16x32_bf16 v[62:65], v[180:183], v[148:151], v[62:65]
	v_mfma_f32_16x16x32_bf16 v[58:61], v[180:183], v[152:155], v[58:61]
	v_mfma_f32_16x16x32_bf16 v[54:57], v[180:183], v[156:159], v[54:57]
	v_mfma_f32_16x16x32_bf16 v[50:53], v[180:183], v[160:163], v[50:53]
	s_waitcnt lgkmcnt(2)
	v_mfma_f32_16x16x32_bf16 v[46:49], v[184:187], v[148:151], v[46:49]
	v_mfma_f32_16x16x32_bf16 v[42:45], v[184:187], v[152:155], v[42:45]
	v_mfma_f32_16x16x32_bf16 v[38:41], v[184:187], v[156:159], v[38:41]
	v_mfma_f32_16x16x32_bf16 v[34:37], v[184:187], v[160:163], v[34:37]
	s_waitcnt lgkmcnt(1)
	v_mfma_f32_16x16x32_bf16 v[30:33], v[188:191], v[148:151], v[30:33]
	v_mfma_f32_16x16x32_bf16 v[26:29], v[188:191], v[152:155], v[26:29]
	v_mfma_f32_16x16x32_bf16 v[22:25], v[188:191], v[156:159], v[22:25]
	v_mfma_f32_16x16x32_bf16 v[18:21], v[188:191], v[160:163], v[18:21]
	s_waitcnt lgkmcnt(0)
	v_mfma_f32_16x16x32_bf16 v[14:17], v[198:201], v[148:151], v[14:17]
	v_mfma_f32_16x16x32_bf16 v[10:13], v[198:201], v[152:155], v[10:13]
	v_mfma_f32_16x16x32_bf16 v[6:9], v[198:201], v[156:159], v[6:9]
	v_mfma_f32_16x16x32_bf16 v[2:5], v[198:201], v[160:163], v[2:5]
	s_add_i32 s48, s13, 1
	s_cmp_lg_u32 s13, 2
	s_cselect_b32 s13, s48, 0
	s_add_u32 s40, s40, 64
	s_addc_u32 s41, s41, 0
	s_cmpk_eq_i32 s40, 0x780
	s_cbranch_scc0 .LBB0_194
	s_waitcnt vmcnt(6)
	v_add_u32_e32 v0, v146, v144
	v_add_u32_e32 v194, v145, v144
	s_waitcnt lgkmcnt(0)
	s_barrier
	ds_read_b128 v[130:133], v0
	ds_read_b128 v[134:137], v0 offset:1024
	ds_read_b128 v[138:141], v0 offset:2048
	ds_read_b128 v[146:149], v0 offset:3072
	ds_read_b128 v[142:145], v194 offset:8192
	ds_read_b128 v[150:153], v194 offset:9216
	ds_read_b128 v[154:157], v194 offset:10240
	ds_read_b128 v[158:161], v194 offset:11264
	ds_read_b128 v[162:165], v194 offset:12288
	ds_read_b128 v[166:169], v194 offset:13312
	ds_read_b128 v[170:173], v194 offset:14336
	ds_read_b128 v[174:177], v194 offset:15360
	s_waitcnt lgkmcnt(7)
	v_mfma_f32_16x16x32_bf16 v[126:129], v[142:145], v[130:133], v[126:129]
	v_mfma_f32_16x16x32_bf16 v[122:125], v[142:145], v[134:137], v[122:125]
	v_mfma_f32_16x16x32_bf16 v[118:121], v[142:145], v[138:141], v[118:121]
	v_mfma_f32_16x16x32_bf16 v[114:117], v[142:145], v[146:149], v[114:117]
	s_waitcnt lgkmcnt(6)
	v_mfma_f32_16x16x32_bf16 v[110:113], v[150:153], v[130:133], v[110:113]
	v_mfma_f32_16x16x32_bf16 v[106:109], v[150:153], v[134:137], v[106:109]
	v_mfma_f32_16x16x32_bf16 v[102:105], v[150:153], v[138:141], v[102:105]
	v_mfma_f32_16x16x32_bf16 v[98:101], v[150:153], v[146:149], v[98:101]
	s_waitcnt lgkmcnt(5)
	v_mfma_f32_16x16x32_bf16 v[94:97], v[154:157], v[130:133], v[94:97]
	v_mfma_f32_16x16x32_bf16 v[90:93], v[154:157], v[134:137], v[90:93]
	v_mfma_f32_16x16x32_bf16 v[86:89], v[154:157], v[138:141], v[86:89]
	v_mfma_f32_16x16x32_bf16 v[82:85], v[154:157], v[146:149], v[82:85]
	s_waitcnt lgkmcnt(4)
	v_mfma_f32_16x16x32_bf16 v[78:81], v[158:161], v[130:133], v[78:81]
	v_mfma_f32_16x16x32_bf16 v[74:77], v[158:161], v[134:137], v[74:77]
	v_mfma_f32_16x16x32_bf16 v[70:73], v[158:161], v[138:141], v[70:73]
	v_mfma_f32_16x16x32_bf16 v[66:69], v[158:161], v[146:149], v[66:69]
	s_waitcnt lgkmcnt(3)
	v_mfma_f32_16x16x32_bf16 v[142:145], v[162:165], v[130:133], v[62:65]
	v_mfma_f32_16x16x32_bf16 v[150:153], v[162:165], v[134:137], v[58:61]
	v_mfma_f32_16x16x32_bf16 v[154:157], v[162:165], v[138:141], v[54:57]
	v_mfma_f32_16x16x32_bf16 v[158:161], v[162:165], v[146:149], v[50:53]
	s_waitcnt lgkmcnt(2)
	v_mfma_f32_16x16x32_bf16 v[162:165], v[166:169], v[130:133], v[46:49]
	v_mfma_f32_16x16x32_bf16 v[178:181], v[166:169], v[134:137], v[42:45]
	v_mfma_f32_16x16x32_bf16 v[182:185], v[166:169], v[138:141], v[38:41]
	v_mfma_f32_16x16x32_bf16 v[166:169], v[166:169], v[146:149], v[34:37]
	s_waitcnt lgkmcnt(1)
	v_mfma_f32_16x16x32_bf16 v[186:189], v[170:173], v[130:133], v[30:33]
	v_mfma_f32_16x16x32_bf16 v[190:193], v[170:173], v[134:137], v[26:29]
	v_mfma_f32_16x16x32_bf16 v[198:201], v[170:173], v[138:141], v[22:25]
	v_mfma_f32_16x16x32_bf16 v[170:173], v[170:173], v[146:149], v[18:21]
	s_waitcnt lgkmcnt(0)
	v_mfma_f32_16x16x32_bf16 v[130:133], v[174:177], v[130:133], v[14:17]
	v_mfma_f32_16x16x32_bf16 v[134:137], v[174:177], v[134:137], v[10:13]
	v_mfma_f32_16x16x32_bf16 v[138:141], v[174:177], v[138:141], v[6:9]
	v_mfma_f32_16x16x32_bf16 v[146:149], v[174:177], v[146:149], v[2:5]
	s_waitcnt vmcnt(0)
	s_waitcnt lgkmcnt(0)
	s_barrier
	ds_read_b128 v[174:177], v0 offset:24576
	ds_read_b128 v[202:205], v0 offset:25600
	ds_read_b128 v[216:219], v0 offset:26624
	ds_read_b128 v[226:229], v0 offset:27648
	ds_read_b128 v[14:17], v194 offset:32768
	ds_read_b128 v[30:33], v194 offset:33792
	ds_read_b128 v[46:49], v194 offset:34816
	ds_read_b128 v[62:65], v194 offset:35840
	ds_read_b128 v[230:233], v194 offset:36864
	ds_read_b128 v[234:237], v194 offset:37888
	ds_read_b128 v[238:241], v194 offset:38912
	ds_read_b128 v[242:245], v194 offset:39936
	s_waitcnt lgkmcnt(7)
	v_mfma_f32_16x16x32_bf16 v[2:5], v[14:17], v[174:177], v[126:129]
	v_mfma_f32_16x16x32_bf16 v[6:9], v[14:17], v[202:205], v[122:125]
	v_mfma_f32_16x16x32_bf16 v[10:13], v[14:17], v[216:219], v[118:121]
	v_mfma_f32_16x16x32_bf16 v[14:17], v[14:17], v[226:229], v[114:117]
	s_waitcnt lgkmcnt(6)
	v_mfma_f32_16x16x32_bf16 v[18:21], v[30:33], v[174:177], v[110:113]
	v_mfma_f32_16x16x32_bf16 v[22:25], v[30:33], v[202:205], v[106:109]
	v_mfma_f32_16x16x32_bf16 v[26:29], v[30:33], v[216:219], v[102:105]
	v_mfma_f32_16x16x32_bf16 v[30:33], v[30:33], v[226:229], v[98:101]
	s_waitcnt lgkmcnt(5)
	v_mfma_f32_16x16x32_bf16 v[34:37], v[46:49], v[174:177], v[94:97]
	v_mfma_f32_16x16x32_bf16 v[38:41], v[46:49], v[202:205], v[90:93]
	v_mfma_f32_16x16x32_bf16 v[42:45], v[46:49], v[216:219], v[86:89]
	v_mfma_f32_16x16x32_bf16 v[46:49], v[46:49], v[226:229], v[82:85]
	s_waitcnt lgkmcnt(4)
	v_mfma_f32_16x16x32_bf16 v[50:53], v[62:65], v[174:177], v[78:81]
	v_mfma_f32_16x16x32_bf16 v[54:57], v[62:65], v[202:205], v[74:77]
	v_mfma_f32_16x16x32_bf16 v[58:61], v[62:65], v[216:219], v[70:73]
	v_mfma_f32_16x16x32_bf16 v[62:65], v[62:65], v[226:229], v[66:69]
	s_waitcnt lgkmcnt(3)
	v_mfma_f32_16x16x32_bf16 v[66:69], v[230:233], v[174:177], v[142:145]
	v_mfma_f32_16x16x32_bf16 v[70:73], v[230:233], v[202:205], v[150:153]
	v_mfma_f32_16x16x32_bf16 v[74:77], v[230:233], v[216:219], v[154:157]
	v_mfma_f32_16x16x32_bf16 v[78:81], v[230:233], v[226:229], v[158:161]
	s_waitcnt lgkmcnt(2)
	v_mfma_f32_16x16x32_bf16 v[82:85], v[234:237], v[174:177], v[162:165]
	v_mfma_f32_16x16x32_bf16 v[86:89], v[234:237], v[202:205], v[178:181]
	v_mfma_f32_16x16x32_bf16 v[90:93], v[234:237], v[216:219], v[182:185]
	v_mfma_f32_16x16x32_bf16 v[94:97], v[234:237], v[226:229], v[166:169]
	s_waitcnt lgkmcnt(1)
	v_mfma_f32_16x16x32_bf16 v[98:101], v[238:241], v[174:177], v[186:189]
	v_mfma_f32_16x16x32_bf16 v[102:105], v[238:241], v[202:205], v[190:193]
	v_mfma_f32_16x16x32_bf16 v[106:109], v[238:241], v[216:219], v[198:201]
	v_mfma_f32_16x16x32_bf16 v[110:113], v[238:241], v[226:229], v[170:173]
	s_waitcnt lgkmcnt(0)
	v_mfma_f32_16x16x32_bf16 v[114:117], v[242:245], v[174:177], v[130:133]
	v_mfma_f32_16x16x32_bf16 v[118:121], v[242:245], v[202:205], v[134:137]
	v_mfma_f32_16x16x32_bf16 v[122:125], v[242:245], v[216:219], v[138:141]
	v_mfma_f32_16x16x32_bf16 v[126:129], v[242:245], v[226:229], v[146:149]
	v_mov_b32_e32 v130, v224
	s_ashr_i32 s13, s12, 31
	v_and_b32_e32 v131, 31, v130
	v_ashrrev_i32_e32 v197, 7, v130
	v_ashrrev_i32_e32 v132, 5, v130
	v_lshlrev_b32_e32 v0, 2, v131
	s_lshl_b64 s[48:49], s[12:13], 11
	v_lshlrev_b32_e32 v164, 4, v131
	v_cmp_eq_u32_e64 s[40:41], 0, v131
	v_and_b32_e32 v131, 0x4f, v130
	v_and_b32_e32 v130, 48, v130
	s_movk_i32 s13, 0x210
	v_cmp_lt_i32_e32 vcc, v247, v214
	v_mad_u32_u24 v202, v131, s13, v130
	s_ashr_i32 s47, s46, 31
	v_cndmask_b32_e32 v130, v225, v247, vcc
	v_cmp_lt_i32_e32 vcc, v248, v214
	v_lshlrev_b32_e32 v203, 2, v130
	s_lshl_b32 s69, s57, 1
	v_cndmask_b32_e32 v130, v225, v248, vcc
	v_cmp_lt_i32_e32 vcc, v249, v214
	v_lshlrev_b32_e32 v204, 2, v130
	s_add_u32 s15, s53, s48
	v_cndmask_b32_e32 v130, v225, v249, vcc
	v_cmp_lt_i32_e32 vcc, v223, v214
	v_lshlrev_b32_e32 v205, 2, v130
	v_lshl_or_b32 v0, v132, 10, v0
	v_cndmask_b32_e32 v130, v225, v223, vcc
	v_cmp_lt_i32_e32 vcc, v252, v214
	v_lshlrev_b32_e32 v206, 2, v130
	v_mul_lo_u32 v165, v132, s13
	v_cndmask_b32_e32 v130, v225, v252, vcc
	v_lshlrev_b32_e32 v207, 2, v130
	v_add_u32_e32 v130, s12, v132
	v_ashrrev_i32_e32 v131, 31, v130
	v_lshlrev_b64 v[132:133], 5, v[130:131]
	v_add_u32_e32 v134, 8, v130
	v_add_u32_e32 v136, 16, v130
	v_add_u32_e32 v138, 24, v130
	v_add_u32_e32 v140, 32, v130
	v_add_u32_e32 v142, 40, v130
	v_add_u32_e32 v144, 48, v130
	v_add_u32_e32 v146, 56, v130
	v_add_u32_e32 v148, 64, v130
	v_add_u32_e32 v150, 0x48, v130
	v_add_u32_e32 v152, 0x50, v130
	v_add_u32_e32 v154, 0x58, v130
	v_add_u32_e32 v156, 0x60, v130
	v_add_u32_e32 v158, 0x68, v130
	v_add_u32_e32 v160, 0x70, v130
	v_add_u32_e32 v130, 0x78, v130
	s_addc_u32 s48, s54, s49
	s_lshl_b64 s[12:13], s[46:47], 1
	v_ashrrev_i32_e32 v135, 31, v134
	v_ashrrev_i32_e32 v137, 31, v136
	v_ashrrev_i32_e32 v139, 31, v138
	v_ashrrev_i32_e32 v141, 31, v140
	v_ashrrev_i32_e32 v143, 31, v142
	v_ashrrev_i32_e32 v145, 31, v144
	v_ashrrev_i32_e32 v147, 31, v146
	v_ashrrev_i32_e32 v149, 31, v148
	v_ashrrev_i32_e32 v151, 31, v150
	v_ashrrev_i32_e32 v153, 31, v152
	v_ashrrev_i32_e32 v155, 31, v154
	v_ashrrev_i32_e32 v157, 31, v156
	v_ashrrev_i32_e32 v159, 31, v158
	v_ashrrev_i32_e32 v161, 31, v160
	v_ashrrev_i32_e32 v131, 31, v130
	s_add_u32 s12, s15, s12
	v_lshlrev_b64 v[134:135], 5, v[134:135]
	v_lshlrev_b64 v[136:137], 5, v[136:137]
	v_lshlrev_b64 v[138:139], 5, v[138:139]
	v_lshlrev_b64 v[140:141], 5, v[140:141]
	v_lshlrev_b64 v[142:143], 5, v[142:143]
	v_lshlrev_b64 v[144:145], 5, v[144:145]
	v_lshlrev_b64 v[146:147], 5, v[146:147]
	v_lshlrev_b64 v[148:149], 5, v[148:149]
	v_lshlrev_b64 v[150:151], 5, v[150:151]
	v_lshlrev_b64 v[152:153], 5, v[152:153]
	v_lshlrev_b64 v[154:155], 5, v[154:155]
	v_lshlrev_b64 v[156:157], 5, v[156:157]
	v_lshlrev_b64 v[158:159], 5, v[158:159]
	v_lshlrev_b64 v[160:161], 5, v[160:161]
	v_lshlrev_b64 v[162:163], 5, v[130:131]
	s_addc_u32 s13, s48, s13
	s_mov_b32 s14, 0
	v_lshl_add_u64 v[130:131], v[0:1], 1, s[12:13]
	v_lshl_add_u64 v[132:133], s[42:43], 0, v[132:133]
	v_lshl_add_u64 v[134:135], s[42:43], 0, v[134:135]
	v_lshl_add_u64 v[136:137], s[42:43], 0, v[136:137]
	v_lshl_add_u64 v[138:139], s[42:43], 0, v[138:139]
	v_lshl_add_u64 v[140:141], s[42:43], 0, v[140:141]
	v_lshl_add_u64 v[142:143], s[42:43], 0, v[142:143]
	v_lshl_add_u64 v[144:145], s[42:43], 0, v[144:145]
	v_lshl_add_u64 v[146:147], s[42:43], 0, v[146:147]
	v_lshl_add_u64 v[148:149], s[42:43], 0, v[148:149]
	v_lshl_add_u64 v[150:151], s[42:43], 0, v[150:151]
	v_lshl_add_u64 v[152:153], s[42:43], 0, v[152:153]
	v_lshl_add_u64 v[154:155], s[42:43], 0, v[154:155]
	v_lshl_add_u64 v[156:157], s[42:43], 0, v[156:157]
	v_lshl_add_u64 v[158:159], s[42:43], 0, v[158:159]
	v_lshl_add_u64 v[160:161], s[42:43], 0, v[160:161]
	v_lshl_add_u64 v[162:163], s[42:43], 0, v[162:163]
	s_mov_b64 s[46:47], -1
	v_add_u32_e32 v0, v164, v165
	v_mov_b32_e32 v243, 0x7f800000
	s_branch .LBB0_197

.LBB0_643:
	s_mul_i32 s44, s43, 0x6000
	s_add_i32 s45, s44, 0xffffa000
	s_cmp_gt_i32 s43, 0
	s_waitcnt vmcnt(6)
	s_cselect_b32 s45, s45, 0xc000
	s_waitcnt lgkmcnt(0)
	s_barrier
	s_setprio 2
	v_add3_u32 v0, s44, v177, v176
	v_add_u32_e32 v0, s55, v0
	v_add3_u32 v212, s44, v178, v176
	ds_read_b128 v[202:205], v212 offset:8192
	ds_read_b128 v[180:183], v0
	ds_read_b128 v[184:187], v0 offset:1024
	ds_read_b128 v[188:191], v0 offset:2048
	ds_read_b128 v[198:201], v0 offset:3072
	ds_read_b128 v[234:237], v212 offset:9216
	ds_read_b128 v[238:241], v212 offset:10240
	ds_read_b128 v[242:245], v212 offset:11264
	ds_read_b128 v[246:249], v212 offset:12288
	ds_read_b128 v[226:229], v212 offset:13312
	ds_read_b128 v[216:219], v212 offset:14336
	ds_read_b128 v[230:233], v212 offset:15360
	v_lshl_add_u64 v[212:213], v[174:175], 0, s[12:13]
	v_lshl_add_u64 v[212:213], v[162:163], 1, v[212:213]
	s_add_i32 s68, s45, s42
	s_mov_b32 m0, s68
	s_nop 0
	global_load_lds_dwordx4 v[212:213], off
	v_lshl_add_u64 v[212:213], v[174:175], 0, s[12:13]
	v_lshl_add_u64 v[212:213], v[164:165], 1, v[212:213]
	s_add_i32 s68, s45, s40
	s_mov_b32 m0, s68
	s_nop 0
	global_load_lds_dwordx4 v[212:213], off
	s_add_i32 s45, s41, s45
	v_lshl_add_u64 v[212:213], v[172:173], 0, s[12:13]
	s_mov_b32 m0, s45
	s_nop 0
	global_load_lds_dwordx4 v[212:213], off
	v_lshl_add_u64 v[212:213], v[170:171], 0, s[12:13]
	s_add_i32 s68, s45, 0x400
	s_mov_b32 m0, s68
	s_nop 0
	global_load_lds_dwordx4 v[212:213], off
	v_lshl_add_u64 v[212:213], v[168:169], 0, s[12:13]
	s_add_i32 s68, s45, 0x800
	s_mov_b32 m0, s68
	s_nop 0
	global_load_lds_dwordx4 v[212:213], off
	s_addk_i32 s45, 0xc00
	v_lshl_add_u64 v[212:213], v[166:167], 0, s[12:13]
	s_mov_b32 m0, s45
	s_nop 0
	global_load_lds_dwordx4 v[212:213], off
	s_setprio 0
	s_waitcnt lgkmcnt(10)
	v_mfma_f32_16x16x32_bf16 v[34:37], v[202:205], v[180:183], v[34:37]
	s_waitcnt lgkmcnt(9)
	v_mfma_f32_16x16x32_bf16 v[38:41], v[202:205], v[184:187], v[38:41]
	s_waitcnt lgkmcnt(8)
	v_mfma_f32_16x16x32_bf16 v[42:45], v[202:205], v[188:191], v[42:45]
	s_waitcnt lgkmcnt(7)
	v_mfma_f32_16x16x32_bf16 v[46:49], v[202:205], v[198:201], v[46:49]
	s_waitcnt lgkmcnt(6)
	v_mfma_f32_16x16x32_bf16 v[50:53], v[234:237], v[180:183], v[50:53]
	v_mfma_f32_16x16x32_bf16 v[54:57], v[234:237], v[184:187], v[54:57]
	v_mfma_f32_16x16x32_bf16 v[58:61], v[234:237], v[188:191], v[58:61]
	v_mfma_f32_16x16x32_bf16 v[62:65], v[234:237], v[198:201], v[62:65]
	s_waitcnt lgkmcnt(5)
	v_mfma_f32_16x16x32_bf16 v[66:69], v[238:241], v[180:183], v[66:69]
	v_mfma_f32_16x16x32_bf16 v[70:73], v[238:241], v[184:187], v[70:73]
	v_mfma_f32_16x16x32_bf16 v[74:77], v[238:241], v[188:191], v[74:77]
	v_mfma_f32_16x16x32_bf16 v[78:81], v[238:241], v[198:201], v[78:81]
	s_waitcnt lgkmcnt(4)
	v_mfma_f32_16x16x32_bf16 v[82:85], v[242:245], v[180:183], v[82:85]
	v_mfma_f32_16x16x32_bf16 v[86:89], v[242:245], v[184:187], v[86:89]
	v_mfma_f32_16x16x32_bf16 v[90:93], v[242:245], v[188:191], v[90:93]
	v_mfma_f32_16x16x32_bf16 v[94:97], v[242:245], v[198:201], v[94:97]
	s_waitcnt lgkmcnt(3)
	v_mfma_f32_16x16x32_bf16 v[98:101], v[246:249], v[180:183], v[98:101]
	v_mfma_f32_16x16x32_bf16 v[102:105], v[246:249], v[184:187], v[102:105]
	v_mfma_f32_16x16x32_bf16 v[106:109], v[246:249], v[188:191], v[106:109]
	v_mfma_f32_16x16x32_bf16 v[110:113], v[246:249], v[198:201], v[110:113]
	s_waitcnt lgkmcnt(2)
	v_mfma_f32_16x16x32_bf16 v[114:117], v[226:229], v[180:183], v[114:117]
	v_mfma_f32_16x16x32_bf16 v[118:121], v[226:229], v[184:187], v[118:121]
	v_mfma_f32_16x16x32_bf16 v[122:125], v[226:229], v[188:191], v[122:125]
	v_mfma_f32_16x16x32_bf16 v[126:129], v[226:229], v[198:201], v[126:129]
	s_waitcnt lgkmcnt(1)
	v_mfma_f32_16x16x32_bf16 v[130:133], v[216:219], v[180:183], v[130:133]
	v_mfma_f32_16x16x32_bf16 v[134:137], v[216:219], v[184:187], v[134:137]
	v_mfma_f32_16x16x32_bf16 v[138:141], v[216:219], v[188:191], v[138:141]
	v_mfma_f32_16x16x32_bf16 v[142:145], v[216:219], v[198:201], v[142:145]
	s_waitcnt lgkmcnt(0)
	v_mfma_f32_16x16x32_bf16 v[146:149], v[230:233], v[180:183], v[146:149]
	v_mfma_f32_16x16x32_bf16 v[150:153], v[230:233], v[184:187], v[150:153]
	v_mfma_f32_16x16x32_bf16 v[154:157], v[230:233], v[188:191], v[154:157]
	v_mfma_f32_16x16x32_bf16 v[158:161], v[230:233], v[198:201], v[158:161]
	s_add_i32 s44, s43, 1
	s_cmp_lg_u32 s43, 2
	s_cselect_b32 s43, s44, 0
	s_add_u32 s12, s12, 64
	s_addc_u32 s13, s13, 0
	s_cmpk_eq_i32 s12, 0x780
	s_cbranch_scc0 .LBB0_643
	s_waitcnt vmcnt(6)
	v_mov_b32_e32 v162, v19
	v_mov_b32_e32 v163, v20
	v_mov_b32_e32 v19, v21
	v_mov_b32_e32 v164, v3
	v_mov_b32_e32 v165, v4
	v_pk_add_f32 v[18:19], v[162:163], v[18:19]
	v_mov_b32_e32 v3, v5
	v_pk_add_f32 v[2:3], v[164:165], v[2:3]
	v_add_f32_e32 v0, v18, v19
	v_add_f32_e32 v0, v0, v2
	v_add_f32_e32 v0, v0, v3
	v_fmamk_f32 v0, v0, 0x3a800000, v250
	s_waitcnt vmcnt(4)
	v_mov_b32_e32 v166, v23
	v_mov_b32_e32 v167, v24
	v_mul_f32_e32 v2, 0x4b800000, v0
	v_cmp_gt_f32_e32 vcc, s80, v0
	v_mov_b32_e32 v23, v25
	v_mov_b32_e32 v168, v7
	v_mov_b32_e32 v169, v8
	v_cndmask_b32_e32 v0, v0, v2, vcc
	v_pk_add_f32 v[2:3], v[166:167], v[22:23]
	v_mov_b32_e32 v7, v9
	v_pk_add_f32 v[4:5], v[168:169], v[6:7]
	v_add_f32_e32 v2, v2, v3
	v_add_f32_e32 v2, v2, v4
	v_add_f32_e32 v2, v2, v5
	v_fmamk_f32 v2, v2, 0x3a800000, v250
	v_mul_f32_e32 v3, 0x4b800000, v2
	v_cmp_gt_f32_e64 s[40:41], s80, v2
	s_waitcnt vmcnt(2)
	v_mov_b32_e32 v170, v27
	v_mov_b32_e32 v171, v28
	v_cndmask_b32_e64 v2, v2, v3, s[40:41]
	v_mov_b32_e32 v27, v29
	v_mov_b32_e32 v172, v11
	v_mov_b32_e32 v173, v12
	v_rsq_f32_e32 v179, v2
	v_pk_add_f32 v[2:3], v[170:171], v[26:27]
	v_mov_b32_e32 v11, v13
	v_pk_add_f32 v[4:5], v[172:173], v[10:11]
	v_add_f32_e32 v2, v2, v3
	v_add_f32_e32 v2, v2, v4
	v_add_f32_e32 v2, v2, v5
	v_fmamk_f32 v2, v2, 0x3a800000, v250
	v_mul_f32_e32 v3, 0x4b800000, v2
	v_cmp_gt_f32_e64 s[42:43], s80, v2
	s_waitcnt vmcnt(0)
	v_mov_b32_e32 v174, v31
	v_mov_b32_e32 v175, v32
	v_cndmask_b32_e64 v2, v2, v3, s[42:43]
	v_mov_b32_e32 v31, v33
	v_mov_b32_e32 v180, v15
	v_mov_b32_e32 v181, v16
	v_rsq_f32_e32 v182, v2
	v_pk_add_f32 v[2:3], v[174:175], v[30:31]
	v_mov_b32_e32 v15, v17
	v_pk_add_f32 v[4:5], v[180:181], v[14:15]
	v_add_f32_e32 v2, v2, v3
	v_add_f32_e32 v2, v2, v4
	v_add_f32_e32 v2, v2, v5
	v_fmamk_f32 v2, v2, 0x3a800000, v250
	v_mul_f32_e32 v3, 0x4b800000, v2
	v_cmp_gt_f32_e64 s[44:45], s80, v2
	s_waitcnt vmcnt(6)
	v_add_u32_e32 v183, v178, v176
	s_waitcnt lgkmcnt(0)
	s_barrier
	v_cndmask_b32_e64 v2, v2, v3, s[44:45]
	v_rsq_f32_e32 v180, v2
	ds_read_b128 v[2:5], v183 offset:15360
	ds_read_b128 v[6:9], v183 offset:14336
	ds_read_b128 v[10:13], v183 offset:13312
	ds_read_b128 v[14:17], v183 offset:12288
	ds_read_b128 v[18:21], v183 offset:11264
	ds_read_b128 v[22:25], v183 offset:10240
	ds_read_b128 v[26:29], v183 offset:9216
	ds_read_b128 v[30:33], v183 offset:8192
	v_add3_u32 v178, s55, v177, v176
	ds_read_b128 v[162:165], v178 offset:3072
	ds_read_b128 v[166:169], v178 offset:2048
	ds_read_b128 v[170:173], v178 offset:1024
	ds_read_b128 v[174:177], v178
	v_rsq_f32_e32 v0, v0
	v_mul_f32_e32 v184, 0x45800000, v179
	v_mul_f32_e32 v185, 0x45800000, v182
	v_mul_f32_e32 v186, 0x45800000, v180
	v_mul_f32_e32 v181, 0x45800000, v0
	s_waitcnt lgkmcnt(0)
	v_mfma_f32_16x16x32_bf16 v[34:37], v[30:33], v[174:177], v[34:37]
	v_mfma_f32_16x16x32_bf16 v[38:41], v[30:33], v[170:173], v[38:41]
	v_mfma_f32_16x16x32_bf16 v[42:45], v[30:33], v[166:169], v[42:45]
	v_mfma_f32_16x16x32_bf16 v[30:33], v[30:33], v[162:165], v[46:49]
	v_mfma_f32_16x16x32_bf16 v[46:49], v[26:29], v[174:177], v[50:53]
	v_mfma_f32_16x16x32_bf16 v[50:53], v[26:29], v[170:173], v[54:57]
	v_mfma_f32_16x16x32_bf16 v[54:57], v[26:29], v[166:169], v[58:61]
	v_mfma_f32_16x16x32_bf16 v[58:61], v[26:29], v[162:165], v[62:65]
	v_mfma_f32_16x16x32_bf16 v[62:65], v[22:25], v[174:177], v[66:69]
	v_mfma_f32_16x16x32_bf16 v[66:69], v[22:25], v[170:173], v[70:73]
	v_mfma_f32_16x16x32_bf16 v[70:73], v[22:25], v[166:169], v[74:77]
	v_mfma_f32_16x16x32_bf16 v[74:77], v[22:25], v[162:165], v[78:81]
	v_mfma_f32_16x16x32_bf16 v[78:81], v[18:21], v[174:177], v[82:85]
	v_mfma_f32_16x16x32_bf16 v[82:85], v[18:21], v[170:173], v[86:89]
	v_mfma_f32_16x16x32_bf16 v[86:89], v[18:21], v[166:169], v[90:93]
	v_mfma_f32_16x16x32_bf16 v[18:21], v[18:21], v[162:165], v[94:97]
	v_mfma_f32_16x16x32_bf16 v[90:93], v[14:17], v[174:177], v[98:101]
	v_mfma_f32_16x16x32_bf16 v[94:97], v[14:17], v[170:173], v[102:105]
	v_mfma_f32_16x16x32_bf16 v[98:101], v[14:17], v[166:169], v[106:109]
	v_mfma_f32_16x16x32_bf16 v[14:17], v[14:17], v[162:165], v[110:113]
	v_mfma_f32_16x16x32_bf16 v[102:105], v[10:13], v[174:177], v[114:117]
	v_mfma_f32_16x16x32_bf16 v[106:109], v[10:13], v[170:173], v[118:121]
	v_mfma_f32_16x16x32_bf16 v[110:113], v[10:13], v[166:169], v[122:125]
	v_mfma_f32_16x16x32_bf16 v[10:13], v[10:13], v[162:165], v[126:129]
	v_mfma_f32_16x16x32_bf16 v[114:117], v[6:9], v[174:177], v[130:133]
	v_mfma_f32_16x16x32_bf16 v[118:121], v[6:9], v[170:173], v[134:137]
	v_mfma_f32_16x16x32_bf16 v[122:125], v[6:9], v[166:169], v[138:141]
	v_mfma_f32_16x16x32_bf16 v[6:9], v[6:9], v[162:165], v[142:145]
	v_mfma_f32_16x16x32_bf16 v[126:129], v[2:5], v[174:177], v[146:149]
	v_mfma_f32_16x16x32_bf16 v[130:133], v[2:5], v[170:173], v[150:153]
	v_mfma_f32_16x16x32_bf16 v[134:137], v[2:5], v[166:169], v[154:157]
	v_mfma_f32_16x16x32_bf16 v[2:5], v[2:5], v[162:165], v[158:161]
	s_waitcnt vmcnt(0)
	v_cndmask_b32_e32 v26, v0, v181, vcc
	v_cndmask_b32_e64 v24, v179, v184, s[40:41]
	v_cndmask_b32_e64 v22, v182, v185, s[42:43]
	v_cndmask_b32_e64 v0, v180, v186, s[44:45]
	s_waitcnt lgkmcnt(0)
	s_barrier
	ds_read_b128 v[138:141], v178 offset:24576
	ds_read_b128 v[142:145], v178 offset:25600
	ds_read_b128 v[146:149], v178 offset:26624
	ds_read_b128 v[150:153], v178 offset:27648
	ds_read_b128 v[154:157], v183 offset:32768
	ds_read_b128 v[158:161], v183 offset:33792
	ds_read_b128 v[162:165], v183 offset:34816
	ds_read_b128 v[166:169], v183 offset:35840
	ds_read_b128 v[170:173], v183 offset:36864
	ds_read_b128 v[174:177], v183 offset:37888
	ds_read_b128 v[178:181], v183 offset:38912
	ds_read_b128 v[182:185], v183 offset:39936
	s_waitcnt lgkmcnt(7)
	v_mfma_f32_16x16x32_bf16 v[34:37], v[154:157], v[138:141], v[34:37]
	v_mfma_f32_16x16x32_bf16 v[38:41], v[154:157], v[142:145], v[38:41]
	v_mfma_f32_16x16x32_bf16 v[42:45], v[154:157], v[146:149], v[42:45]
	v_mfma_f32_16x16x32_bf16 v[28:31], v[154:157], v[150:153], v[30:33]
	s_waitcnt lgkmcnt(6)
	v_mfma_f32_16x16x32_bf16 v[46:49], v[158:161], v[138:141], v[46:49]
	v_mfma_f32_16x16x32_bf16 v[50:53], v[158:161], v[142:145], v[50:53]
	v_mfma_f32_16x16x32_bf16 v[54:57], v[158:161], v[146:149], v[54:57]
	v_mfma_f32_16x16x32_bf16 v[58:61], v[158:161], v[150:153], v[58:61]
	s_waitcnt lgkmcnt(5)
	v_mfma_f32_16x16x32_bf16 v[62:65], v[162:165], v[138:141], v[62:65]
	v_mfma_f32_16x16x32_bf16 v[66:69], v[162:165], v[142:145], v[66:69]
	v_mfma_f32_16x16x32_bf16 v[70:73], v[162:165], v[146:149], v[70:73]
	v_mfma_f32_16x16x32_bf16 v[74:77], v[162:165], v[150:153], v[74:77]
	s_waitcnt lgkmcnt(4)
	v_mfma_f32_16x16x32_bf16 v[78:81], v[166:169], v[138:141], v[78:81]
	v_mfma_f32_16x16x32_bf16 v[82:85], v[166:169], v[142:145], v[82:85]
	v_mfma_f32_16x16x32_bf16 v[86:89], v[166:169], v[146:149], v[86:89]
	v_mfma_f32_16x16x32_bf16 v[154:157], v[166:169], v[150:153], v[18:21]
	s_waitcnt lgkmcnt(3)
	v_mfma_f32_16x16x32_bf16 v[90:93], v[170:173], v[138:141], v[90:93]
	v_mfma_f32_16x16x32_bf16 v[94:97], v[170:173], v[142:145], v[94:97]
	v_mfma_f32_16x16x32_bf16 v[98:101], v[170:173], v[146:149], v[98:101]
	v_mfma_f32_16x16x32_bf16 v[158:161], v[170:173], v[150:153], v[14:17]
	s_waitcnt lgkmcnt(2)
	v_mfma_f32_16x16x32_bf16 v[102:105], v[174:177], v[138:141], v[102:105]
	v_mfma_f32_16x16x32_bf16 v[106:109], v[174:177], v[142:145], v[106:109]
	v_mfma_f32_16x16x32_bf16 v[110:113], v[174:177], v[146:149], v[110:113]
	v_mfma_f32_16x16x32_bf16 v[162:165], v[174:177], v[150:153], v[10:13]
	s_waitcnt lgkmcnt(1)
	v_mfma_f32_16x16x32_bf16 v[114:117], v[178:181], v[138:141], v[114:117]
	v_mfma_f32_16x16x32_bf16 v[118:121], v[178:181], v[142:145], v[118:121]
	v_mfma_f32_16x16x32_bf16 v[122:125], v[178:181], v[146:149], v[122:125]
	v_mfma_f32_16x16x32_bf16 v[18:21], v[178:181], v[150:153], v[6:9]
	s_waitcnt lgkmcnt(0)
	v_mfma_f32_16x16x32_bf16 v[14:17], v[182:185], v[138:141], v[126:129]
	v_mfma_f32_16x16x32_bf16 v[10:13], v[182:185], v[142:145], v[130:133]
	v_mfma_f32_16x16x32_bf16 v[6:9], v[182:185], v[146:149], v[134:137]
	v_mfma_f32_16x16x32_bf16 v[2:5], v[182:185], v[150:153], v[2:5]
	v_mov_b32_e32 v23, v224
	s_movk_i32 s12, 0x210
	v_lshrrev_b32_e32 v32, 1, v23
	v_and_b32_e32 v27, 0x7fffff80, v23
	v_and_b32_e32 v32, 24, v32
	v_and_b32_e32 v25, 0x4f, v23
	v_lshl_or_b32 v27, v27, 1, v32
	v_pk_mul_f32 v[32:33], v[26:27], v[34:35] op_sel_hi:[0,1]
	v_pk_mul_f32 v[34:35], v[26:27], v[36:37] op_sel_hi:[0,1]
	v_mad_u32_u24 v25, v25, s12, v27
	v_cvt_pk_bf16_f32 v32, v32, v33
	v_cvt_pk_bf16_f32 v33, v34, v35
	v_pk_mul_f32 v[34:35], v[24:25], v[38:39] op_sel_hi:[0,1]
	v_pk_mul_f32 v[36:37], v[24:25], v[40:41] op_sel_hi:[0,1]
	v_cvt_pk_bf16_f32 v34, v34, v35
	v_cvt_pk_bf16_f32 v35, v36, v37
	v_pk_mul_f32 v[36:37], v[22:23], v[42:43] op_sel_hi:[0,1]
	v_pk_mul_f32 v[38:39], v[22:23], v[44:45] op_sel_hi:[0,1]
	v_pk_mul_f32 v[28:29], v[0:1], v[28:29] op_sel_hi:[0,1]
	v_pk_mul_f32 v[30:31], v[0:1], v[30:31] op_sel_hi:[0,1]
	v_cvt_pk_bf16_f32 v36, v36, v37
	v_cvt_pk_bf16_f32 v37, v38, v39
	v_cvt_pk_bf16_f32 v28, v28, v29
	v_cvt_pk_bf16_f32 v29, v30, v31
	v_pk_mul_f32 v[30:31], v[26:27], v[46:47] op_sel_hi:[0,1]
	v_pk_mul_f32 v[38:39], v[26:27], v[48:49] op_sel_hi:[0,1]
	v_cvt_pk_bf16_f32 v30, v30, v31
	v_cvt_pk_bf16_f32 v31, v38, v39
	s_barrier
	ds_write2_b64 v25, v[32:33], v[30:31] offset1:4
	v_pk_mul_f32 v[30:31], v[24:25], v[50:51] op_sel_hi:[0,1]
	v_pk_mul_f32 v[32:33], v[24:25], v[52:53] op_sel_hi:[0,1]
	v_cvt_pk_bf16_f32 v30, v30, v31
	v_cvt_pk_bf16_f32 v31, v32, v33
	v_add_u32_e32 v27, 0x2000, v25
	ds_write2_b64 v27, v[34:35], v[30:31] offset0:32 offset1:36
	v_pk_mul_f32 v[30:31], v[22:23], v[54:55] op_sel_hi:[0,1]
	v_pk_mul_f32 v[32:33], v[22:23], v[56:57] op_sel_hi:[0,1]
	v_cvt_pk_bf16_f32 v30, v30, v31
	v_cvt_pk_bf16_f32 v31, v32, v33
	v_add_u32_e32 v40, 0x4000, v25
	ds_write2_b64 v40, v[36:37], v[30:31] offset0:64 offset1:68
	v_pk_mul_f32 v[30:31], v[0:1], v[58:59] op_sel_hi:[0,1]
	v_pk_mul_f32 v[32:33], v[0:1], v[60:61] op_sel_hi:[0,1]
	v_cvt_pk_bf16_f32 v30, v30, v31
	v_cvt_pk_bf16_f32 v31, v32, v33
	v_add_u32_e32 v41, 0x6000, v25
	ds_write2_b64 v41, v[28:29], v[30:31] offset0:96 offset1:100
	v_pk_mul_f32 v[28:29], v[26:27], v[62:63] op_sel_hi:[0,1]
	v_pk_mul_f32 v[30:31], v[26:27], v[64:65] op_sel_hi:[0,1]
	v_cvt_pk_bf16_f32 v28, v28, v29
	v_cvt_pk_bf16_f32 v29, v30, v31
	v_pk_mul_f32 v[30:31], v[24:25], v[66:67] op_sel_hi:[0,1]
	v_pk_mul_f32 v[32:33], v[24:25], v[68:69] op_sel_hi:[0,1]
	v_cvt_pk_bf16_f32 v30, v30, v31
	v_cvt_pk_bf16_f32 v31, v32, v33
	v_pk_mul_f32 v[32:33], v[22:23], v[70:71] op_sel_hi:[0,1]
	v_pk_mul_f32 v[34:35], v[22:23], v[72:73] op_sel_hi:[0,1]
	v_cvt_pk_bf16_f32 v32, v32, v33
	v_cvt_pk_bf16_f32 v33, v34, v35
	v_pk_mul_f32 v[34:35], v[0:1], v[74:75] op_sel_hi:[0,1]
	v_pk_mul_f32 v[36:37], v[0:1], v[76:77] op_sel_hi:[0,1]
	v_cvt_pk_bf16_f32 v34, v34, v35
	v_cvt_pk_bf16_f32 v35, v36, v37
	v_pk_mul_f32 v[36:37], v[26:27], v[78:79] op_sel_hi:[0,1]
	v_pk_mul_f32 v[38:39], v[26:27], v[80:81] op_sel_hi:[0,1]
	v_cvt_pk_bf16_f32 v36, v36, v37
	v_cvt_pk_bf16_f32 v37, v38, v39
	ds_write2_b64 v25, v[28:29], v[36:37] offset0:8 offset1:12
	v_pk_mul_f32 v[28:29], v[24:25], v[82:83] op_sel_hi:[0,1]
	v_pk_mul_f32 v[36:37], v[24:25], v[84:85] op_sel_hi:[0,1]
	v_cvt_pk_bf16_f32 v28, v28, v29
	v_cvt_pk_bf16_f32 v29, v36, v37
	ds_write2_b64 v27, v[30:31], v[28:29] offset0:40 offset1:44
	v_pk_mul_f32 v[28:29], v[22:23], v[86:87] op_sel_hi:[0,1]
	v_pk_mul_f32 v[30:31], v[22:23], v[88:89] op_sel_hi:[0,1]
	v_cvt_pk_bf16_f32 v28, v28, v29
	v_cvt_pk_bf16_f32 v29, v30, v31
	ds_write2_b64 v40, v[32:33], v[28:29] offset0:72 offset1:76
	v_pk_mul_f32 v[28:29], v[0:1], v[154:155] op_sel_hi:[0,1]
	v_pk_mul_f32 v[30:31], v[0:1], v[156:157] op_sel_hi:[0,1]
	v_cvt_pk_bf16_f32 v28, v28, v29
	v_cvt_pk_bf16_f32 v29, v30, v31
	ds_write2_b64 v41, v[34:35], v[28:29] offset0:104 offset1:108
	v_pk_mul_f32 v[28:29], v[26:27], v[90:91] op_sel_hi:[0,1]
	v_pk_mul_f32 v[30:31], v[26:27], v[92:93] op_sel_hi:[0,1]
	v_cvt_pk_bf16_f32 v28, v28, v29
	v_cvt_pk_bf16_f32 v29, v30, v31
	v_pk_mul_f32 v[30:31], v[24:25], v[94:95] op_sel_hi:[0,1]
	v_pk_mul_f32 v[32:33], v[24:25], v[96:97] op_sel_hi:[0,1]
	v_cvt_pk_bf16_f32 v30, v30, v31
	v_cvt_pk_bf16_f32 v31, v32, v33
	v_pk_mul_f32 v[32:33], v[22:23], v[98:99] op_sel_hi:[0,1]
	v_pk_mul_f32 v[34:35], v[22:23], v[100:101] op_sel_hi:[0,1]
	v_cvt_pk_bf16_f32 v32, v32, v33
	v_cvt_pk_bf16_f32 v33, v34, v35
	v_pk_mul_f32 v[34:35], v[0:1], v[158:159] op_sel_hi:[0,1]
	v_pk_mul_f32 v[36:37], v[0:1], v[160:161] op_sel_hi:[0,1]
	v_cvt_pk_bf16_f32 v34, v34, v35
	v_cvt_pk_bf16_f32 v35, v36, v37
	v_pk_mul_f32 v[36:37], v[26:27], v[102:103] op_sel_hi:[0,1]
	v_pk_mul_f32 v[38:39], v[26:27], v[104:105] op_sel_hi:[0,1]
	v_cvt_pk_bf16_f32 v36, v36, v37
	v_cvt_pk_bf16_f32 v37, v38, v39
	ds_write2_b64 v25, v[28:29], v[36:37] offset0:16 offset1:20
	v_pk_mul_f32 v[28:29], v[24:25], v[106:107] op_sel_hi:[0,1]
	v_pk_mul_f32 v[36:37], v[24:25], v[108:109] op_sel_hi:[0,1]
	v_cvt_pk_bf16_f32 v28, v28, v29
	v_cvt_pk_bf16_f32 v29, v36, v37
	ds_write2_b64 v27, v[30:31], v[28:29] offset0:48 offset1:52
	v_pk_mul_f32 v[28:29], v[22:23], v[110:111] op_sel_hi:[0,1]
	v_pk_mul_f32 v[30:31], v[22:23], v[112:113] op_sel_hi:[0,1]
	v_cvt_pk_bf16_f32 v28, v28, v29
	v_cvt_pk_bf16_f32 v29, v30, v31
	ds_write2_b64 v40, v[32:33], v[28:29] offset0:80 offset1:84
	v_pk_mul_f32 v[28:29], v[0:1], v[162:163] op_sel_hi:[0,1]
	v_pk_mul_f32 v[30:31], v[0:1], v[164:165] op_sel_hi:[0,1]
	v_cvt_pk_bf16_f32 v28, v28, v29
	v_cvt_pk_bf16_f32 v29, v30, v31
	ds_write2_b64 v41, v[34:35], v[28:29] offset0:112 offset1:116
	v_pk_mul_f32 v[28:29], v[26:27], v[114:115] op_sel_hi:[0,1]
	v_pk_mul_f32 v[30:31], v[26:27], v[116:117] op_sel_hi:[0,1]
	v_pk_mul_f32 v[18:19], v[0:1], v[18:19] op_sel_hi:[0,1]
	v_pk_mul_f32 v[20:21], v[0:1], v[20:21] op_sel_hi:[0,1]
	v_pk_mul_f32 v[2:3], v[0:1], v[2:3] op_sel_hi:[0,1]
	v_pk_mul_f32 v[4:5], v[0:1], v[4:5] op_sel_hi:[0,1]
	v_lshlrev_b32_e32 v0, 3, v23
	v_cvt_pk_bf16_f32 v28, v28, v29
	v_cvt_pk_bf16_f32 v29, v30, v31
	v_pk_mul_f32 v[30:31], v[24:25], v[118:119] op_sel_hi:[0,1]
	v_pk_mul_f32 v[32:33], v[24:25], v[120:121] op_sel_hi:[0,1]
	v_cvt_pk_bf16_f32 v18, v18, v19
	v_cvt_pk_bf16_f32 v19, v20, v21
	v_cvt_pk_bf16_f32 v2, v2, v3
	v_cvt_pk_bf16_f32 v3, v4, v5
	v_and_b32_e32 v0, 0xf8, v0
	v_cvt_pk_bf16_f32 v30, v30, v31
	v_cvt_pk_bf16_f32 v31, v32, v33
	v_pk_mul_f32 v[32:33], v[22:23], v[122:123] op_sel_hi:[0,1]
	v_pk_mul_f32 v[34:35], v[22:23], v[124:125] op_sel_hi:[0,1]
	v_pk_mul_f32 v[14:15], v[26:27], v[14:15] op_sel_hi:[0,1]
	v_pk_mul_f32 v[16:17], v[26:27], v[16:17] op_sel_hi:[0,1]
	v_pk_mul_f32 v[10:11], v[24:25], v[10:11] op_sel_hi:[0,1]
	v_pk_mul_f32 v[12:13], v[24:25], v[12:13] op_sel_hi:[0,1]
	v_pk_mul_f32 v[6:7], v[22:23], v[6:7] op_sel_hi:[0,1]
	v_pk_mul_f32 v[8:9], v[22:23], v[8:9] op_sel_hi:[0,1]
	ds_write2_b64 v41, v[18:19], v[2:3] offset0:120 offset1:124
	v_or_b32_e32 v2, s54, v0
	s_movk_i32 s12, 0xa30
	v_cvt_pk_bf16_f32 v32, v32, v33
	v_cvt_pk_bf16_f32 v33, v34, v35
	v_cvt_pk_bf16_f32 v14, v14, v15
	v_cvt_pk_bf16_f32 v15, v16, v17
	v_cvt_pk_bf16_f32 v10, v10, v11
	v_cvt_pk_bf16_f32 v11, v12, v13
	v_cvt_pk_bf16_f32 v6, v6, v7
	v_cvt_pk_bf16_f32 v7, v8, v9
	v_cmp_gt_i32_e32 vcc, s12, v2
	ds_write2_b64 v25, v[28:29], v[14:15] offset0:24 offset1:28
	ds_write2_b64 v27, v[30:31], v[10:11] offset0:56 offset1:60
	ds_write2_b64 v40, v[32:33], v[6:7] offset0:88 offset1:92
	s_waitcnt lgkmcnt(0)
	s_barrier
	s_and_saveexec_b64 s[12:13], vcc
	s_cbranch_execz .LBB0_641
	v_ashrrev_i32_e32 v8, 5, v23
	v_lshlrev_b32_e32 v0, 1, v0
	s_movk_i32 s40, 0x210
	v_mad_u64_u32 v[6:7], s[40:41], v8, s40, v[0:1]
	ds_read_b128 v[2:5], v6
	v_add_u32_e32 v7, s57, v8
	v_mov_b64_e32 v[8:9], s[4:5]
	s_ashr_i32 s55, s54, 31
	v_mad_i64_i32 v[10:11], s[40:41], v7, s16, v[8:9]
	s_lshl_b64 s[40:41], s[54:55], 1
	s_nop 0
	v_lshl_add_u64 v[10:11], v[10:11], 0, s[40:41]
	v_lshl_add_u64 v[10:11], v[10:11], 0, v[0:1]
	s_waitcnt lgkmcnt(0)
	global_store_dwordx4 v[10:11], v[2:5], off
	ds_read_b128 v[2:5], v6 offset:4224
	v_add_u32_e32 v10, 8, v7
	v_mad_i64_i32 v[10:11], s[42:43], v10, s16, v[8:9]
	v_lshl_add_u64 v[10:11], v[10:11], 0, s[40:41]
	v_lshl_add_u64 v[10:11], v[10:11], 0, v[0:1]
	s_waitcnt lgkmcnt(0)
	global_store_dwordx4 v[10:11], v[2:5], off
	ds_read_b128 v[2:5], v6 offset:8448
	v_add_u32_e32 v10, 16, v7
	v_mad_i64_i32 v[10:11], s[42:43], v10, s16, v[8:9]
	v_lshl_add_u64 v[10:11], v[10:11], 0, s[40:41]
	v_lshl_add_u64 v[10:11], v[10:11], 0, v[0:1]
	s_waitcnt lgkmcnt(0)
	global_store_dwordx4 v[10:11], v[2:5], off
	ds_read_b128 v[2:5], v6 offset:12672
	v_add_u32_e32 v10, 24, v7
	v_mad_i64_i32 v[10:11], s[42:43], v10, s16, v[8:9]
	v_lshl_add_u64 v[10:11], v[10:11], 0, s[40:41]
	v_lshl_add_u64 v[10:11], v[10:11], 0, v[0:1]
	s_waitcnt lgkmcnt(0)
	global_store_dwordx4 v[10:11], v[2:5], off
	ds_read_b128 v[2:5], v6 offset:16896
	v_add_u32_e32 v10, 32, v7
	v_mad_i64_i32 v[10:11], s[42:43], v10, s16, v[8:9]
	v_lshl_add_u64 v[10:11], v[10:11], 0, s[40:41]
	v_lshl_add_u64 v[10:11], v[10:11], 0, v[0:1]
	s_waitcnt lgkmcnt(0)
	global_store_dwordx4 v[10:11], v[2:5], off
	ds_read_b128 v[2:5], v6 offset:21120
	v_add_u32_e32 v10, 40, v7
	v_mad_i64_i32 v[10:11], s[42:43], v10, s16, v[8:9]
	v_lshl_add_u64 v[10:11], v[10:11], 0, s[40:41]
	v_lshl_add_u64 v[10:11], v[10:11], 0, v[0:1]
	s_waitcnt lgkmcnt(0)
	global_store_dwordx4 v[10:11], v[2:5], off
	ds_read_b128 v[2:5], v6 offset:25344
	v_add_u32_e32 v10, 48, v7
	v_mad_i64_i32 v[10:11], s[42:43], v10, s16, v[8:9]
	v_lshl_add_u64 v[10:11], v[10:11], 0, s[40:41]
	v_lshl_add_u64 v[10:11], v[10:11], 0, v[0:1]
	s_waitcnt lgkmcnt(0)
	global_store_dwordx4 v[10:11], v[2:5], off
	ds_read_b128 v[2:5], v6 offset:29568
	v_add_u32_e32 v10, 56, v7
	v_mad_i64_i32 v[10:11], s[42:43], v10, s16, v[8:9]
	v_lshl_add_u64 v[10:11], v[10:11], 0, s[40:41]
	v_lshl_add_u64 v[10:11], v[10:11], 0, v[0:1]
	s_waitcnt lgkmcnt(0)
	global_store_dwordx4 v[10:11], v[2:5], off
	ds_read_b128 v[2:5], v6 offset:33792
	v_add_u32_e32 v10, 64, v7
	v_mad_i64_i32 v[10:11], s[42:43], v10, s16, v[8:9]
	v_lshl_add_u64 v[10:11], v[10:11], 0, s[40:41]
	v_lshl_add_u64 v[10:11], v[10:11], 0, v[0:1]
	s_waitcnt lgkmcnt(0)
	global_store_dwordx4 v[10:11], v[2:5], off
	ds_read_b128 v[2:5], v6 offset:38016
	v_add_u32_e32 v10, 0x48, v7
	v_mad_i64_i32 v[10:11], s[42:43], v10, s16, v[8:9]
	v_lshl_add_u64 v[10:11], v[10:11], 0, s[40:41]
	v_lshl_add_u64 v[10:11], v[10:11], 0, v[0:1]
	s_waitcnt lgkmcnt(0)
	global_store_dwordx4 v[10:11], v[2:5], off
	ds_read_b128 v[2:5], v6 offset:42240
	v_add_u32_e32 v10, 0x50, v7
	v_mad_i64_i32 v[10:11], s[42:43], v10, s16, v[8:9]
	v_lshl_add_u64 v[10:11], v[10:11], 0, s[40:41]
	v_lshl_add_u64 v[10:11], v[10:11], 0, v[0:1]
	s_waitcnt lgkmcnt(0)
	global_store_dwordx4 v[10:11], v[2:5], off
	ds_read_b128 v[2:5], v6 offset:46464
	v_add_u32_e32 v10, 0x58, v7
	v_mad_i64_i32 v[10:11], s[42:43], v10, s16, v[8:9]
	v_lshl_add_u64 v[10:11], v[10:11], 0, s[40:41]
	v_lshl_add_u64 v[10:11], v[10:11], 0, v[0:1]
	s_waitcnt lgkmcnt(0)
	global_store_dwordx4 v[10:11], v[2:5], off
	ds_read_b128 v[2:5], v6 offset:50688
	v_add_u32_e32 v10, 0x60, v7
	v_mad_i64_i32 v[10:11], s[42:43], v10, s16, v[8:9]
	v_lshl_add_u64 v[10:11], v[10:11], 0, s[40:41]
	v_lshl_add_u64 v[10:11], v[10:11], 0, v[0:1]
	s_waitcnt lgkmcnt(0)
	global_store_dwordx4 v[10:11], v[2:5], off
	ds_read_b128 v[2:5], v6 offset:54912
	v_add_u32_e32 v10, 0x68, v7
	v_mad_i64_i32 v[10:11], s[42:43], v10, s16, v[8:9]
	v_lshl_add_u64 v[10:11], v[10:11], 0, s[40:41]
	v_lshl_add_u64 v[10:11], v[10:11], 0, v[0:1]
	s_waitcnt lgkmcnt(0)
	global_store_dwordx4 v[10:11], v[2:5], off
	ds_read_b128 v[2:5], v6 offset:59136
	v_add_u32_e32 v10, 0x70, v7
	v_mad_i64_i32 v[10:11], s[42:43], v10, s16, v[8:9]
	v_lshl_add_u64 v[10:11], v[10:11], 0, s[40:41]
	v_lshl_add_u64 v[10:11], v[10:11], 0, v[0:1]
	s_waitcnt lgkmcnt(0)
	global_store_dwordx4 v[10:11], v[2:5], off
	ds_read_b128 v[2:5], v6 offset:63360
	v_add_u32_e32 v6, 0x78, v7
	v_mad_i64_i32 v[6:7], s[42:43], v6, s16, v[8:9]
	v_lshl_add_u64 v[6:7], v[6:7], 0, s[40:41]
	v_lshl_add_u64 v[6:7], v[6:7], 0, v[0:1]
	s_waitcnt lgkmcnt(0)
	global_store_dwordx4 v[6:7], v[2:5], off
	s_branch .LBB0_641
